# GEMM sub-phases: the separate s_waitcnt vmcnt(8) and s_waitcnt lgkmcnt(0) before each pre-MFMA barrier merged into one s_waitcnt (32 sites)
# baseline (speedup 1.0000x reference)
; #define PG8_STAGE(bufoff, gbase, voff) do { _Pragma("unroll") for (int _i = 0; _i < 2; ++_i) \
;         __builtin_amdgcn_global_load_lds((const unsigned*)((const char*)(gbase) + (voff)[_i]), (PG8_LAS unsigned*)(lds + (bufoff) + ldsw + _i * 8192), 16, 0, 0); } while (0)
; #define PG8_LDA(dst, b, h) do { _Pragma("unroll") for (int m = 0; m < 4; ++m) _Pragma("unroll") for (int k = 0; k < 2; ++k) dst[m][k] = *(const PG8_LAS bf16x8*)(lds + PG8_SA(b, h) + aoff + m * 2048 + k * 1024); } while (0)
; #define PG8_LDB(dst, b, h) do { _Pragma("unroll") for (int n = 0; n < 2; ++n) _Pragma("unroll") for (int k = 0; k < 2; ++k) dst[n][k] = *(const PG8_LAS bf16x8*)(lds + PG8_SB(b, h) + boff + n * 2048 + k * 1024); } while (0)
; #define PG8_MMA(ai, bj, At, Bt) do { __builtin_amdgcn_s_setprio(1); _Pragma("unroll") for (int m = 0; m < 4; ++m) _Pragma("unroll") for (int n = 0; n < 2; ++n) _Pragma("unroll") for (int k = 0; k < 2; ++k) \
;         acc[ai][bj][m][n] = __builtin_amdgcn_mfma_f32_16x16x32_bf16(Bt[n][k], At[m][k], acc[ai][bj][m][n], 0, 0, 0); __builtin_amdgcn_s_setprio(0); } while (0)
; #define PG8_WAIT_V(n) asm volatile("s_waitcnt vmcnt(" #n ")" ::: "memory")
; #define PG8_WAIT_L(n) asm volatile("s_waitcnt lgkmcnt(" #n ")" ::: "memory")
; template <class Epi, class Sched, bool ALIGN_EPI = false, bool SP2 = false>
; __device__ __forceinline__ void gemm_phase(PG8_LAS unsigned char* lds, const Gemm g, const Sched& S, const Epi& E, const int tid) {
;     ...
;             const bool last = (t == nt - 2);
;             const char* a1 = cA + (size_t)(t + 1) * kstep;
;             const char* a2 = last ? nA : cA + (size_t)(t + 2) * kstep; const char* b2 = last ? nB : cB + (size_t)(t + 2) * kstep;
;             const char* a3 = a2 + kstep; const char* b3 = b2 + kstep;
;             if (last && has_next) S.a_ready(nxt);
;             if constexpr (SP2) {
;             PG8_LDB(B0, 0, 0); PG8_LDB(B1, 0, 1); PG8_SCHED; PG8_LDA(At, 0, 0); PG8_STAGE(PG8_SA(1, 1), a1 + hstep, voffA);
;             PG8_WAIT_V(8); PG8_WAIT_L(0); PG8_BAR; PG8_MMA(0, 0, At, B0); PG8_MMA(0, 1, At, B1); PG8_BAR; PG8_SCHED;
;             PG8_LDA(At, 0, 1); PG8_STAGE(PG8_SB(0, 0), b2, voffB); PG8_STAGE(PG8_SB(0, 1), b2 + hstep, voffB); PG8_STAGE(PG8_SA(0, 0), a2, voffA);
;             PG8_WAIT_V(8); PG8_WAIT_L(0); PG8_BAR; PG8_MMA(1, 0, At, B0); PG8_MMA(1, 1, At, B1); PG8_BAR; PG8_SCHED;
.LBB0_137:
	s_add_u32 s16, s10, s14
	s_addc_u32 s17, s11, s15
	s_add_u32 s16, s16, 0x100
	s_addc_u32 s17, s17, 0
	s_add_u32 s52, s49, s14
	s_addc_u32 s53, s50, s15
	s_add_i32 s54, 0, 0x10000
	s_cmpk_eq_i32 s14, 0x1500
	s_cselect_b32 s19, s13, s17
	s_cselect_b32 s18, s12, s16
	v_add_u32_e32 v147, s54, v145
	s_cselect_b32 s17, s5, s53
	s_cselect_b32 s16, s4, s52
	s_add_i32 s55, 0, 0x14000
	ds_read_b128 v[148:151], v147
	ds_read_b128 v[152:155], v147 offset:1024
	ds_read_b128 v[160:163], v147 offset:2048
	ds_read_b128 v[164:167], v147 offset:3072
	v_add_u32_e32 v147, s55, v145
	ds_read_b128 v[168:171], v147
	ds_read_b128 v[172:175], v147 offset:1024
	ds_read_b128 v[176:179], v147 offset:2048
	ds_read_b128 v[180:183], v147 offset:3072
	v_lshl_add_u64 v[156:157], v[142:143], 0, s[14:15]
	s_add_i32 m0, s29, 0xc000
	ds_read_b128 v[184:187], v146
	ds_read_b128 v[188:191], v146 offset:1024
	ds_read_b128 v[192:195], v146 offset:2048
	ds_read_b128 v[196:199], v146 offset:3072
	ds_read_b128 v[200:203], v146 offset:4096
	ds_read_b128 v[206:209], v146 offset:5120
	ds_read_b128 v[214:217], v146 offset:6144
	ds_read_b128 v[218:221], v146 offset:7168
	global_load_lds_dwordx4 v[156:157], off
	v_lshl_add_u64 v[156:157], v[140:141], 0, s[14:15]
	s_add_i32 m0, s29, 0xe000
	s_nop 0
	global_load_lds_dwordx4 v[156:157], off
	s_waitcnt vmcnt(8) lgkmcnt(0)
	s_setprio 1
	s_barrier
	v_mfma_f32_16x16x32_bf16 v[32:35], v[148:151], v[184:187], v[32:35]
	v_mfma_f32_16x16x32_bf16 v[36:39], v[160:163], v[184:187], v[36:39]
	v_mfma_f32_16x16x32_bf16 v[48:51], v[148:151], v[192:195], v[48:51]
	v_mfma_f32_16x16x32_bf16 v[52:55], v[160:163], v[192:195], v[52:55]
	v_mfma_f32_16x16x32_bf16 v[56:59], v[148:151], v[200:203], v[56:59]
	v_mfma_f32_16x16x32_bf16 v[60:63], v[160:163], v[200:203], v[60:63]
	v_mfma_f32_16x16x32_bf16 v[74:77], v[148:151], v[214:217], v[74:77]
	v_mfma_f32_16x16x32_bf16 v[78:81], v[160:163], v[214:217], v[78:81]
	v_mfma_f32_16x16x32_bf16 v[32:35], v[152:155], v[188:191], v[32:35]
	v_mfma_f32_16x16x32_bf16 v[36:39], v[164:167], v[188:191], v[36:39]
	v_mfma_f32_16x16x32_bf16 v[48:51], v[152:155], v[196:199], v[48:51]
	v_mfma_f32_16x16x32_bf16 v[52:55], v[164:167], v[196:199], v[52:55]
	v_mfma_f32_16x16x32_bf16 v[56:59], v[152:155], v[206:209], v[56:59]
	v_mfma_f32_16x16x32_bf16 v[60:63], v[164:167], v[206:209], v[60:63]
	v_mfma_f32_16x16x32_bf16 v[74:77], v[152:155], v[218:221], v[74:77]
	v_mfma_f32_16x16x32_bf16 v[78:81], v[164:167], v[218:221], v[78:81]
	v_mfma_f32_16x16x32_bf16 v[106:109], v[168:171], v[184:187], v[106:109]
	v_mfma_f32_16x16x32_bf16 v[110:113], v[176:179], v[184:187], v[110:113]
	v_mfma_f32_16x16x32_bf16 v[102:105], v[168:171], v[192:195], v[102:105]
	v_mfma_f32_16x16x32_bf16 v[98:101], v[176:179], v[192:195], v[98:101]
	v_mfma_f32_16x16x32_bf16 v[70:73], v[168:171], v[200:203], v[70:73]
	v_mfma_f32_16x16x32_bf16 v[66:69], v[176:179], v[200:203], v[66:69]
	v_mfma_f32_16x16x32_bf16 v[44:47], v[168:171], v[214:217], v[44:47]
	v_mfma_f32_16x16x32_bf16 v[40:43], v[176:179], v[214:217], v[40:43]
	v_mfma_f32_16x16x32_bf16 v[106:109], v[172:175], v[188:191], v[106:109]
	v_mfma_f32_16x16x32_bf16 v[110:113], v[180:183], v[188:191], v[110:113]
	v_mfma_f32_16x16x32_bf16 v[102:105], v[172:175], v[196:199], v[102:105]
	v_mfma_f32_16x16x32_bf16 v[98:101], v[180:183], v[196:199], v[98:101]
	v_mfma_f32_16x16x32_bf16 v[70:73], v[172:175], v[206:209], v[70:73]
	v_mfma_f32_16x16x32_bf16 v[66:69], v[180:183], v[206:209], v[66:69]
	v_mfma_f32_16x16x32_bf16 v[44:47], v[172:175], v[218:221], v[44:47]
	v_mfma_f32_16x16x32_bf16 v[40:43], v[180:183], v[218:221], v[40:43]
	s_barrier
	s_setprio 0
	s_add_i32 s52, s54, s28
	v_lshl_add_u64 v[156:157], s[16:17], 0, v[64:65]
	s_mov_b32 m0, s52
	ds_read_b128 v[184:187], v146 offset:16384
	ds_read_b128 v[188:191], v146 offset:17408
	ds_read_b128 v[192:195], v146 offset:18432
	ds_read_b128 v[196:199], v146 offset:19456
	ds_read_b128 v[200:203], v146 offset:20480
	ds_read_b128 v[206:209], v146 offset:21504
	ds_read_b128 v[214:217], v146 offset:22528
	ds_read_b128 v[218:221], v146 offset:23552
	global_load_lds_dwordx4 v[156:157], off
	s_add_i32 m0, s52, 0x2000
	s_add_u32 s52, s16, 0xb0000
	v_lshl_add_u64 v[210:211], s[16:17], 0, v[130:131]
	s_addc_u32 s53, s17, 0
	s_add_i32 s54, s55, s28
	global_load_lds_dwordx4 v[210:211], off
	v_lshl_add_u64 v[222:223], s[52:53], 0, v[64:65]
	s_mov_b32 m0, s54
	v_lshl_add_u64 v[224:225], s[18:19], 0, v[132:133]
	global_load_lds_dwordx4 v[222:223], off
	v_lshl_add_u64 v[222:223], s[52:53], 0, v[130:131]
	s_add_i32 m0, s54, 0x2000
	s_nop 0
	global_load_lds_dwordx4 v[222:223], off
	v_lshl_add_u64 v[222:223], s[18:19], 0, v[134:135]
	s_mov_b32 m0, s29
	s_nop 0
	global_load_lds_dwordx4 v[222:223], off
	s_mov_b32 m0, s30
	s_nop 0
	global_load_lds_dwordx4 v[224:225], off
	s_waitcnt vmcnt(8) lgkmcnt(0)
	s_setprio 1
	s_barrier
; #define PG8_STAGE(bufoff, gbase, voff) do { _Pragma("unroll") for (int _i = 0; _i < 2; ++_i) \
;         __builtin_amdgcn_global_load_lds((const unsigned*)((const char*)(gbase) + (voff)[_i]), (PG8_LAS unsigned*)(lds + (bufoff) + ldsw + _i * 8192), 16, 0, 0); } while (0)
; #define PG8_LDA(dst, b, h) do { _Pragma("unroll") for (int m = 0; m < 4; ++m) _Pragma("unroll") for (int k = 0; k < 2; ++k) dst[m][k] = *(const PG8_LAS bf16x8*)(lds + PG8_SA(b, h) + aoff + m * 2048 + k * 1024); } while (0)
; #define PG8_LDB(dst, b, h) do { _Pragma("unroll") for (int n = 0; n < 2; ++n) _Pragma("unroll") for (int k = 0; k < 2; ++k) dst[n][k] = *(const PG8_LAS bf16x8*)(lds + PG8_SB(b, h) + boff + n * 2048 + k * 1024); } while (0)
; #define PG8_MMA(ai, bj, At, Bt) do { __builtin_amdgcn_s_setprio(1); _Pragma("unroll") for (int m = 0; m < 4; ++m) _Pragma("unroll") for (int n = 0; n < 2; ++n) _Pragma("unroll") for (int k = 0; k < 2; ++k) \
;         acc[ai][bj][m][n] = __builtin_amdgcn_mfma_f32_16x16x32_bf16(Bt[n][k], At[m][k], acc[ai][bj][m][n], 0, 0, 0); __builtin_amdgcn_s_setprio(0); } while (0)
; #define PG8_WAIT_V(n) asm volatile("s_waitcnt vmcnt(" #n ")" ::: "memory")
; #define PG8_WAIT_L(n) asm volatile("s_waitcnt lgkmcnt(" #n ")" ::: "memory")
; #define PG8_BAR __builtin_amdgcn_s_barrier()
; #define PG8_SCHED __builtin_amdgcn_sched_barrier(0)
; template <class Epi, class Sched, bool ALIGN_EPI = false, bool SP2 = false>
; __device__ __forceinline__ void gemm_phase(PG8_LAS unsigned char* lds, const Gemm g, const Sched& S, const Epi& E, const int tid) {
;     ...
;             PG8_WAIT_V(8); PG8_WAIT_L(0); PG8_BAR; PG8_MMA(1, 0, At, B0); PG8_MMA(1, 1, At, B1); PG8_BAR; PG8_SCHED;
;             PG8_LDB(B0, 1, 0); PG8_LDB(B1, 1, 1); PG8_SCHED; PG8_LDA(At, 1, 0); PG8_STAGE(PG8_SA(0, 1), a2 + hstep, voffA);
;             PG8_WAIT_V(8); PG8_WAIT_L(0); PG8_BAR; PG8_MMA(0, 0, At, B0); PG8_MMA(0, 1, At, B1); PG8_BAR; PG8_SCHED;
	v_mfma_f32_16x16x32_bf16 v[82:85], v[148:151], v[184:187], v[82:85]
	v_mfma_f32_16x16x32_bf16 v[86:89], v[160:163], v[184:187], v[86:89]
	v_mfma_f32_16x16x32_bf16 v[90:93], v[148:151], v[192:195], v[90:93]
	v_mfma_f32_16x16x32_bf16 v[94:97], v[160:163], v[192:195], v[94:97]
	v_mfma_f32_16x16x32_bf16 v[114:117], v[148:151], v[200:203], v[114:117]
	v_mfma_f32_16x16x32_bf16 v[118:121], v[160:163], v[200:203], v[118:121]
	v_mfma_f32_16x16x32_bf16 v[122:125], v[148:151], v[214:217], v[122:125]
	v_mfma_f32_16x16x32_bf16 v[126:129], v[160:163], v[214:217], v[126:129]
	v_mfma_f32_16x16x32_bf16 v[82:85], v[152:155], v[188:191], v[82:85]
	v_mfma_f32_16x16x32_bf16 v[86:89], v[164:167], v[188:191], v[86:89]
	v_mfma_f32_16x16x32_bf16 v[90:93], v[152:155], v[196:199], v[90:93]
	v_mfma_f32_16x16x32_bf16 v[94:97], v[164:167], v[196:199], v[94:97]
	v_mfma_f32_16x16x32_bf16 v[114:117], v[152:155], v[206:209], v[114:117]
	v_mfma_f32_16x16x32_bf16 v[118:121], v[164:167], v[206:209], v[118:121]
	v_mfma_f32_16x16x32_bf16 v[122:125], v[152:155], v[218:221], v[122:125]
	v_mfma_f32_16x16x32_bf16 v[126:129], v[164:167], v[218:221], v[126:129]
	v_mfma_f32_16x16x32_bf16 v[28:31], v[168:171], v[184:187], v[28:31]
	v_mfma_f32_16x16x32_bf16 v[24:27], v[176:179], v[184:187], v[24:27]
	v_mfma_f32_16x16x32_bf16 v[20:23], v[168:171], v[192:195], v[20:23]
	v_mfma_f32_16x16x32_bf16 v[16:19], v[176:179], v[192:195], v[16:19]
	v_mfma_f32_16x16x32_bf16 v[12:15], v[168:171], v[200:203], v[12:15]
	v_mfma_f32_16x16x32_bf16 v[8:11], v[176:179], v[200:203], v[8:11]
	v_mfma_f32_16x16x32_bf16 v[4:7], v[168:171], v[214:217], v[4:7]
	v_mfma_f32_16x16x32_bf16 v[0:3], v[176:179], v[214:217], v[0:3]
	v_mfma_f32_16x16x32_bf16 v[28:31], v[172:175], v[188:191], v[28:31]
	v_mfma_f32_16x16x32_bf16 v[24:27], v[180:183], v[188:191], v[24:27]
	v_mfma_f32_16x16x32_bf16 v[20:23], v[172:175], v[196:199], v[20:23]
	v_mfma_f32_16x16x32_bf16 v[16:19], v[180:183], v[196:199], v[16:19]
	v_mfma_f32_16x16x32_bf16 v[12:15], v[172:175], v[206:209], v[12:15]
	v_mfma_f32_16x16x32_bf16 v[8:11], v[180:183], v[206:209], v[8:11]
	v_mfma_f32_16x16x32_bf16 v[4:7], v[172:175], v[218:221], v[4:7]
	v_mfma_f32_16x16x32_bf16 v[0:3], v[180:183], v[218:221], v[0:3]
	s_barrier
	s_setprio 0
	s_add_i32 s52, 0, 0x18000
	v_add_u32_e32 v147, s52, v145
	s_add_i32 s53, 0, 0x1c000
	ds_read_b128 v[148:151], v147
	ds_read_b128 v[152:155], v147 offset:1024
	ds_read_b128 v[160:163], v147 offset:2048
	ds_read_b128 v[164:167], v147 offset:3072
	v_add_u32_e32 v147, s53, v145
	ds_read_b128 v[168:171], v147
	ds_read_b128 v[172:175], v147 offset:1024
	ds_read_b128 v[176:179], v147 offset:2048
	ds_read_b128 v[180:183], v147 offset:3072
	s_add_u32 s18, s18, 0xb0000
	s_addc_u32 s19, s19, 0
	s_mov_b32 m0, s31
	v_lshl_add_u64 v[226:227], s[18:19], 0, v[134:135]
	ds_read_b128 v[184:187], v146 offset:32768
	ds_read_b128 v[188:191], v146 offset:33792
	ds_read_b128 v[192:195], v146 offset:34816
	ds_read_b128 v[196:199], v146 offset:35840
	ds_read_b128 v[200:203], v146 offset:36864
	ds_read_b128 v[206:209], v146 offset:37888
	ds_read_b128 v[214:217], v146 offset:38912
	ds_read_b128 v[218:221], v146 offset:39936
	global_load_lds_dwordx4 v[226:227], off
	v_lshl_add_u64 v[226:227], s[18:19], 0, v[132:133]
	s_mov_b32 m0, s34
	s_nop 0
	global_load_lds_dwordx4 v[226:227], off
	s_waitcnt vmcnt(8) lgkmcnt(0)
	s_setprio 1
	s_barrier
	v_mfma_f32_16x16x32_bf16 v[32:35], v[148:151], v[184:187], v[32:35]
	v_mfma_f32_16x16x32_bf16 v[36:39], v[160:163], v[184:187], v[36:39]
	v_mfma_f32_16x16x32_bf16 v[48:51], v[148:151], v[192:195], v[48:51]
	v_mfma_f32_16x16x32_bf16 v[52:55], v[160:163], v[192:195], v[52:55]
	v_mfma_f32_16x16x32_bf16 v[56:59], v[148:151], v[200:203], v[56:59]
	v_mfma_f32_16x16x32_bf16 v[60:63], v[160:163], v[200:203], v[60:63]
	v_mfma_f32_16x16x32_bf16 v[74:77], v[148:151], v[214:217], v[74:77]
	v_mfma_f32_16x16x32_bf16 v[78:81], v[160:163], v[214:217], v[78:81]
	v_mfma_f32_16x16x32_bf16 v[32:35], v[152:155], v[188:191], v[32:35]
	v_mfma_f32_16x16x32_bf16 v[36:39], v[164:167], v[188:191], v[36:39]
	v_mfma_f32_16x16x32_bf16 v[48:51], v[152:155], v[196:199], v[48:51]
	v_mfma_f32_16x16x32_bf16 v[52:55], v[164:167], v[196:199], v[52:55]
	v_mfma_f32_16x16x32_bf16 v[56:59], v[152:155], v[206:209], v[56:59]
	v_mfma_f32_16x16x32_bf16 v[60:63], v[164:167], v[206:209], v[60:63]
	v_mfma_f32_16x16x32_bf16 v[74:77], v[152:155], v[218:221], v[74:77]
	v_mfma_f32_16x16x32_bf16 v[78:81], v[164:167], v[218:221], v[78:81]
	v_mfma_f32_16x16x32_bf16 v[106:109], v[168:171], v[184:187], v[106:109]
	v_mfma_f32_16x16x32_bf16 v[110:113], v[176:179], v[184:187], v[110:113]
	v_mfma_f32_16x16x32_bf16 v[102:105], v[168:171], v[192:195], v[102:105]
	v_mfma_f32_16x16x32_bf16 v[98:101], v[176:179], v[192:195], v[98:101]
	v_mfma_f32_16x16x32_bf16 v[70:73], v[168:171], v[200:203], v[70:73]
	v_mfma_f32_16x16x32_bf16 v[66:69], v[176:179], v[200:203], v[66:69]
	v_mfma_f32_16x16x32_bf16 v[44:47], v[168:171], v[214:217], v[44:47]
	v_mfma_f32_16x16x32_bf16 v[40:43], v[176:179], v[214:217], v[40:43]
	v_mfma_f32_16x16x32_bf16 v[106:109], v[172:175], v[188:191], v[106:109]
	v_mfma_f32_16x16x32_bf16 v[110:113], v[180:183], v[188:191], v[110:113]
	v_mfma_f32_16x16x32_bf16 v[102:105], v[172:175], v[196:199], v[102:105]
	v_mfma_f32_16x16x32_bf16 v[98:101], v[180:183], v[196:199], v[98:101]
	v_mfma_f32_16x16x32_bf16 v[70:73], v[172:175], v[206:209], v[70:73]
	v_mfma_f32_16x16x32_bf16 v[66:69], v[180:183], v[206:209], v[66:69]
	v_mfma_f32_16x16x32_bf16 v[44:47], v[172:175], v[218:221], v[44:47]
	v_mfma_f32_16x16x32_bf16 v[40:43], v[180:183], v[218:221], v[40:43]
	s_barrier
; #define PG8_STAGE(bufoff, gbase, voff) do { _Pragma("unroll") for (int _i = 0; _i < 2; ++_i) \
;         __builtin_amdgcn_global_load_lds((const unsigned*)((const char*)(gbase) + (voff)[_i]), (PG8_LAS unsigned*)(lds + (bufoff) + ldsw + _i * 8192), 16, 0, 0); } while (0)
; #define PG8_LDA(dst, b, h) do { _Pragma("unroll") for (int m = 0; m < 4; ++m) _Pragma("unroll") for (int k = 0; k < 2; ++k) dst[m][k] = *(const PG8_LAS bf16x8*)(lds + PG8_SA(b, h) + aoff + m * 2048 + k * 1024); } while (0)
; #define PG8_MMA(ai, bj, At, Bt) do { __builtin_amdgcn_s_setprio(1); _Pragma("unroll") for (int m = 0; m < 4; ++m) _Pragma("unroll") for (int n = 0; n < 2; ++n) _Pragma("unroll") for (int k = 0; k < 2; ++k) \
;         acc[ai][bj][m][n] = __builtin_amdgcn_mfma_f32_16x16x32_bf16(Bt[n][k], At[m][k], acc[ai][bj][m][n], 0, 0, 0); __builtin_amdgcn_s_setprio(0); } while (0)
; #define PG8_WAIT_V(n) asm volatile("s_waitcnt vmcnt(" #n ")" ::: "memory")
; #define PG8_WAIT_L(n) asm volatile("s_waitcnt lgkmcnt(" #n ")" ::: "memory")
; #define PG8_BAR __builtin_amdgcn_s_barrier()
; #define PG8_SCHED __builtin_amdgcn_sched_barrier(0)
; template <class Epi, class Sched, bool ALIGN_EPI = false, bool SP2 = false>
; __device__ __forceinline__ void gemm_phase(PG8_LAS unsigned char* lds, const Gemm g, const Sched& S, const Epi& E, const int tid) {
;     ...
;             PG8_LDA(At, 1, 1); PG8_STAGE(PG8_SB(1, 0), b3, voffB); PG8_STAGE(PG8_SB(1, 1), b3 + hstep, voffB); PG8_STAGE(PG8_SA(1, 0), a3, voffA);
;             PG8_WAIT_V(8); PG8_WAIT_L(0); PG8_BAR; PG8_MMA(1, 0, At, B0); PG8_MMA(1, 1, At, B1); PG8_BAR; PG8_SCHED;
;     ...
;         if (!has_next) break;
; #pragma unroll
;         for (int a = 0; a < 2; ++a)
; #pragma unroll
;             for (int b = 0; b < 2; ++b)
; #pragma unroll
;                 for (int m = 0; m < 4; ++m)
; #pragma unroll
;                     for (int n = 0; n < 2; ++n) acc[a][b][m][n] = (f32x4){0.f, 0.f, 0.f, 0.f};
;         cur = nxt; cA = nA; cB = nB; ++ui;
	s_setprio 0
	s_add_i32 s18, s52, s28
	v_lshl_add_u64 v[156:157], v[156:157], 0, s[94:95]
	s_mov_b32 m0, s18
	ds_read_b128 v[184:187], v146 offset:49152
	ds_read_b128 v[188:191], v146 offset:50176
	ds_read_b128 v[192:195], v146 offset:51200
	ds_read_b128 v[196:199], v146 offset:52224
	ds_read_b128 v[200:203], v146 offset:53248
	ds_read_b128 v[206:209], v146 offset:54272
	ds_read_b128 v[214:217], v146 offset:55296
	ds_read_b128 v[218:221], v146 offset:56320
	global_load_lds_dwordx4 v[156:157], off
	s_add_i32 m0, s18, 0x2000
	s_add_u32 s16, s16, 0xb0080
	v_lshl_add_u64 v[156:157], v[210:211], 0, s[94:95]
	s_addc_u32 s17, s17, 0
	s_add_i32 s18, s53, s28
	global_load_lds_dwordx4 v[156:157], off
	v_lshl_add_u64 v[156:157], s[16:17], 0, v[64:65]
	s_mov_b32 m0, s18
	s_nop 0
	global_load_lds_dwordx4 v[156:157], off
	v_lshl_add_u64 v[156:157], s[16:17], 0, v[130:131]
	s_add_i32 m0, s18, 0x2000
	s_nop 0
	global_load_lds_dwordx4 v[156:157], off
	v_lshl_add_u64 v[156:157], v[222:223], 0, s[94:95]
	s_mov_b32 m0, s42
	s_nop 0
	global_load_lds_dwordx4 v[156:157], off
	v_lshl_add_u64 v[156:157], v[224:225], 0, s[94:95]
	s_mov_b32 m0, s44
	s_nop 0
	global_load_lds_dwordx4 v[156:157], off
	s_waitcnt vmcnt(8) lgkmcnt(0)
	s_setprio 1
	s_barrier
	v_mfma_f32_16x16x32_bf16 v[82:85], v[148:151], v[184:187], v[82:85]
	v_mfma_f32_16x16x32_bf16 v[86:89], v[160:163], v[184:187], v[86:89]
	v_mfma_f32_16x16x32_bf16 v[90:93], v[148:151], v[192:195], v[90:93]
	v_mfma_f32_16x16x32_bf16 v[94:97], v[160:163], v[192:195], v[94:97]
	v_mfma_f32_16x16x32_bf16 v[114:117], v[148:151], v[200:203], v[114:117]
	v_mfma_f32_16x16x32_bf16 v[118:121], v[160:163], v[200:203], v[118:121]
	v_mfma_f32_16x16x32_bf16 v[122:125], v[148:151], v[214:217], v[122:125]
	v_mfma_f32_16x16x32_bf16 v[126:129], v[160:163], v[214:217], v[126:129]
	v_mfma_f32_16x16x32_bf16 v[82:85], v[152:155], v[188:191], v[82:85]
	v_mfma_f32_16x16x32_bf16 v[86:89], v[164:167], v[188:191], v[86:89]
	v_mfma_f32_16x16x32_bf16 v[90:93], v[152:155], v[196:199], v[90:93]
	v_mfma_f32_16x16x32_bf16 v[94:97], v[164:167], v[196:199], v[94:97]
	v_mfma_f32_16x16x32_bf16 v[114:117], v[152:155], v[206:209], v[114:117]
	v_mfma_f32_16x16x32_bf16 v[118:121], v[164:167], v[206:209], v[118:121]
	v_mfma_f32_16x16x32_bf16 v[122:125], v[152:155], v[218:221], v[122:125]
	v_mfma_f32_16x16x32_bf16 v[126:129], v[164:167], v[218:221], v[126:129]
	v_mfma_f32_16x16x32_bf16 v[28:31], v[168:171], v[184:187], v[28:31]
	v_mfma_f32_16x16x32_bf16 v[24:27], v[176:179], v[184:187], v[24:27]
	v_mfma_f32_16x16x32_bf16 v[20:23], v[168:171], v[192:195], v[20:23]
	v_mfma_f32_16x16x32_bf16 v[16:19], v[176:179], v[192:195], v[16:19]
	v_mfma_f32_16x16x32_bf16 v[12:15], v[168:171], v[200:203], v[12:15]
	v_mfma_f32_16x16x32_bf16 v[8:11], v[176:179], v[200:203], v[8:11]
	v_mfma_f32_16x16x32_bf16 v[4:7], v[168:171], v[214:217], v[4:7]
	v_mfma_f32_16x16x32_bf16 v[0:3], v[176:179], v[214:217], v[0:3]
	v_mfma_f32_16x16x32_bf16 v[28:31], v[172:175], v[188:191], v[28:31]
	v_mfma_f32_16x16x32_bf16 v[24:27], v[180:183], v[188:191], v[24:27]
	v_mfma_f32_16x16x32_bf16 v[20:23], v[172:175], v[196:199], v[20:23]
	v_mfma_f32_16x16x32_bf16 v[16:19], v[180:183], v[196:199], v[16:19]
	v_mfma_f32_16x16x32_bf16 v[12:15], v[172:175], v[206:209], v[12:15]
	v_mfma_f32_16x16x32_bf16 v[8:11], v[180:183], v[206:209], v[8:11]
	v_mfma_f32_16x16x32_bf16 v[4:7], v[172:175], v[218:221], v[4:7]
	v_mfma_f32_16x16x32_bf16 v[0:3], v[180:183], v[218:221], v[0:3]
	s_barrier
	s_setprio 0
	s_add_i32 s51, s51, 2
	s_add_u32 s14, s14, 0x100
	s_addc_u32 s15, s15, 0
	s_cmp_gt_u32 s51, 41
	s_cbranch_scc0 .LBB0_137
	s_add_u32 s14, s49, 0xffffff00
	s_addc_u32 s15, s50, -1
	s_and_b64 vcc, exec, s[2:3]
	s_cbranch_vccnz .LBB0_140
	v_mov_b32_e32 v0, 0
	s_mov_b32 s8, s46
	s_mov_b32 s22, s47
	s_mov_b64 s[10:11], s[12:13]
	s_mov_b32 s45, s48
	v_mov_b32_e32 v1, v0
	v_mov_b32_e32 v2, v0
	v_mov_b32_e32 v3, v0
	v_mov_b32_e32 v4, v0
	v_mov_b32_e32 v5, v0
	v_mov_b32_e32 v6, v0
	v_mov_b32_e32 v7, v0
	v_mov_b32_e32 v8, v0
	v_mov_b32_e32 v9, v0
	v_mov_b32_e32 v10, v0
	v_mov_b32_e32 v11, v0
	v_mov_b32_e32 v12, v0
	v_mov_b32_e32 v13, v0
	v_mov_b32_e32 v14, v0
	v_mov_b32_e32 v15, v0
	v_mov_b32_e32 v16, v0
	v_mov_b32_e32 v17, v0
	v_mov_b32_e32 v18, v0
	v_mov_b32_e32 v19, v0
	v_mov_b32_e32 v20, v0
	v_mov_b32_e32 v21, v0
	v_mov_b32_e32 v22, v0
	v_mov_b32_e32 v23, v0
	v_mov_b32_e32 v24, v0
	v_mov_b32_e32 v25, v0
	v_mov_b32_e32 v26, v0
	v_mov_b32_e32 v27, v0
	v_mov_b32_e32 v28, v0
	v_mov_b32_e32 v29, v0
	v_mov_b32_e32 v30, v0
	v_mov_b32_e32 v31, v0
	v_mov_b32_e32 v126, v0
	v_mov_b32_e32 v127, v0
	v_mov_b32_e32 v128, v0
	v_mov_b32_e32 v129, v0
	v_mov_b32_e32 v122, v0
	v_mov_b32_e32 v123, v0
	v_mov_b32_e32 v124, v0
	v_mov_b32_e32 v125, v0
	v_mov_b32_e32 v118, v0
	v_mov_b32_e32 v119, v0
	v_mov_b32_e32 v120, v0
	v_mov_b32_e32 v121, v0
	v_mov_b32_e32 v114, v0
	v_mov_b32_e32 v115, v0
	v_mov_b32_e32 v116, v0
	v_mov_b32_e32 v117, v0
	v_mov_b32_e32 v94, v0
	v_mov_b32_e32 v95, v0
	v_mov_b32_e32 v96, v0
	v_mov_b32_e32 v97, v0
	v_mov_b32_e32 v90, v0
	v_mov_b32_e32 v91, v0
	v_mov_b32_e32 v92, v0
	v_mov_b32_e32 v93, v0
	v_mov_b32_e32 v86, v0
	v_mov_b32_e32 v87, v0
	v_mov_b32_e32 v88, v0
	v_mov_b32_e32 v89, v0
	v_mov_b32_e32 v82, v0
	v_mov_b32_e32 v83, v0
	v_mov_b32_e32 v84, v0
	v_mov_b32_e32 v85, v0
	v_mov_b32_e32 v40, v0
	v_mov_b32_e32 v41, v0
	v_mov_b32_e32 v42, v0
	v_mov_b32_e32 v43, v0
	v_mov_b32_e32 v44, v0
	v_mov_b32_e32 v45, v0
	v_mov_b32_e32 v46, v0
	v_mov_b32_e32 v47, v0
	v_mov_b32_e32 v66, v0
	v_mov_b32_e32 v67, v0
	v_mov_b32_e32 v68, v0
	v_mov_b32_e32 v69, v0
	v_mov_b32_e32 v70, v0
	v_mov_b32_e32 v71, v0
	v_mov_b32_e32 v72, v0
	v_mov_b32_e32 v73, v0
	v_mov_b32_e32 v98, v0
	v_mov_b32_e32 v99, v0
	v_mov_b32_e32 v100, v0
	v_mov_b32_e32 v101, v0
	v_mov_b32_e32 v102, v0
	v_mov_b32_e32 v103, v0
	v_mov_b32_e32 v104, v0
	v_mov_b32_e32 v105, v0
	v_mov_b32_e32 v110, v0
	v_mov_b32_e32 v111, v0
	v_mov_b32_e32 v112, v0
	v_mov_b32_e32 v113, v0
	v_mov_b32_e32 v106, v0
	v_mov_b32_e32 v107, v0
	v_mov_b32_e32 v108, v0
	v_mov_b32_e32 v109, v0
	v_mov_b32_e32 v78, v0
	v_mov_b32_e32 v79, v0
	v_mov_b32_e32 v80, v0
	v_mov_b32_e32 v81, v0
	v_mov_b32_e32 v74, v0
	v_mov_b32_e32 v75, v0
	v_mov_b32_e32 v76, v0
	v_mov_b32_e32 v77, v0
	v_mov_b32_e32 v60, v0
	v_mov_b32_e32 v61, v0
	v_mov_b32_e32 v62, v0
	v_mov_b32_e32 v63, v0
	v_mov_b32_e32 v56, v0
	v_mov_b32_e32 v57, v0
	v_mov_b32_e32 v58, v0
	v_mov_b32_e32 v59, v0
	v_mov_b32_e32 v52, v0
	v_mov_b32_e32 v53, v0
	v_mov_b32_e32 v54, v0
	v_mov_b32_e32 v55, v0
	v_mov_b32_e32 v48, v0
	v_mov_b32_e32 v49, v0
	v_mov_b32_e32 v50, v0
	v_mov_b32_e32 v51, v0
	v_mov_b32_e32 v36, v0
	v_mov_b32_e32 v37, v0
	v_mov_b32_e32 v38, v0
	v_mov_b32_e32 v39, v0
	v_mov_b32_e32 v32, v0
	v_mov_b32_e32 v33, v0
	v_mov_b32_e32 v34, v0
	v_mov_b32_e32 v35, v0
	s_andn2_b64 vcc, exec, s[0:1]
	s_cbranch_vccnz .LBB0_141
	s_branch .LBB0_142

; #define PG8_STAGE(bufoff, gbase, voff) do { _Pragma("unroll") for (int _i = 0; _i < 2; ++_i) \
;         __builtin_amdgcn_global_load_lds((const unsigned*)((const char*)(gbase) + (voff)[_i]), (PG8_LAS unsigned*)(lds + (bufoff) + ldsw + _i * 8192), 16, 0, 0); } while (0)
; #define PG8_LDA(dst, b, h) do { _Pragma("unroll") for (int m = 0; m < 4; ++m) _Pragma("unroll") for (int k = 0; k < 2; ++k) dst[m][k] = *(const PG8_LAS bf16x8*)(lds + PG8_SA(b, h) + aoff + m * 2048 + k * 1024); } while (0)
; #define PG8_LDB(dst, b, h) do { _Pragma("unroll") for (int n = 0; n < 2; ++n) _Pragma("unroll") for (int k = 0; k < 2; ++k) dst[n][k] = *(const PG8_LAS bf16x8*)(lds + PG8_SB(b, h) + boff + n * 2048 + k * 1024); } while (0)
; #define PG8_MMA(ai, bj, At, Bt) do { __builtin_amdgcn_s_setprio(1); _Pragma("unroll") for (int m = 0; m < 4; ++m) _Pragma("unroll") for (int n = 0; n < 2; ++n) _Pragma("unroll") for (int k = 0; k < 2; ++k) \
;         acc[ai][bj][m][n] = __builtin_amdgcn_mfma_f32_16x16x32_bf16(Bt[n][k], At[m][k], acc[ai][bj][m][n], 0, 0, 0); __builtin_amdgcn_s_setprio(0); } while (0)
; #define PG8_WAIT_V(n) asm volatile("s_waitcnt vmcnt(" #n ")" ::: "memory")
; #define PG8_WAIT_L(n) asm volatile("s_waitcnt lgkmcnt(" #n ")" ::: "memory")
; template <class Epi, class Sched, bool ALIGN_EPI = false, bool SP2 = false>
; __device__ __forceinline__ void gemm_phase(PG8_LAS unsigned char* lds, const Gemm g, const Sched& S, const Epi& E, const int tid) {
;     ...
;             const bool last = (t == nt - 2);
;             const char* a1 = cA + (size_t)(t + 1) * kstep;
;             const char* a2 = last ? nA : cA + (size_t)(t + 2) * kstep; const char* b2 = last ? nB : cB + (size_t)(t + 2) * kstep;
;             const char* a3 = a2 + kstep; const char* b3 = b2 + kstep;
;             if (last && has_next) S.a_ready(nxt);
;             if constexpr (SP2) {
;             PG8_LDB(B0, 0, 0); PG8_LDB(B1, 0, 1); PG8_SCHED; PG8_LDA(At, 0, 0); PG8_STAGE(PG8_SA(1, 1), a1 + hstep, voffA);
;             PG8_WAIT_V(8); PG8_WAIT_L(0); PG8_BAR; PG8_MMA(0, 0, At, B0); PG8_MMA(0, 1, At, B1); PG8_BAR; PG8_SCHED;
;             PG8_LDA(At, 0, 1); PG8_STAGE(PG8_SB(0, 0), b2, voffB); PG8_STAGE(PG8_SB(0, 1), b2 + hstep, voffB); PG8_STAGE(PG8_SA(0, 0), a2, voffA);
;             PG8_WAIT_V(8); PG8_WAIT_L(0); PG8_BAR; PG8_MMA(1, 0, At, B0); PG8_MMA(1, 1, At, B1); PG8_BAR; PG8_SCHED;
.LBB0_254:
	s_add_u32 s18, s16, 0xfffc0080
	s_addc_u32 s19, s17, -1
	s_add_i32 s48, 0, 0x10000
	s_cmp_eq_u32 s47, 12
	s_cselect_b32 s21, s11, s19
	s_cselect_b32 s20, s42, s18
	v_add_u32_e32 v64, s48, v143
	s_cselect_b32 s19, s9, s46
	s_cselect_b32 s18, s44, s45
	s_add_i32 s50, 0, 0x14000
	ds_read_b128 v[146:149], v64
	ds_read_b128 v[150:153], v64 offset:1024
	ds_read_b128 v[154:157], v64 offset:2048
	ds_read_b128 v[158:161], v64 offset:3072
	v_add_u32_e32 v64, s50, v143
	ds_read_b128 v[162:165], v64
	ds_read_b128 v[166:169], v64 offset:1024
	ds_read_b128 v[170:173], v64 offset:2048
	ds_read_b128 v[174:177], v64 offset:3072
	v_lshl_add_u64 v[202:203], s[16:17], 0, v[140:141]
	s_add_i32 m0, s25, 0xc000
	ds_read_b128 v[178:181], v145
	ds_read_b128 v[182:185], v145 offset:1024
	ds_read_b128 v[186:189], v145 offset:2048
	ds_read_b128 v[190:193], v145 offset:3072
	ds_read_b128 v[194:197], v145 offset:4096
	ds_read_b128 v[198:201], v145 offset:5120
	ds_read_b128 v[206:209], v145 offset:6144
	ds_read_b128 v[214:217], v145 offset:7168
	global_load_lds_dwordx4 v[202:203], off
	v_lshl_add_u64 v[202:203], s[16:17], 0, v[138:139]
	s_add_i32 m0, s25, 0xe000
	s_nop 0
	global_load_lds_dwordx4 v[202:203], off
	s_waitcnt vmcnt(8) lgkmcnt(0)
	s_setprio 1
	s_barrier
	v_mfma_f32_16x16x32_bf16 v[126:129], v[146:149], v[178:181], v[126:129]
	v_mfma_f32_16x16x32_bf16 v[122:125], v[154:157], v[178:181], v[122:125]
	v_mfma_f32_16x16x32_bf16 v[110:113], v[146:149], v[186:189], v[110:113]
	v_mfma_f32_16x16x32_bf16 v[106:109], v[154:157], v[186:189], v[106:109]
	v_mfma_f32_16x16x32_bf16 v[94:97], v[146:149], v[194:197], v[94:97]
	v_mfma_f32_16x16x32_bf16 v[90:93], v[154:157], v[194:197], v[90:93]
	v_mfma_f32_16x16x32_bf16 v[78:81], v[146:149], v[206:209], v[78:81]
	v_mfma_f32_16x16x32_bf16 v[74:77], v[154:157], v[206:209], v[74:77]
	v_mfma_f32_16x16x32_bf16 v[126:129], v[150:153], v[182:185], v[126:129]
	v_mfma_f32_16x16x32_bf16 v[122:125], v[158:161], v[182:185], v[122:125]
	v_mfma_f32_16x16x32_bf16 v[110:113], v[150:153], v[190:193], v[110:113]
	v_mfma_f32_16x16x32_bf16 v[106:109], v[158:161], v[190:193], v[106:109]
	v_mfma_f32_16x16x32_bf16 v[94:97], v[150:153], v[198:201], v[94:97]
	v_mfma_f32_16x16x32_bf16 v[90:93], v[158:161], v[198:201], v[90:93]
	v_mfma_f32_16x16x32_bf16 v[78:81], v[150:153], v[214:217], v[78:81]
	v_mfma_f32_16x16x32_bf16 v[74:77], v[158:161], v[214:217], v[74:77]
	v_mfma_f32_16x16x32_bf16 v[118:121], v[162:165], v[178:181], v[118:121]
	v_mfma_f32_16x16x32_bf16 v[114:117], v[170:173], v[178:181], v[114:117]
	v_mfma_f32_16x16x32_bf16 v[102:105], v[162:165], v[186:189], v[102:105]
	v_mfma_f32_16x16x32_bf16 v[98:101], v[170:173], v[186:189], v[98:101]
	v_mfma_f32_16x16x32_bf16 v[86:89], v[162:165], v[194:197], v[86:89]
	v_mfma_f32_16x16x32_bf16 v[82:85], v[170:173], v[194:197], v[82:85]
	v_mfma_f32_16x16x32_bf16 v[70:73], v[162:165], v[206:209], v[70:73]
	v_mfma_f32_16x16x32_bf16 v[66:69], v[170:173], v[206:209], v[66:69]
	v_mfma_f32_16x16x32_bf16 v[118:121], v[166:169], v[182:185], v[118:121]
	v_mfma_f32_16x16x32_bf16 v[114:117], v[174:177], v[182:185], v[114:117]
	v_mfma_f32_16x16x32_bf16 v[102:105], v[166:169], v[190:193], v[102:105]
	v_mfma_f32_16x16x32_bf16 v[98:101], v[174:177], v[190:193], v[98:101]
	v_mfma_f32_16x16x32_bf16 v[86:89], v[166:169], v[198:201], v[86:89]
	v_mfma_f32_16x16x32_bf16 v[82:85], v[174:177], v[198:201], v[82:85]
	v_mfma_f32_16x16x32_bf16 v[70:73], v[166:169], v[214:217], v[70:73]
	v_mfma_f32_16x16x32_bf16 v[66:69], v[174:177], v[214:217], v[66:69]
	s_barrier
	s_setprio 0
	s_add_i32 s48, s48, s24
	v_lshl_add_u64 v[202:203], s[18:19], 0, v[134:135]
	s_mov_b32 m0, s48
	ds_read_b128 v[178:181], v145 offset:16384
	ds_read_b128 v[182:185], v145 offset:17408
	ds_read_b128 v[186:189], v145 offset:18432
	ds_read_b128 v[190:193], v145 offset:19456
	ds_read_b128 v[194:197], v145 offset:20480
	ds_read_b128 v[198:201], v145 offset:21504
	ds_read_b128 v[206:209], v145 offset:22528
	ds_read_b128 v[214:217], v145 offset:23552
	global_load_lds_dwordx4 v[202:203], off
	s_add_i32 m0, s48, 0x2000
	s_add_u32 s48, s18, 0x40000
	v_lshl_add_u64 v[210:211], s[18:19], 0, v[130:131]
	s_addc_u32 s49, s19, 0
	s_add_i32 s50, s50, s24
	global_load_lds_dwordx4 v[210:211], off
	v_lshl_add_u64 v[218:219], s[48:49], 0, v[134:135]
	s_mov_b32 m0, s50
	v_lshl_add_u64 v[220:221], s[20:21], 0, v[132:133]
	global_load_lds_dwordx4 v[218:219], off
	v_lshl_add_u64 v[218:219], s[48:49], 0, v[130:131]
	s_add_i32 m0, s50, 0x2000
	s_nop 0
	global_load_lds_dwordx4 v[218:219], off
	v_lshl_add_u64 v[218:219], s[20:21], 0, v[136:137]
	s_mov_b32 m0, s25
	s_nop 0
	global_load_lds_dwordx4 v[218:219], off
	s_mov_b32 m0, s26
	s_nop 0
	global_load_lds_dwordx4 v[220:221], off
	s_waitcnt vmcnt(8) lgkmcnt(0)
	s_setprio 1
	s_barrier
; #define PG8_STAGE(bufoff, gbase, voff) do { _Pragma("unroll") for (int _i = 0; _i < 2; ++_i) \
;         __builtin_amdgcn_global_load_lds((const unsigned*)((const char*)(gbase) + (voff)[_i]), (PG8_LAS unsigned*)(lds + (bufoff) + ldsw + _i * 8192), 16, 0, 0); } while (0)
; #define PG8_LDA(dst, b, h) do { _Pragma("unroll") for (int m = 0; m < 4; ++m) _Pragma("unroll") for (int k = 0; k < 2; ++k) dst[m][k] = *(const PG8_LAS bf16x8*)(lds + PG8_SA(b, h) + aoff + m * 2048 + k * 1024); } while (0)
; #define PG8_LDB(dst, b, h) do { _Pragma("unroll") for (int n = 0; n < 2; ++n) _Pragma("unroll") for (int k = 0; k < 2; ++k) dst[n][k] = *(const PG8_LAS bf16x8*)(lds + PG8_SB(b, h) + boff + n * 2048 + k * 1024); } while (0)
; #define PG8_MMA(ai, bj, At, Bt) do { __builtin_amdgcn_s_setprio(1); _Pragma("unroll") for (int m = 0; m < 4; ++m) _Pragma("unroll") for (int n = 0; n < 2; ++n) _Pragma("unroll") for (int k = 0; k < 2; ++k) \
;         acc[ai][bj][m][n] = __builtin_amdgcn_mfma_f32_16x16x32_bf16(Bt[n][k], At[m][k], acc[ai][bj][m][n], 0, 0, 0); __builtin_amdgcn_s_setprio(0); } while (0)
; #define PG8_WAIT_V(n) asm volatile("s_waitcnt vmcnt(" #n ")" ::: "memory")
; #define PG8_WAIT_L(n) asm volatile("s_waitcnt lgkmcnt(" #n ")" ::: "memory")
; #define PG8_BAR __builtin_amdgcn_s_barrier()
; #define PG8_SCHED __builtin_amdgcn_sched_barrier(0)
; template <class Epi, class Sched, bool ALIGN_EPI = false, bool SP2 = false>
; __device__ __forceinline__ void gemm_phase(PG8_LAS unsigned char* lds, const Gemm g, const Sched& S, const Epi& E, const int tid) {
;     ...
;             PG8_WAIT_V(8); PG8_WAIT_L(0); PG8_BAR; PG8_MMA(1, 0, At, B0); PG8_MMA(1, 1, At, B1); PG8_BAR; PG8_SCHED;
;             PG8_LDB(B0, 1, 0); PG8_LDB(B1, 1, 1); PG8_SCHED; PG8_LDA(At, 1, 0); PG8_STAGE(PG8_SA(0, 1), a2 + hstep, voffA);
;             PG8_WAIT_V(8); PG8_WAIT_L(0); PG8_BAR; PG8_MMA(0, 0, At, B0); PG8_MMA(0, 1, At, B1); PG8_BAR; PG8_SCHED;
	v_mfma_f32_16x16x32_bf16 v[60:63], v[146:149], v[178:181], v[60:63]
	v_mfma_f32_16x16x32_bf16 v[56:59], v[154:157], v[178:181], v[56:59]
	v_mfma_f32_16x16x32_bf16 v[44:47], v[146:149], v[186:189], v[44:47]
	v_mfma_f32_16x16x32_bf16 v[40:43], v[154:157], v[186:189], v[40:43]
	v_mfma_f32_16x16x32_bf16 v[28:31], v[146:149], v[194:197], v[28:31]
	v_mfma_f32_16x16x32_bf16 v[24:27], v[154:157], v[194:197], v[24:27]
	v_mfma_f32_16x16x32_bf16 v[12:15], v[146:149], v[206:209], v[12:15]
	v_mfma_f32_16x16x32_bf16 v[8:11], v[154:157], v[206:209], v[8:11]
	v_mfma_f32_16x16x32_bf16 v[60:63], v[150:153], v[182:185], v[60:63]
	v_mfma_f32_16x16x32_bf16 v[56:59], v[158:161], v[182:185], v[56:59]
	v_mfma_f32_16x16x32_bf16 v[44:47], v[150:153], v[190:193], v[44:47]
	v_mfma_f32_16x16x32_bf16 v[40:43], v[158:161], v[190:193], v[40:43]
	v_mfma_f32_16x16x32_bf16 v[28:31], v[150:153], v[198:201], v[28:31]
	v_mfma_f32_16x16x32_bf16 v[24:27], v[158:161], v[198:201], v[24:27]
	v_mfma_f32_16x16x32_bf16 v[12:15], v[150:153], v[214:217], v[12:15]
	v_mfma_f32_16x16x32_bf16 v[8:11], v[158:161], v[214:217], v[8:11]
	v_mfma_f32_16x16x32_bf16 v[52:55], v[162:165], v[178:181], v[52:55]
	v_mfma_f32_16x16x32_bf16 v[48:51], v[170:173], v[178:181], v[48:51]
	v_mfma_f32_16x16x32_bf16 v[36:39], v[162:165], v[186:189], v[36:39]
	v_mfma_f32_16x16x32_bf16 v[32:35], v[170:173], v[186:189], v[32:35]
	v_mfma_f32_16x16x32_bf16 v[20:23], v[162:165], v[194:197], v[20:23]
	v_mfma_f32_16x16x32_bf16 v[16:19], v[170:173], v[194:197], v[16:19]
	v_mfma_f32_16x16x32_bf16 v[4:7], v[162:165], v[206:209], v[4:7]
	v_mfma_f32_16x16x32_bf16 v[0:3], v[170:173], v[206:209], v[0:3]
	v_mfma_f32_16x16x32_bf16 v[52:55], v[166:169], v[182:185], v[52:55]
	v_mfma_f32_16x16x32_bf16 v[48:51], v[174:177], v[182:185], v[48:51]
	v_mfma_f32_16x16x32_bf16 v[36:39], v[166:169], v[190:193], v[36:39]
	v_mfma_f32_16x16x32_bf16 v[32:35], v[174:177], v[190:193], v[32:35]
	v_mfma_f32_16x16x32_bf16 v[20:23], v[166:169], v[198:201], v[20:23]
	v_mfma_f32_16x16x32_bf16 v[16:19], v[174:177], v[198:201], v[16:19]
	v_mfma_f32_16x16x32_bf16 v[4:7], v[166:169], v[214:217], v[4:7]
	v_mfma_f32_16x16x32_bf16 v[0:3], v[174:177], v[214:217], v[0:3]
	s_barrier
	s_setprio 0
	s_add_i32 s48, 0, 0x18000
	v_add_u32_e32 v64, s48, v143
	s_add_i32 s49, 0, 0x1c000
	ds_read_b128 v[146:149], v64
	ds_read_b128 v[150:153], v64 offset:1024
	ds_read_b128 v[154:157], v64 offset:2048
	ds_read_b128 v[158:161], v64 offset:3072
	v_add_u32_e32 v64, s49, v143
	ds_read_b128 v[162:165], v64
	ds_read_b128 v[166:169], v64 offset:1024
	ds_read_b128 v[170:173], v64 offset:2048
	ds_read_b128 v[174:177], v64 offset:3072
	s_add_u32 s20, s20, 0x40000
	s_addc_u32 s21, s21, 0
	s_mov_b32 m0, s27
	v_lshl_add_u64 v[222:223], s[20:21], 0, v[136:137]
	ds_read_b128 v[178:181], v145 offset:32768
	ds_read_b128 v[182:185], v145 offset:33792
	ds_read_b128 v[186:189], v145 offset:34816
	ds_read_b128 v[190:193], v145 offset:35840
	ds_read_b128 v[194:197], v145 offset:36864
	ds_read_b128 v[198:201], v145 offset:37888
	ds_read_b128 v[206:209], v145 offset:38912
	ds_read_b128 v[214:217], v145 offset:39936
	global_load_lds_dwordx4 v[222:223], off
	v_lshl_add_u64 v[222:223], s[20:21], 0, v[132:133]
	s_mov_b32 m0, s28
	s_nop 0
	global_load_lds_dwordx4 v[222:223], off
	s_waitcnt vmcnt(8) lgkmcnt(0)
	s_setprio 1
	s_barrier
	v_mfma_f32_16x16x32_bf16 v[126:129], v[146:149], v[178:181], v[126:129]
	v_mfma_f32_16x16x32_bf16 v[122:125], v[154:157], v[178:181], v[122:125]
	v_mfma_f32_16x16x32_bf16 v[110:113], v[146:149], v[186:189], v[110:113]
	v_mfma_f32_16x16x32_bf16 v[106:109], v[154:157], v[186:189], v[106:109]
	v_mfma_f32_16x16x32_bf16 v[94:97], v[146:149], v[194:197], v[94:97]
	v_mfma_f32_16x16x32_bf16 v[90:93], v[154:157], v[194:197], v[90:93]
	v_mfma_f32_16x16x32_bf16 v[78:81], v[146:149], v[206:209], v[78:81]
	v_mfma_f32_16x16x32_bf16 v[74:77], v[154:157], v[206:209], v[74:77]
	v_mfma_f32_16x16x32_bf16 v[126:129], v[150:153], v[182:185], v[126:129]
	v_mfma_f32_16x16x32_bf16 v[122:125], v[158:161], v[182:185], v[122:125]
	v_mfma_f32_16x16x32_bf16 v[110:113], v[150:153], v[190:193], v[110:113]
	v_mfma_f32_16x16x32_bf16 v[106:109], v[158:161], v[190:193], v[106:109]
	v_mfma_f32_16x16x32_bf16 v[94:97], v[150:153], v[198:201], v[94:97]
	v_mfma_f32_16x16x32_bf16 v[90:93], v[158:161], v[198:201], v[90:93]
	v_mfma_f32_16x16x32_bf16 v[78:81], v[150:153], v[214:217], v[78:81]
	v_mfma_f32_16x16x32_bf16 v[74:77], v[158:161], v[214:217], v[74:77]
	v_mfma_f32_16x16x32_bf16 v[118:121], v[162:165], v[178:181], v[118:121]
	v_mfma_f32_16x16x32_bf16 v[114:117], v[170:173], v[178:181], v[114:117]
	v_mfma_f32_16x16x32_bf16 v[102:105], v[162:165], v[186:189], v[102:105]
	v_mfma_f32_16x16x32_bf16 v[98:101], v[170:173], v[186:189], v[98:101]
	v_mfma_f32_16x16x32_bf16 v[86:89], v[162:165], v[194:197], v[86:89]
	v_mfma_f32_16x16x32_bf16 v[82:85], v[170:173], v[194:197], v[82:85]
	v_mfma_f32_16x16x32_bf16 v[70:73], v[162:165], v[206:209], v[70:73]
	v_mfma_f32_16x16x32_bf16 v[66:69], v[170:173], v[206:209], v[66:69]
	v_mfma_f32_16x16x32_bf16 v[118:121], v[166:169], v[182:185], v[118:121]
	v_mfma_f32_16x16x32_bf16 v[114:117], v[174:177], v[182:185], v[114:117]
	v_mfma_f32_16x16x32_bf16 v[102:105], v[166:169], v[190:193], v[102:105]
	v_mfma_f32_16x16x32_bf16 v[98:101], v[174:177], v[190:193], v[98:101]
	v_mfma_f32_16x16x32_bf16 v[86:89], v[166:169], v[198:201], v[86:89]
	v_mfma_f32_16x16x32_bf16 v[82:85], v[174:177], v[198:201], v[82:85]
	v_mfma_f32_16x16x32_bf16 v[70:73], v[166:169], v[214:217], v[70:73]
	v_mfma_f32_16x16x32_bf16 v[66:69], v[174:177], v[214:217], v[66:69]
	s_barrier
; #define PG8_STAGE(bufoff, gbase, voff) do { _Pragma("unroll") for (int _i = 0; _i < 2; ++_i) \
;         __builtin_amdgcn_global_load_lds((const unsigned*)((const char*)(gbase) + (voff)[_i]), (PG8_LAS unsigned*)(lds + (bufoff) + ldsw + _i * 8192), 16, 0, 0); } while (0)
; #define PG8_LDA(dst, b, h) do { _Pragma("unroll") for (int m = 0; m < 4; ++m) _Pragma("unroll") for (int k = 0; k < 2; ++k) dst[m][k] = *(const PG8_LAS bf16x8*)(lds + PG8_SA(b, h) + aoff + m * 2048 + k * 1024); } while (0)
; #define PG8_MMA(ai, bj, At, Bt) do { __builtin_amdgcn_s_setprio(1); _Pragma("unroll") for (int m = 0; m < 4; ++m) _Pragma("unroll") for (int n = 0; n < 2; ++n) _Pragma("unroll") for (int k = 0; k < 2; ++k) \
;         acc[ai][bj][m][n] = __builtin_amdgcn_mfma_f32_16x16x32_bf16(Bt[n][k], At[m][k], acc[ai][bj][m][n], 0, 0, 0); __builtin_amdgcn_s_setprio(0); } while (0)
; #define PG8_WAIT_V(n) asm volatile("s_waitcnt vmcnt(" #n ")" ::: "memory")
; #define PG8_WAIT_L(n) asm volatile("s_waitcnt lgkmcnt(" #n ")" ::: "memory")
; #define PG8_BAR __builtin_amdgcn_s_barrier()
; #define PG8_SCHED __builtin_amdgcn_sched_barrier(0)
; template <class Epi, class Sched, bool ALIGN_EPI = false, bool SP2 = false>
; __device__ __forceinline__ void gemm_phase(PG8_LAS unsigned char* lds, const Gemm g, const Sched& S, const Epi& E, const int tid) {
;     ...
;             PG8_LDA(At, 1, 1); PG8_STAGE(PG8_SB(1, 0), b3, voffB); PG8_STAGE(PG8_SB(1, 1), b3 + hstep, voffB); PG8_STAGE(PG8_SA(1, 0), a3, voffA);
;             PG8_WAIT_V(8); PG8_WAIT_L(0); PG8_BAR; PG8_MMA(1, 0, At, B0); PG8_MMA(1, 1, At, B1); PG8_BAR; PG8_SCHED;
;     ...
;         if constexpr (ALIGN_EPI) { if (wr == 0) PG8_BAR; }
	s_setprio 0
	s_add_i32 s20, s48, s24
	v_lshl_add_u64 v[202:203], v[202:203], 0, s[94:95]
	s_mov_b32 m0, s20
	ds_read_b128 v[178:181], v145 offset:49152
	ds_read_b128 v[182:185], v145 offset:50176
	ds_read_b128 v[186:189], v145 offset:51200
	ds_read_b128 v[190:193], v145 offset:52224
	ds_read_b128 v[194:197], v145 offset:53248
	ds_read_b128 v[198:201], v145 offset:54272
	ds_read_b128 v[206:209], v145 offset:55296
	ds_read_b128 v[214:217], v145 offset:56320
	global_load_lds_dwordx4 v[202:203], off
	s_add_i32 m0, s20, 0x2000
	s_add_u32 s18, s18, 0x40080
	v_lshl_add_u64 v[202:203], v[210:211], 0, s[94:95]
	s_addc_u32 s19, s19, 0
	s_add_i32 s20, s49, s24
	global_load_lds_dwordx4 v[202:203], off
	v_lshl_add_u64 v[202:203], s[18:19], 0, v[134:135]
	s_mov_b32 m0, s20
	s_nop 0
	global_load_lds_dwordx4 v[202:203], off
	v_lshl_add_u64 v[202:203], s[18:19], 0, v[130:131]
	s_add_i32 m0, s20, 0x2000
	s_nop 0
	global_load_lds_dwordx4 v[202:203], off
	v_lshl_add_u64 v[202:203], v[218:219], 0, s[94:95]
	s_mov_b32 m0, s29
	s_nop 0
	global_load_lds_dwordx4 v[202:203], off
	v_lshl_add_u64 v[202:203], v[220:221], 0, s[94:95]
	s_mov_b32 m0, s30
	s_nop 0
	global_load_lds_dwordx4 v[202:203], off
	s_waitcnt vmcnt(8) lgkmcnt(0)
	s_setprio 1
	s_barrier
	v_mfma_f32_16x16x32_bf16 v[60:63], v[146:149], v[178:181], v[60:63]
	v_mfma_f32_16x16x32_bf16 v[56:59], v[154:157], v[178:181], v[56:59]
	v_mfma_f32_16x16x32_bf16 v[44:47], v[146:149], v[186:189], v[44:47]
	v_mfma_f32_16x16x32_bf16 v[40:43], v[154:157], v[186:189], v[40:43]
	v_mfma_f32_16x16x32_bf16 v[28:31], v[146:149], v[194:197], v[28:31]
	v_mfma_f32_16x16x32_bf16 v[24:27], v[154:157], v[194:197], v[24:27]
	v_mfma_f32_16x16x32_bf16 v[12:15], v[146:149], v[206:209], v[12:15]
	v_mfma_f32_16x16x32_bf16 v[8:11], v[154:157], v[206:209], v[8:11]
	v_mfma_f32_16x16x32_bf16 v[60:63], v[150:153], v[182:185], v[60:63]
	v_mfma_f32_16x16x32_bf16 v[56:59], v[158:161], v[182:185], v[56:59]
	v_mfma_f32_16x16x32_bf16 v[44:47], v[150:153], v[190:193], v[44:47]
	v_mfma_f32_16x16x32_bf16 v[40:43], v[158:161], v[190:193], v[40:43]
	v_mfma_f32_16x16x32_bf16 v[28:31], v[150:153], v[198:201], v[28:31]
	v_mfma_f32_16x16x32_bf16 v[24:27], v[158:161], v[198:201], v[24:27]
	v_mfma_f32_16x16x32_bf16 v[12:15], v[150:153], v[214:217], v[12:15]
	v_mfma_f32_16x16x32_bf16 v[8:11], v[158:161], v[214:217], v[8:11]
	v_mfma_f32_16x16x32_bf16 v[52:55], v[162:165], v[178:181], v[52:55]
	v_mfma_f32_16x16x32_bf16 v[48:51], v[170:173], v[178:181], v[48:51]
	v_mfma_f32_16x16x32_bf16 v[36:39], v[162:165], v[186:189], v[36:39]
	v_mfma_f32_16x16x32_bf16 v[32:35], v[170:173], v[186:189], v[32:35]
	v_mfma_f32_16x16x32_bf16 v[20:23], v[162:165], v[194:197], v[20:23]
	v_mfma_f32_16x16x32_bf16 v[16:19], v[170:173], v[194:197], v[16:19]
	v_mfma_f32_16x16x32_bf16 v[4:7], v[162:165], v[206:209], v[4:7]
	v_mfma_f32_16x16x32_bf16 v[0:3], v[170:173], v[206:209], v[0:3]
	v_mfma_f32_16x16x32_bf16 v[52:55], v[166:169], v[182:185], v[52:55]
	v_mfma_f32_16x16x32_bf16 v[48:51], v[174:177], v[182:185], v[48:51]
	v_mfma_f32_16x16x32_bf16 v[36:39], v[166:169], v[190:193], v[36:39]
	v_mfma_f32_16x16x32_bf16 v[32:35], v[174:177], v[190:193], v[32:35]
	v_mfma_f32_16x16x32_bf16 v[20:23], v[166:169], v[198:201], v[20:23]
	v_mfma_f32_16x16x32_bf16 v[16:19], v[174:177], v[198:201], v[16:19]
	v_mfma_f32_16x16x32_bf16 v[4:7], v[166:169], v[214:217], v[4:7]
	v_mfma_f32_16x16x32_bf16 v[0:3], v[174:177], v[214:217], v[0:3]
	s_barrier
	s_setprio 0
	s_add_i32 s47, s47, 2
	s_add_u32 s45, s45, 0x100
	s_addc_u32 s46, s46, 0
	s_add_u32 s16, s16, 0x100
	s_addc_u32 s17, s17, 0
	s_cmp_gt_u32 s47, 13
	s_cbranch_scc0 .LBB0_254
	s_and_b64 vcc, exec, s[4:5]
	s_cbranch_vccz .LBB0_257
	s_barrier

; #define PG8_STAGE(bufoff, gbase, voff) do { _Pragma("unroll") for (int _i = 0; _i < 2; ++_i) \
;         __builtin_amdgcn_global_load_lds((const unsigned*)((const char*)(gbase) + (voff)[_i]), (PG8_LAS unsigned*)(lds + (bufoff) + ldsw + _i * 8192), 16, 0, 0); } while (0)
; #define PG8_LDA(dst, b, h) do { _Pragma("unroll") for (int m = 0; m < 4; ++m) _Pragma("unroll") for (int k = 0; k < 2; ++k) dst[m][k] = *(const PG8_LAS bf16x8*)(lds + PG8_SA(b, h) + aoff + m * 2048 + k * 1024); } while (0)
; #define PG8_LDB(dst, b, h) do { _Pragma("unroll") for (int n = 0; n < 2; ++n) _Pragma("unroll") for (int k = 0; k < 2; ++k) dst[n][k] = *(const PG8_LAS bf16x8*)(lds + PG8_SB(b, h) + boff + n * 2048 + k * 1024); } while (0)
; #define PG8_MMA(ai, bj, At, Bt) do { __builtin_amdgcn_s_setprio(1); _Pragma("unroll") for (int m = 0; m < 4; ++m) _Pragma("unroll") for (int n = 0; n < 2; ++n) _Pragma("unroll") for (int k = 0; k < 2; ++k) \
;         acc[ai][bj][m][n] = __builtin_amdgcn_mfma_f32_16x16x32_bf16(Bt[n][k], At[m][k], acc[ai][bj][m][n], 0, 0, 0); __builtin_amdgcn_s_setprio(0); } while (0)
; #define PG8_WAIT_V(n) asm volatile("s_waitcnt vmcnt(" #n ")" ::: "memory")
; #define PG8_WAIT_L(n) asm volatile("s_waitcnt lgkmcnt(" #n ")" ::: "memory")
; template <class Epi, class Sched, bool ALIGN_EPI = false, bool SP2 = false>
; __device__ __forceinline__ void gemm_phase(PG8_LAS unsigned char* lds, const Gemm g, const Sched& S, const Epi& E, const int tid) {
;     ...
;             const bool last = (t == nt - 2);
;             const char* a1 = cA + (size_t)(t + 1) * kstep;
;             const char* a2 = last ? nA : cA + (size_t)(t + 2) * kstep; const char* b2 = last ? nB : cB + (size_t)(t + 2) * kstep;
;             const char* a3 = a2 + kstep; const char* b3 = b2 + kstep;
;             if (last && has_next) S.a_ready(nxt);
;             if constexpr (SP2) {
;             PG8_LDB(B0, 0, 0); PG8_LDB(B1, 0, 1); PG8_SCHED; PG8_LDA(At, 0, 0); PG8_STAGE(PG8_SA(1, 1), a1 + hstep, voffA);
;             PG8_WAIT_V(8); PG8_WAIT_L(0); PG8_BAR; PG8_MMA(0, 0, At, B0); PG8_MMA(0, 1, At, B1); PG8_BAR; PG8_SCHED;
;             PG8_LDA(At, 0, 1); PG8_STAGE(PG8_SB(0, 0), b2, voffB); PG8_STAGE(PG8_SB(0, 1), b2 + hstep, voffB); PG8_STAGE(PG8_SA(0, 0), a2, voffA);
;             PG8_WAIT_V(8); PG8_WAIT_L(0); PG8_BAR; PG8_MMA(1, 0, At, B0); PG8_MMA(1, 1, At, B1); PG8_BAR; PG8_SCHED;
.LBB0_286:
	s_add_u32 s20, s8, s18
	s_addc_u32 s21, s9, s19
	s_add_u32 s20, s20, 0x100
	s_addc_u32 s21, s21, 0
	s_add_u32 s54, s49, s18
	s_addc_u32 s55, s50, s19
	s_add_i32 s56, 0, 0x10000
	s_cmpk_eq_i32 s18, 0x700
	s_cselect_b32 s23, s13, s21
	s_cselect_b32 s22, s51, s20
	s_cselect_b32 s21, s11, s55
	s_cselect_b32 s20, s52, s54
	s_add_i32 s57, 0, 0x14000
	v_add_u32_e32 v86, s56, v72
	v_add_u32_e32 v110, s57, v72
	ds_read_b128 v[74:77], v86
	ds_read_b128 v[78:81], v86 offset:1024
	ds_read_b128 v[82:85], v86 offset:2048
	ds_read_b128 v[86:89], v86 offset:3072
	ds_read_b128 v[90:93], v110
	ds_read_b128 v[94:97], v110 offset:1024
	ds_read_b128 v[106:109], v110 offset:2048
	ds_read_b128 v[110:113], v110 offset:3072
	v_lshl_add_u64 v[202:203], v[70:71], 0, s[18:19]
	s_add_i32 m0, s31, 0xc000
	ds_read_b128 v[114:117], v73
	ds_read_b128 v[118:121], v73 offset:1024
	ds_read_b128 v[122:125], v73 offset:2048
	ds_read_b128 v[126:129], v73 offset:3072
	ds_read_b128 v[194:197], v73 offset:4096
	ds_read_b128 v[198:201], v73 offset:5120
	ds_read_b128 v[206:209], v73 offset:6144
	ds_read_b128 v[214:217], v73 offset:7168
	global_load_lds_dwordx4 v[202:203], off
	v_lshl_add_u64 v[202:203], v[68:69], 0, s[18:19]
	s_add_i32 m0, s31, 0xe000
	s_nop 0
	global_load_lds_dwordx4 v[202:203], off
	s_waitcnt vmcnt(8) lgkmcnt(0)
	s_setprio 1
	s_barrier
	v_mfma_f32_16x16x32_bf16 v[190:193], v[74:77], v[114:117], v[190:193]
	v_mfma_f32_16x16x32_bf16 v[186:189], v[82:85], v[114:117], v[186:189]
	v_mfma_f32_16x16x32_bf16 v[182:185], v[74:77], v[122:125], v[182:185]
	v_mfma_f32_16x16x32_bf16 v[178:181], v[82:85], v[122:125], v[178:181]
	v_mfma_f32_16x16x32_bf16 v[174:177], v[74:77], v[194:197], v[174:177]
	v_mfma_f32_16x16x32_bf16 v[170:173], v[82:85], v[194:197], v[170:173]
	v_mfma_f32_16x16x32_bf16 v[166:169], v[74:77], v[206:209], v[166:169]
	v_mfma_f32_16x16x32_bf16 v[162:165], v[82:85], v[206:209], v[162:165]
	v_mfma_f32_16x16x32_bf16 v[190:193], v[78:81], v[118:121], v[190:193]
	v_mfma_f32_16x16x32_bf16 v[186:189], v[86:89], v[118:121], v[186:189]
	v_mfma_f32_16x16x32_bf16 v[182:185], v[78:81], v[126:129], v[182:185]
	v_mfma_f32_16x16x32_bf16 v[178:181], v[86:89], v[126:129], v[178:181]
	v_mfma_f32_16x16x32_bf16 v[174:177], v[78:81], v[198:201], v[174:177]
	v_mfma_f32_16x16x32_bf16 v[170:173], v[86:89], v[198:201], v[170:173]
	v_mfma_f32_16x16x32_bf16 v[166:169], v[78:81], v[214:217], v[166:169]
	v_mfma_f32_16x16x32_bf16 v[162:165], v[86:89], v[214:217], v[162:165]
	v_mfma_f32_16x16x32_bf16 v[102:105], v[90:93], v[114:117], v[102:105]
	v_mfma_f32_16x16x32_bf16 v[98:101], v[106:109], v[114:117], v[98:101]
	v_mfma_f32_16x16x32_bf16 v[56:59], v[90:93], v[122:125], v[56:59]
	v_mfma_f32_16x16x32_bf16 v[48:51], v[106:109], v[122:125], v[48:51]
	v_mfma_f32_16x16x32_bf16 v[44:47], v[90:93], v[194:197], v[44:47]
	v_mfma_f32_16x16x32_bf16 v[40:43], v[106:109], v[194:197], v[40:43]
	v_mfma_f32_16x16x32_bf16 v[36:39], v[90:93], v[206:209], v[36:39]
	v_mfma_f32_16x16x32_bf16 v[32:35], v[106:109], v[206:209], v[32:35]
	v_mfma_f32_16x16x32_bf16 v[102:105], v[94:97], v[118:121], v[102:105]
	v_mfma_f32_16x16x32_bf16 v[98:101], v[110:113], v[118:121], v[98:101]
	v_mfma_f32_16x16x32_bf16 v[56:59], v[94:97], v[126:129], v[56:59]
	v_mfma_f32_16x16x32_bf16 v[48:51], v[110:113], v[126:129], v[48:51]
	v_mfma_f32_16x16x32_bf16 v[44:47], v[94:97], v[198:201], v[44:47]
	v_mfma_f32_16x16x32_bf16 v[40:43], v[110:113], v[198:201], v[40:43]
	v_mfma_f32_16x16x32_bf16 v[36:39], v[94:97], v[214:217], v[36:39]
	v_mfma_f32_16x16x32_bf16 v[32:35], v[110:113], v[214:217], v[32:35]
	s_barrier
	s_setprio 0
	s_add_i32 s54, s56, s30
	v_lshl_add_u64 v[202:203], s[20:21], 0, v[64:65]
	s_mov_b32 m0, s54
	ds_read_b128 v[114:117], v73 offset:16384
	ds_read_b128 v[118:121], v73 offset:17408
	ds_read_b128 v[122:125], v73 offset:18432
	ds_read_b128 v[126:129], v73 offset:19456
	ds_read_b128 v[194:197], v73 offset:20480
	ds_read_b128 v[198:201], v73 offset:21504
	ds_read_b128 v[206:209], v73 offset:22528
	ds_read_b128 v[214:217], v73 offset:23552
	global_load_lds_dwordx4 v[202:203], off
	s_add_i32 m0, s54, 0x2000
	s_add_u32 s54, s20, 0x40000
	v_lshl_add_u64 v[210:211], s[20:21], 0, v[52:53]
	s_addc_u32 s55, s21, 0
	s_add_i32 s56, s57, s30
	global_load_lds_dwordx4 v[210:211], off
	v_lshl_add_u64 v[218:219], s[54:55], 0, v[64:65]
	s_mov_b32 m0, s56
	v_lshl_add_u64 v[226:227], s[22:23], 0, v[60:61]
	global_load_lds_dwordx4 v[218:219], off
	v_lshl_add_u64 v[218:219], s[54:55], 0, v[52:53]
	s_add_i32 m0, s56, 0x2000
	v_lshl_add_u64 v[228:229], s[22:23], 0, v[54:55]
	global_load_lds_dwordx4 v[218:219], off
	s_mov_b32 m0, s31
	s_nop 0
	global_load_lds_dwordx4 v[226:227], off
	s_mov_b32 m0, s35
	s_nop 0
	global_load_lds_dwordx4 v[228:229], off
	s_waitcnt vmcnt(8) lgkmcnt(0)
	s_setprio 1
	s_barrier
; #define PG8_STAGE(bufoff, gbase, voff) do { _Pragma("unroll") for (int _i = 0; _i < 2; ++_i) \
;         __builtin_amdgcn_global_load_lds((const unsigned*)((const char*)(gbase) + (voff)[_i]), (PG8_LAS unsigned*)(lds + (bufoff) + ldsw + _i * 8192), 16, 0, 0); } while (0)
; #define PG8_LDA(dst, b, h) do { _Pragma("unroll") for (int m = 0; m < 4; ++m) _Pragma("unroll") for (int k = 0; k < 2; ++k) dst[m][k] = *(const PG8_LAS bf16x8*)(lds + PG8_SA(b, h) + aoff + m * 2048 + k * 1024); } while (0)
; #define PG8_LDB(dst, b, h) do { _Pragma("unroll") for (int n = 0; n < 2; ++n) _Pragma("unroll") for (int k = 0; k < 2; ++k) dst[n][k] = *(const PG8_LAS bf16x8*)(lds + PG8_SB(b, h) + boff + n * 2048 + k * 1024); } while (0)
; #define PG8_MMA(ai, bj, At, Bt) do { __builtin_amdgcn_s_setprio(1); _Pragma("unroll") for (int m = 0; m < 4; ++m) _Pragma("unroll") for (int n = 0; n < 2; ++n) _Pragma("unroll") for (int k = 0; k < 2; ++k) \
;         acc[ai][bj][m][n] = __builtin_amdgcn_mfma_f32_16x16x32_bf16(Bt[n][k], At[m][k], acc[ai][bj][m][n], 0, 0, 0); __builtin_amdgcn_s_setprio(0); } while (0)
; #define PG8_WAIT_V(n) asm volatile("s_waitcnt vmcnt(" #n ")" ::: "memory")
; #define PG8_WAIT_L(n) asm volatile("s_waitcnt lgkmcnt(" #n ")" ::: "memory")
; #define PG8_BAR __builtin_amdgcn_s_barrier()
; #define PG8_SCHED __builtin_amdgcn_sched_barrier(0)
; template <class Epi, class Sched, bool ALIGN_EPI = false, bool SP2 = false>
; __device__ __forceinline__ void gemm_phase(PG8_LAS unsigned char* lds, const Gemm g, const Sched& S, const Epi& E, const int tid) {
;     ...
;             PG8_WAIT_V(8); PG8_WAIT_L(0); PG8_BAR; PG8_MMA(1, 0, At, B0); PG8_MMA(1, 1, At, B1); PG8_BAR; PG8_SCHED;
;             PG8_LDB(B0, 1, 0); PG8_LDB(B1, 1, 1); PG8_SCHED; PG8_LDA(At, 1, 0); PG8_STAGE(PG8_SA(0, 1), a2 + hstep, voffA);
;             PG8_WAIT_V(8); PG8_WAIT_L(0); PG8_BAR; PG8_MMA(0, 0, At, B0); PG8_MMA(0, 1, At, B1); PG8_BAR; PG8_SCHED;
	v_mfma_f32_16x16x32_bf16 v[158:161], v[74:77], v[114:117], v[158:161]
	v_mfma_f32_16x16x32_bf16 v[154:157], v[82:85], v[114:117], v[154:157]
	v_mfma_f32_16x16x32_bf16 v[150:153], v[74:77], v[122:125], v[150:153]
	v_mfma_f32_16x16x32_bf16 v[146:149], v[82:85], v[122:125], v[146:149]
	v_mfma_f32_16x16x32_bf16 v[142:145], v[74:77], v[194:197], v[142:145]
	v_mfma_f32_16x16x32_bf16 v[138:141], v[82:85], v[194:197], v[138:141]
	v_mfma_f32_16x16x32_bf16 v[74:77], v[74:77], v[206:209], v[134:137]
	v_mfma_f32_16x16x32_bf16 v[158:161], v[78:81], v[118:121], v[158:161]
	v_mfma_f32_16x16x32_bf16 v[154:157], v[86:89], v[118:121], v[154:157]
	v_mfma_f32_16x16x32_bf16 v[150:153], v[78:81], v[126:129], v[150:153]
	v_mfma_f32_16x16x32_bf16 v[146:149], v[86:89], v[126:129], v[146:149]
	v_mfma_f32_16x16x32_bf16 v[142:145], v[78:81], v[198:201], v[142:145]
	v_mfma_f32_16x16x32_bf16 v[138:141], v[86:89], v[198:201], v[138:141]
	v_mfma_f32_16x16x32_bf16 v[74:77], v[78:81], v[214:217], v[74:77]
	v_mfma_f32_16x16x32_bf16 v[78:81], v[82:85], v[206:209], v[130:133]
	v_mfma_f32_16x16x32_bf16 v[78:81], v[86:89], v[214:217], v[78:81]
	v_mfma_f32_16x16x32_bf16 v[28:31], v[90:93], v[114:117], v[28:31]
	v_mfma_f32_16x16x32_bf16 v[24:27], v[106:109], v[114:117], v[24:27]
	v_mfma_f32_16x16x32_bf16 v[20:23], v[90:93], v[122:125], v[20:23]
	v_mfma_f32_16x16x32_bf16 v[16:19], v[106:109], v[122:125], v[16:19]
	v_mfma_f32_16x16x32_bf16 v[12:15], v[90:93], v[194:197], v[12:15]
	v_mfma_f32_16x16x32_bf16 v[8:11], v[106:109], v[194:197], v[8:11]
	v_mfma_f32_16x16x32_bf16 v[4:7], v[90:93], v[206:209], v[4:7]
	v_mfma_f32_16x16x32_bf16 v[0:3], v[106:109], v[206:209], v[0:3]
	v_mfma_f32_16x16x32_bf16 v[28:31], v[94:97], v[118:121], v[28:31]
	v_mfma_f32_16x16x32_bf16 v[24:27], v[110:113], v[118:121], v[24:27]
	v_mfma_f32_16x16x32_bf16 v[20:23], v[94:97], v[126:129], v[20:23]
	v_mfma_f32_16x16x32_bf16 v[16:19], v[110:113], v[126:129], v[16:19]
	v_mfma_f32_16x16x32_bf16 v[12:15], v[94:97], v[198:201], v[12:15]
	v_mfma_f32_16x16x32_bf16 v[8:11], v[110:113], v[198:201], v[8:11]
	v_mfma_f32_16x16x32_bf16 v[4:7], v[94:97], v[214:217], v[4:7]
	v_mfma_f32_16x16x32_bf16 v[0:3], v[110:113], v[214:217], v[0:3]
	s_barrier
	s_setprio 0
	s_add_i32 s54, 0, 0x18000
	s_add_i32 s55, 0, 0x1c000
	v_add_u32_e32 v94, s54, v72
	v_add_u32_e32 v118, s55, v72
	ds_read_b128 v[82:85], v94
	ds_read_b128 v[86:89], v94 offset:1024
	ds_read_b128 v[90:93], v94 offset:2048
	ds_read_b128 v[94:97], v94 offset:3072
	ds_read_b128 v[106:109], v118
	ds_read_b128 v[110:113], v118 offset:1024
	ds_read_b128 v[114:117], v118 offset:2048
	ds_read_b128 v[118:121], v118 offset:3072
	s_add_u32 s22, s22, 0x40000
	s_addc_u32 s23, s23, 0
	s_mov_b32 m0, s42
	v_lshl_add_u64 v[218:219], s[22:23], 0, v[60:61]
	ds_read_b128 v[122:125], v73 offset:32768
	ds_read_b128 v[126:129], v73 offset:33792
	ds_read_b128 v[130:133], v73 offset:34816
	ds_read_b128 v[134:137], v73 offset:35840
	ds_read_b128 v[194:197], v73 offset:36864
	ds_read_b128 v[198:201], v73 offset:37888
	ds_read_b128 v[206:209], v73 offset:38912
	ds_read_b128 v[214:217], v73 offset:39936
	global_load_lds_dwordx4 v[218:219], off
	v_lshl_add_u64 v[218:219], s[22:23], 0, v[54:55]
	s_mov_b32 m0, s44
	s_nop 0
	global_load_lds_dwordx4 v[218:219], off
	s_waitcnt vmcnt(8) lgkmcnt(0)
	s_setprio 1
	s_barrier
	v_mfma_f32_16x16x32_bf16 v[190:193], v[82:85], v[122:125], v[190:193]
	v_mfma_f32_16x16x32_bf16 v[186:189], v[90:93], v[122:125], v[186:189]
	v_mfma_f32_16x16x32_bf16 v[182:185], v[82:85], v[130:133], v[182:185]
	v_mfma_f32_16x16x32_bf16 v[178:181], v[90:93], v[130:133], v[178:181]
	v_mfma_f32_16x16x32_bf16 v[174:177], v[82:85], v[194:197], v[174:177]
	v_mfma_f32_16x16x32_bf16 v[170:173], v[90:93], v[194:197], v[170:173]
	v_mfma_f32_16x16x32_bf16 v[166:169], v[82:85], v[206:209], v[166:169]
	v_mfma_f32_16x16x32_bf16 v[162:165], v[90:93], v[206:209], v[162:165]
	v_mfma_f32_16x16x32_bf16 v[190:193], v[86:89], v[126:129], v[190:193]
	v_mfma_f32_16x16x32_bf16 v[186:189], v[94:97], v[126:129], v[186:189]
	v_mfma_f32_16x16x32_bf16 v[182:185], v[86:89], v[134:137], v[182:185]
	v_mfma_f32_16x16x32_bf16 v[178:181], v[94:97], v[134:137], v[178:181]
	v_mfma_f32_16x16x32_bf16 v[174:177], v[86:89], v[198:201], v[174:177]
	v_mfma_f32_16x16x32_bf16 v[170:173], v[94:97], v[198:201], v[170:173]
	v_mfma_f32_16x16x32_bf16 v[166:169], v[86:89], v[214:217], v[166:169]
	v_mfma_f32_16x16x32_bf16 v[162:165], v[94:97], v[214:217], v[162:165]
	v_mfma_f32_16x16x32_bf16 v[102:105], v[106:109], v[122:125], v[102:105]
	v_mfma_f32_16x16x32_bf16 v[98:101], v[114:117], v[122:125], v[98:101]
	v_mfma_f32_16x16x32_bf16 v[56:59], v[106:109], v[130:133], v[56:59]
	v_mfma_f32_16x16x32_bf16 v[48:51], v[114:117], v[130:133], v[48:51]
	v_mfma_f32_16x16x32_bf16 v[44:47], v[106:109], v[194:197], v[44:47]
	v_mfma_f32_16x16x32_bf16 v[40:43], v[114:117], v[194:197], v[40:43]
	v_mfma_f32_16x16x32_bf16 v[36:39], v[106:109], v[206:209], v[36:39]
	v_mfma_f32_16x16x32_bf16 v[32:35], v[114:117], v[206:209], v[32:35]
	v_mfma_f32_16x16x32_bf16 v[102:105], v[110:113], v[126:129], v[102:105]
	v_mfma_f32_16x16x32_bf16 v[98:101], v[118:121], v[126:129], v[98:101]
	v_mfma_f32_16x16x32_bf16 v[56:59], v[110:113], v[134:137], v[56:59]
	v_mfma_f32_16x16x32_bf16 v[48:51], v[118:121], v[134:137], v[48:51]
	v_mfma_f32_16x16x32_bf16 v[44:47], v[110:113], v[198:201], v[44:47]
	v_mfma_f32_16x16x32_bf16 v[40:43], v[118:121], v[198:201], v[40:43]
	v_mfma_f32_16x16x32_bf16 v[36:39], v[110:113], v[214:217], v[36:39]
	v_mfma_f32_16x16x32_bf16 v[32:35], v[118:121], v[214:217], v[32:35]
	s_barrier
; #define PG8_STAGE(bufoff, gbase, voff) do { _Pragma("unroll") for (int _i = 0; _i < 2; ++_i) \
;         __builtin_amdgcn_global_load_lds((const unsigned*)((const char*)(gbase) + (voff)[_i]), (PG8_LAS unsigned*)(lds + (bufoff) + ldsw + _i * 8192), 16, 0, 0); } while (0)
; #define PG8_LDA(dst, b, h) do { _Pragma("unroll") for (int m = 0; m < 4; ++m) _Pragma("unroll") for (int k = 0; k < 2; ++k) dst[m][k] = *(const PG8_LAS bf16x8*)(lds + PG8_SA(b, h) + aoff + m * 2048 + k * 1024); } while (0)
; #define PG8_MMA(ai, bj, At, Bt) do { __builtin_amdgcn_s_setprio(1); _Pragma("unroll") for (int m = 0; m < 4; ++m) _Pragma("unroll") for (int n = 0; n < 2; ++n) _Pragma("unroll") for (int k = 0; k < 2; ++k) \
;         acc[ai][bj][m][n] = __builtin_amdgcn_mfma_f32_16x16x32_bf16(Bt[n][k], At[m][k], acc[ai][bj][m][n], 0, 0, 0); __builtin_amdgcn_s_setprio(0); } while (0)
; #define PG8_WAIT_V(n) asm volatile("s_waitcnt vmcnt(" #n ")" ::: "memory")
; #define PG8_WAIT_L(n) asm volatile("s_waitcnt lgkmcnt(" #n ")" ::: "memory")
; #define PG8_BAR __builtin_amdgcn_s_barrier()
; #define PG8_SCHED __builtin_amdgcn_sched_barrier(0)
; template <class Epi, class Sched, bool ALIGN_EPI = false, bool SP2 = false>
; __device__ __forceinline__ void gemm_phase(PG8_LAS unsigned char* lds, const Gemm g, const Sched& S, const Epi& E, const int tid) {
;     ...
;             PG8_LDA(At, 1, 1); PG8_STAGE(PG8_SB(1, 0), b3, voffB); PG8_STAGE(PG8_SB(1, 1), b3 + hstep, voffB); PG8_STAGE(PG8_SA(1, 0), a3, voffA);
;             PG8_WAIT_V(8); PG8_WAIT_L(0); PG8_BAR; PG8_MMA(1, 0, At, B0); PG8_MMA(1, 1, At, B1); PG8_BAR; PG8_SCHED;
;     ...
;         if (!has_next) break;
; #pragma unroll
;         for (int a = 0; a < 2; ++a)
; #pragma unroll
;             for (int b = 0; b < 2; ++b)
; #pragma unroll
;                 for (int m = 0; m < 4; ++m)
; #pragma unroll
;                     for (int n = 0; n < 2; ++n) acc[a][b][m][n] = (f32x4){0.f, 0.f, 0.f, 0.f};
;         cur = nxt; cA = nA; cB = nB; ++ui;
	s_setprio 0
	s_add_i32 s22, s54, s30
	v_lshl_add_u64 v[130:131], v[202:203], 0, s[94:95]
	s_mov_b32 m0, s22
	ds_read_b128 v[122:125], v73 offset:49152
	ds_read_b128 v[126:129], v73 offset:50176
	ds_read_b128 v[194:197], v73 offset:51200
	ds_read_b128 v[198:201], v73 offset:52224
	ds_read_b128 v[206:209], v73 offset:53248
	ds_read_b128 v[214:217], v73 offset:54272
	ds_read_b128 v[218:221], v73 offset:55296
	ds_read_b128 v[222:225], v73 offset:56320
	global_load_lds_dwordx4 v[130:131], off
	s_add_i32 m0, s22, 0x2000
	s_add_u32 s20, s20, 0x40080
	v_lshl_add_u64 v[130:131], v[210:211], 0, s[94:95]
	s_addc_u32 s21, s21, 0
	s_add_i32 s22, s55, s30
	global_load_lds_dwordx4 v[130:131], off
	v_lshl_add_u64 v[130:131], s[20:21], 0, v[64:65]
	s_mov_b32 m0, s22
	s_nop 0
	global_load_lds_dwordx4 v[130:131], off
	v_lshl_add_u64 v[130:131], s[20:21], 0, v[52:53]
	s_add_i32 m0, s22, 0x2000
	s_nop 0
	global_load_lds_dwordx4 v[130:131], off
	v_lshl_add_u64 v[130:131], v[226:227], 0, s[94:95]
	s_mov_b32 m0, s45
	s_nop 0
	global_load_lds_dwordx4 v[130:131], off
	v_lshl_add_u64 v[130:131], v[228:229], 0, s[94:95]
	s_mov_b32 m0, s46
	s_nop 0
	global_load_lds_dwordx4 v[130:131], off
	s_waitcnt vmcnt(8) lgkmcnt(0)
	s_setprio 1
	s_barrier
	v_mfma_f32_16x16x32_bf16 v[130:133], v[82:85], v[122:125], v[158:161]
	v_mfma_f32_16x16x32_bf16 v[158:161], v[86:89], v[126:129], v[130:133]
	v_mfma_f32_16x16x32_bf16 v[130:133], v[90:93], v[122:125], v[154:157]
	v_mfma_f32_16x16x32_bf16 v[154:157], v[94:97], v[126:129], v[130:133]
	v_mfma_f32_16x16x32_bf16 v[130:133], v[82:85], v[194:197], v[150:153]
	v_mfma_f32_16x16x32_bf16 v[150:153], v[86:89], v[198:201], v[130:133]
	v_mfma_f32_16x16x32_bf16 v[130:133], v[90:93], v[194:197], v[146:149]
	v_mfma_f32_16x16x32_bf16 v[146:149], v[94:97], v[198:201], v[130:133]
	v_mfma_f32_16x16x32_bf16 v[130:133], v[82:85], v[206:209], v[142:145]
	v_mfma_f32_16x16x32_bf16 v[74:77], v[82:85], v[218:221], v[74:77]
	v_mfma_f32_16x16x32_bf16 v[142:145], v[86:89], v[214:217], v[130:133]
	v_mfma_f32_16x16x32_bf16 v[130:133], v[90:93], v[206:209], v[138:141]
	v_mfma_f32_16x16x32_bf16 v[134:137], v[86:89], v[222:225], v[74:77]
	v_mfma_f32_16x16x32_bf16 v[74:77], v[90:93], v[218:221], v[78:81]
	v_mfma_f32_16x16x32_bf16 v[138:141], v[94:97], v[214:217], v[130:133]
	v_mfma_f32_16x16x32_bf16 v[130:133], v[94:97], v[222:225], v[74:77]
	v_mfma_f32_16x16x32_bf16 v[28:31], v[106:109], v[122:125], v[28:31]
	v_mfma_f32_16x16x32_bf16 v[24:27], v[114:117], v[122:125], v[24:27]
	v_mfma_f32_16x16x32_bf16 v[20:23], v[106:109], v[194:197], v[20:23]
	v_mfma_f32_16x16x32_bf16 v[16:19], v[114:117], v[194:197], v[16:19]
	v_mfma_f32_16x16x32_bf16 v[12:15], v[106:109], v[206:209], v[12:15]
	v_mfma_f32_16x16x32_bf16 v[8:11], v[114:117], v[206:209], v[8:11]
	v_mfma_f32_16x16x32_bf16 v[4:7], v[106:109], v[218:221], v[4:7]
	v_mfma_f32_16x16x32_bf16 v[0:3], v[114:117], v[218:221], v[0:3]
	v_mfma_f32_16x16x32_bf16 v[28:31], v[110:113], v[126:129], v[28:31]
	v_mfma_f32_16x16x32_bf16 v[24:27], v[118:121], v[126:129], v[24:27]
	v_mfma_f32_16x16x32_bf16 v[20:23], v[110:113], v[198:201], v[20:23]
	v_mfma_f32_16x16x32_bf16 v[16:19], v[118:121], v[198:201], v[16:19]
	v_mfma_f32_16x16x32_bf16 v[12:15], v[110:113], v[214:217], v[12:15]
	v_mfma_f32_16x16x32_bf16 v[8:11], v[118:121], v[214:217], v[8:11]
	v_mfma_f32_16x16x32_bf16 v[4:7], v[110:113], v[222:225], v[4:7]
	v_mfma_f32_16x16x32_bf16 v[0:3], v[118:121], v[222:225], v[0:3]
	s_barrier
	s_setprio 0
	s_add_i32 s53, s53, 2
	s_add_u32 s18, s18, 0x100
	s_addc_u32 s19, s19, 0
	s_cmp_gt_u32 s53, 13
	s_cbranch_scc0 .LBB0_286
	s_add_u32 s18, s49, 0xffffff00
	s_addc_u32 s19, s50, -1
	s_andn2_b64 vcc, exec, s[2:3]
	s_cbranch_vccnz .LBB0_289
	v_mov_b32_e32 v0, 0
	s_mov_b32 s4, s10
	s_mov_b32 s24, s12
	s_mov_b64 s[8:9], s[16:17]
	s_mov_b32 s47, s48
	v_mov_b32_e32 v1, v0
	v_mov_b32_e32 v2, v0
	v_mov_b32_e32 v3, v0
	v_mov_b32_e32 v4, v0
	v_mov_b32_e32 v5, v0
	v_mov_b32_e32 v6, v0
	v_mov_b32_e32 v7, v0
	v_mov_b32_e32 v8, v0
	v_mov_b32_e32 v9, v0
	v_mov_b32_e32 v10, v0
	v_mov_b32_e32 v11, v0
	v_mov_b32_e32 v12, v0
	v_mov_b32_e32 v13, v0
	v_mov_b32_e32 v14, v0
	v_mov_b32_e32 v15, v0
	v_mov_b32_e32 v16, v0
	v_mov_b32_e32 v17, v0
	v_mov_b32_e32 v18, v0
	v_mov_b32_e32 v19, v0
	v_mov_b32_e32 v20, v0
	v_mov_b32_e32 v21, v0
	v_mov_b32_e32 v22, v0
	v_mov_b32_e32 v23, v0
	v_mov_b32_e32 v24, v0
	v_mov_b32_e32 v25, v0
	v_mov_b32_e32 v26, v0
	v_mov_b32_e32 v27, v0
	v_mov_b32_e32 v28, v0
	v_mov_b32_e32 v29, v0
	v_mov_b32_e32 v30, v0
	v_mov_b32_e32 v31, v0
	v_mov_b32_e32 v130, v0
	v_mov_b32_e32 v131, v0
	v_mov_b32_e32 v132, v0
	v_mov_b32_e32 v133, v0
	v_mov_b32_e32 v134, v0
	v_mov_b32_e32 v135, v0
	v_mov_b32_e32 v136, v0
	v_mov_b32_e32 v137, v0
	v_mov_b32_e32 v138, v0
	v_mov_b32_e32 v139, v0
	v_mov_b32_e32 v140, v0
	v_mov_b32_e32 v141, v0
	v_mov_b32_e32 v142, v0
	v_mov_b32_e32 v143, v0
	v_mov_b32_e32 v144, v0
	v_mov_b32_e32 v145, v0
	v_mov_b32_e32 v146, v0
	v_mov_b32_e32 v147, v0
	v_mov_b32_e32 v148, v0
	v_mov_b32_e32 v149, v0
	v_mov_b32_e32 v150, v0
	v_mov_b32_e32 v151, v0
	v_mov_b32_e32 v152, v0
	v_mov_b32_e32 v153, v0
	v_mov_b32_e32 v154, v0
	v_mov_b32_e32 v155, v0
	v_mov_b32_e32 v156, v0
	v_mov_b32_e32 v157, v0
	v_mov_b32_e32 v158, v0
	v_mov_b32_e32 v159, v0
	v_mov_b32_e32 v160, v0
	v_mov_b32_e32 v161, v0
	v_mov_b32_e32 v32, v0
	v_mov_b32_e32 v33, v0
	v_mov_b32_e32 v34, v0
	v_mov_b32_e32 v35, v0
	v_mov_b32_e32 v36, v0
	v_mov_b32_e32 v37, v0
	v_mov_b32_e32 v38, v0
	v_mov_b32_e32 v39, v0
	v_mov_b32_e32 v40, v0
	v_mov_b32_e32 v41, v0
	v_mov_b32_e32 v42, v0
	v_mov_b32_e32 v43, v0
	v_mov_b32_e32 v44, v0
	v_mov_b32_e32 v45, v0
	v_mov_b32_e32 v46, v0
	v_mov_b32_e32 v47, v0
	v_mov_b32_e32 v48, v0
	v_mov_b32_e32 v49, v0
	v_mov_b32_e32 v50, v0
	v_mov_b32_e32 v51, v0
	v_mov_b32_e32 v56, v0
	v_mov_b32_e32 v57, v0
	v_mov_b32_e32 v58, v0
	v_mov_b32_e32 v59, v0
	v_mov_b32_e32 v98, v0
	v_mov_b32_e32 v99, v0
	v_mov_b32_e32 v100, v0
	v_mov_b32_e32 v101, v0
	v_mov_b32_e32 v102, v0
	v_mov_b32_e32 v103, v0
	v_mov_b32_e32 v104, v0
	v_mov_b32_e32 v105, v0
	v_mov_b32_e32 v162, v0
	v_mov_b32_e32 v163, v0
	v_mov_b32_e32 v164, v0
	v_mov_b32_e32 v165, v0
	v_mov_b32_e32 v166, v0
	v_mov_b32_e32 v167, v0
	v_mov_b32_e32 v168, v0
	v_mov_b32_e32 v169, v0
	v_mov_b32_e32 v170, v0
	v_mov_b32_e32 v171, v0
	v_mov_b32_e32 v172, v0
	v_mov_b32_e32 v173, v0
	v_mov_b32_e32 v174, v0
	v_mov_b32_e32 v175, v0
	v_mov_b32_e32 v176, v0
	v_mov_b32_e32 v177, v0
	v_mov_b32_e32 v178, v0
	v_mov_b32_e32 v179, v0
	v_mov_b32_e32 v180, v0
	v_mov_b32_e32 v181, v0
	v_mov_b32_e32 v182, v0
	v_mov_b32_e32 v183, v0
	v_mov_b32_e32 v184, v0
	v_mov_b32_e32 v185, v0
	v_mov_b32_e32 v186, v0
	v_mov_b32_e32 v187, v0
	v_mov_b32_e32 v188, v0
	v_mov_b32_e32 v189, v0
	v_mov_b32_e32 v190, v0
	v_mov_b32_e32 v191, v0
	v_mov_b32_e32 v192, v0
	v_mov_b32_e32 v193, v0
	s_andn2_b64 vcc, exec, s[0:1]
	s_cbranch_vccnz .LBB0_290
	s_branch .LBB0_291

; #define PG8_STAGE(bufoff, gbase, voff) do { _Pragma("unroll") for (int _i = 0; _i < 2; ++_i) \
;         __builtin_amdgcn_global_load_lds((const unsigned*)((const char*)(gbase) + (voff)[_i]), (PG8_LAS unsigned*)(lds + (bufoff) + ldsw + _i * 8192), 16, 0, 0); } while (0)
; #define PG8_LDA(dst, b, h) do { _Pragma("unroll") for (int m = 0; m < 4; ++m) _Pragma("unroll") for (int k = 0; k < 2; ++k) dst[m][k] = *(const PG8_LAS bf16x8*)(lds + PG8_SA(b, h) + aoff + m * 2048 + k * 1024); } while (0)
; #define PG8_LDB(dst, b, h) do { _Pragma("unroll") for (int n = 0; n < 2; ++n) _Pragma("unroll") for (int k = 0; k < 2; ++k) dst[n][k] = *(const PG8_LAS bf16x8*)(lds + PG8_SB(b, h) + boff + n * 2048 + k * 1024); } while (0)
; #define PG8_MMA(ai, bj, At, Bt) do { __builtin_amdgcn_s_setprio(1); _Pragma("unroll") for (int m = 0; m < 4; ++m) _Pragma("unroll") for (int n = 0; n < 2; ++n) _Pragma("unroll") for (int k = 0; k < 2; ++k) \
;         acc[ai][bj][m][n] = __builtin_amdgcn_mfma_f32_16x16x32_bf16(Bt[n][k], At[m][k], acc[ai][bj][m][n], 0, 0, 0); __builtin_amdgcn_s_setprio(0); } while (0)
; #define PG8_WAIT_V(n) asm volatile("s_waitcnt vmcnt(" #n ")" ::: "memory")
; #define PG8_WAIT_L(n) asm volatile("s_waitcnt lgkmcnt(" #n ")" ::: "memory")
; #define PG8_BAR __builtin_amdgcn_s_barrier()
; #define PG8_SCHED __builtin_amdgcn_sched_barrier(0)
; template <class Epi, class Sched, bool ALIGN_EPI = false, bool SP2 = false>
; __device__ __forceinline__ void gemm_phase(PG8_LAS unsigned char* lds, const Gemm g, const Sched& S, const Epi& E, const int tid) {
;     ...
;             PG8_LDB(B0, 0, 0); PG8_LDB(B1, 0, 1); PG8_SCHED; PG8_LDA(At, 0, 0); PG8_STAGE(PG8_SA(1, 1), a1 + hstep, voffA);
;             PG8_WAIT_V(8); PG8_WAIT_L(0); PG8_BAR; PG8_MMA(0, 0, At, B0); PG8_MMA(0, 1, At, B1); PG8_BAR; PG8_SCHED;
;             PG8_LDA(At, 0, 1); PG8_STAGE(PG8_SB(0, 0), b2, voffB); PG8_STAGE(PG8_SB(0, 1), b2 + hstep, voffB); PG8_STAGE(PG8_SA(0, 0), a2, voffA);
;             PG8_WAIT_V(8); PG8_WAIT_L(0); PG8_BAR; PG8_MMA(1, 0, At, B0); PG8_MMA(1, 1, At, B1); PG8_BAR; PG8_SCHED;
.LBB0_348:
	s_add_i32 s47, 0, 0x10000
	s_add_i32 s45, 0, 0x14000
	v_add_u32_e32 v8, s47, v141
	v_add_u32_e32 v9, s45, v141
	ds_read_b128 v[10:13], v8
	ds_read_b128 v[14:17], v8 offset:1024
	ds_read_b128 v[18:21], v8 offset:2048
	ds_read_b128 v[22:25], v8 offset:3072
	ds_read_b128 v[26:29], v9
	ds_read_b128 v[30:33], v9 offset:1024
	ds_read_b128 v[34:37], v9 offset:2048
	ds_read_b128 v[38:41], v9 offset:3072
	s_add_u32 s2, s14, 0x18080
	s_addc_u32 s3, s15, 0
	s_add_i32 s50, s23, 0xc000
	v_lshl_add_u64 v[62:63], s[2:3], 0, v[136:137]
	s_mov_b32 m0, s50
	ds_read_b128 v[0:3], v142
	ds_read_b128 v[4:7], v142 offset:1024
	ds_read_b128 v[42:45], v142 offset:2048
	ds_read_b128 v[46:49], v142 offset:3072
	ds_read_b128 v[50:53], v142 offset:4096
	ds_read_b128 v[54:57], v142 offset:5120
	ds_read_b128 v[58:61], v142 offset:6144
	ds_read_b128 v[66:69], v142 offset:7168
	global_load_lds_dwordx4 v[62:63], off
	v_lshl_add_u64 v[62:63], s[2:3], 0, v[132:133]
	s_add_i32 s2, s23, 0xe000
	s_mov_b32 m0, s2
	s_nop 0
	global_load_lds_dwordx4 v[62:63], off
	s_waitcnt vmcnt(8) lgkmcnt(0)
	s_setprio 1
	s_barrier
	v_mfma_f32_16x16x32_bf16 v[70:73], v[10:13], v[0:3], 0
	v_mfma_f32_16x16x32_bf16 v[74:77], v[18:21], v[0:3], 0
	v_mfma_f32_16x16x32_bf16 v[78:81], v[10:13], v[42:45], 0
	v_mfma_f32_16x16x32_bf16 v[82:85], v[18:21], v[42:45], 0
	v_mfma_f32_16x16x32_bf16 v[86:89], v[10:13], v[50:53], 0
	v_mfma_f32_16x16x32_bf16 v[90:93], v[18:21], v[50:53], 0
	v_mfma_f32_16x16x32_bf16 v[94:97], v[10:13], v[58:61], 0
	v_mfma_f32_16x16x32_bf16 v[98:101], v[18:21], v[58:61], 0
	v_mfma_f32_16x16x32_bf16 v[70:73], v[14:17], v[4:7], v[70:73]
	v_mfma_f32_16x16x32_bf16 v[74:77], v[22:25], v[4:7], v[74:77]
	v_mfma_f32_16x16x32_bf16 v[78:81], v[14:17], v[46:49], v[78:81]
	v_mfma_f32_16x16x32_bf16 v[82:85], v[22:25], v[46:49], v[82:85]
	v_mfma_f32_16x16x32_bf16 v[86:89], v[14:17], v[54:57], v[86:89]
	v_mfma_f32_16x16x32_bf16 v[90:93], v[22:25], v[54:57], v[90:93]
	v_mfma_f32_16x16x32_bf16 v[94:97], v[14:17], v[66:69], v[94:97]
	v_mfma_f32_16x16x32_bf16 v[98:101], v[22:25], v[66:69], v[98:101]
	v_mfma_f32_16x16x32_bf16 v[102:105], v[26:29], v[0:3], 0
	v_mfma_f32_16x16x32_bf16 v[0:3], v[34:37], v[0:3], 0
	v_mfma_f32_16x16x32_bf16 v[106:109], v[38:41], v[4:7], v[0:3]
	v_mfma_f32_16x16x32_bf16 v[0:3], v[26:29], v[42:45], 0
	v_mfma_f32_16x16x32_bf16 v[110:113], v[30:33], v[46:49], v[0:3]
	v_mfma_f32_16x16x32_bf16 v[0:3], v[34:37], v[42:45], 0
	v_mfma_f32_16x16x32_bf16 v[42:45], v[38:41], v[46:49], v[0:3]
	v_mfma_f32_16x16x32_bf16 v[0:3], v[26:29], v[50:53], 0
	v_mfma_f32_16x16x32_bf16 v[46:49], v[30:33], v[54:57], v[0:3]
	v_mfma_f32_16x16x32_bf16 v[0:3], v[34:37], v[50:53], 0
	v_mfma_f32_16x16x32_bf16 v[50:53], v[38:41], v[54:57], v[0:3]
	v_mfma_f32_16x16x32_bf16 v[0:3], v[26:29], v[58:61], 0
	v_mfma_f32_16x16x32_bf16 v[54:57], v[30:33], v[66:69], v[0:3]
	v_mfma_f32_16x16x32_bf16 v[0:3], v[34:37], v[58:61], 0
	v_mfma_f32_16x16x32_bf16 v[102:105], v[30:33], v[4:7], v[102:105]
	v_mfma_f32_16x16x32_bf16 v[58:61], v[38:41], v[66:69], v[0:3]
	s_barrier
	s_setprio 0
	s_nop 3
	v_lshl_add_u64 v[0:1], s[16:17], 0, v[134:135]
	s_mov_b64 s[52:53], 0x100
	s_add_i32 s47, s47, s22
	v_lshl_add_u64 v[2:3], v[0:1], 0, s[52:53]
	s_mov_b32 m0, s47
	s_add_i32 s3, s47, 0x2000
	ds_read_b128 v[66:69], v142 offset:16384
	ds_read_b128 v[114:117], v142 offset:17408
	ds_read_b128 v[118:121], v142 offset:18432
	ds_read_b128 v[122:125], v142 offset:19456
	ds_read_b128 v[126:129], v142 offset:20480
	ds_read_b128 v[144:147], v142 offset:21504
	ds_read_b128 v[148:151], v142 offset:22528
	ds_read_b128 v[152:155], v142 offset:23552
	global_load_lds_dwordx4 v[2:3], off
	v_lshl_add_u64 v[2:3], s[16:17], 0, v[130:131]
	s_add_u32 s48, s16, 0x18100
	v_lshl_add_u64 v[4:5], v[2:3], 0, s[52:53]
	s_mov_b32 m0, s3
	s_addc_u32 s49, s17, 0
	s_add_i32 s45, s45, s22
	global_load_lds_dwordx4 v[4:5], off
	v_lshl_add_u64 v[4:5], s[48:49], 0, v[134:135]
	s_mov_b32 m0, s45
	s_add_i32 s46, s45, 0x2000
	global_load_lds_dwordx4 v[4:5], off
	v_lshl_add_u64 v[4:5], s[48:49], 0, v[130:131]
	s_mov_b32 m0, s46
	s_nop 0
	global_load_lds_dwordx4 v[4:5], off
	v_lshl_add_u64 v[4:5], s[14:15], 0, v[136:137]
	v_lshl_add_u64 v[6:7], v[4:5], 0, s[52:53]
	s_mov_b32 m0, s23
	s_nop 0
	global_load_lds_dwordx4 v[6:7], off
	v_lshl_add_u64 v[6:7], s[14:15], 0, v[132:133]
	v_lshl_add_u64 v[62:63], v[6:7], 0, s[52:53]
	s_mov_b32 m0, s24
	s_nop 0
	global_load_lds_dwordx4 v[62:63], off
	s_waitcnt vmcnt(8) lgkmcnt(0)
	s_setprio 1
	s_barrier
	v_mfma_f32_16x16x32_bf16 v[156:159], v[10:13], v[66:69], 0
	v_mfma_f32_16x16x32_bf16 v[164:167], v[10:13], v[118:121], 0
	v_mfma_f32_16x16x32_bf16 v[172:175], v[10:13], v[126:129], 0
	v_mfma_f32_16x16x32_bf16 v[10:13], v[10:13], v[148:151], 0
	v_mfma_f32_16x16x32_bf16 v[156:159], v[14:17], v[114:117], v[156:159]
	v_mfma_f32_16x16x32_bf16 v[160:163], v[18:21], v[66:69], 0
	v_mfma_f32_16x16x32_bf16 v[164:167], v[14:17], v[122:125], v[164:167]
	v_mfma_f32_16x16x32_bf16 v[168:171], v[18:21], v[118:121], 0
	v_mfma_f32_16x16x32_bf16 v[172:175], v[14:17], v[144:147], v[172:175]
	v_mfma_f32_16x16x32_bf16 v[176:179], v[18:21], v[126:129], 0
	v_mfma_f32_16x16x32_bf16 v[12:15], v[14:17], v[152:155], v[10:13]
	v_mfma_f32_16x16x32_bf16 v[16:19], v[18:21], v[148:151], 0
	v_mfma_f32_16x16x32_bf16 v[16:19], v[22:25], v[152:155], v[16:19]
	v_mfma_f32_16x16x32_bf16 v[160:163], v[22:25], v[114:117], v[160:163]
	v_mfma_f32_16x16x32_bf16 v[168:171], v[22:25], v[122:125], v[168:171]
	v_mfma_f32_16x16x32_bf16 v[176:179], v[22:25], v[144:147], v[176:179]
	v_mfma_f32_16x16x32_bf16 v[20:23], v[26:29], v[66:69], 0
	v_mfma_f32_16x16x32_bf16 v[66:69], v[34:37], v[66:69], 0
	v_mfma_f32_16x16x32_bf16 v[20:23], v[30:33], v[114:117], v[20:23]
	v_mfma_f32_16x16x32_bf16 v[66:69], v[38:41], v[114:117], v[66:69]
	v_mfma_f32_16x16x32_bf16 v[114:117], v[26:29], v[118:121], 0
	v_mfma_f32_16x16x32_bf16 v[118:121], v[34:37], v[118:121], 0
	v_mfma_f32_16x16x32_bf16 v[114:117], v[30:33], v[122:125], v[114:117]
	v_mfma_f32_16x16x32_bf16 v[118:121], v[38:41], v[122:125], v[118:121]
	v_mfma_f32_16x16x32_bf16 v[122:125], v[26:29], v[126:129], 0
	v_mfma_f32_16x16x32_bf16 v[24:27], v[26:29], v[148:151], 0
	v_mfma_f32_16x16x32_bf16 v[122:125], v[30:33], v[144:147], v[122:125]
	v_mfma_f32_16x16x32_bf16 v[126:129], v[34:37], v[126:129], 0
	v_mfma_f32_16x16x32_bf16 v[24:27], v[30:33], v[152:155], v[24:27]
	v_mfma_f32_16x16x32_bf16 v[28:31], v[34:37], v[148:151], 0
	v_mfma_f32_16x16x32_bf16 v[126:129], v[38:41], v[144:147], v[126:129]
	v_mfma_f32_16x16x32_bf16 v[28:31], v[38:41], v[152:155], v[28:31]
	s_barrier
; #define PG8_STAGE(bufoff, gbase, voff) do { _Pragma("unroll") for (int _i = 0; _i < 2; ++_i) \
;         __builtin_amdgcn_global_load_lds((const unsigned*)((const char*)(gbase) + (voff)[_i]), (PG8_LAS unsigned*)(lds + (bufoff) + ldsw + _i * 8192), 16, 0, 0); } while (0)
; #define PG8_LDA(dst, b, h) do { _Pragma("unroll") for (int m = 0; m < 4; ++m) _Pragma("unroll") for (int k = 0; k < 2; ++k) dst[m][k] = *(const PG8_LAS bf16x8*)(lds + PG8_SA(b, h) + aoff + m * 2048 + k * 1024); } while (0)
; #define PG8_LDB(dst, b, h) do { _Pragma("unroll") for (int n = 0; n < 2; ++n) _Pragma("unroll") for (int k = 0; k < 2; ++k) dst[n][k] = *(const PG8_LAS bf16x8*)(lds + PG8_SB(b, h) + boff + n * 2048 + k * 1024); } while (0)
; #define PG8_MMA(ai, bj, At, Bt) do { __builtin_amdgcn_s_setprio(1); _Pragma("unroll") for (int m = 0; m < 4; ++m) _Pragma("unroll") for (int n = 0; n < 2; ++n) _Pragma("unroll") for (int k = 0; k < 2; ++k) \
;         acc[ai][bj][m][n] = __builtin_amdgcn_mfma_f32_16x16x32_bf16(Bt[n][k], At[m][k], acc[ai][bj][m][n], 0, 0, 0); __builtin_amdgcn_s_setprio(0); } while (0)
; #define PG8_WAIT_V(n) asm volatile("s_waitcnt vmcnt(" #n ")" ::: "memory")
; #define PG8_WAIT_L(n) asm volatile("s_waitcnt lgkmcnt(" #n ")" ::: "memory")
; #define PG8_BAR __builtin_amdgcn_s_barrier()
; #define PG8_SCHED __builtin_amdgcn_sched_barrier(0)
; template <class Epi, class Sched, bool ALIGN_EPI = false, bool SP2 = false>
; __device__ __forceinline__ void gemm_phase(PG8_LAS unsigned char* lds, const Gemm g, const Sched& S, const Epi& E, const int tid) {
;     ...
;             PG8_LDB(B0, 1, 0); PG8_LDB(B1, 1, 1); PG8_SCHED; PG8_LDA(At, 1, 0); PG8_STAGE(PG8_SA(0, 1), a2 + hstep, voffA);
;             PG8_WAIT_V(8); PG8_WAIT_L(0); PG8_BAR; PG8_MMA(0, 0, At, B0); PG8_MMA(0, 1, At, B1); PG8_BAR; PG8_SCHED;
;             PG8_LDA(At, 1, 1); PG8_STAGE(PG8_SB(1, 0), b3, voffB); PG8_STAGE(PG8_SB(1, 1), b3 + hstep, voffB); PG8_STAGE(PG8_SA(1, 0), a3, voffA);
;             PG8_WAIT_V(8); PG8_WAIT_L(0); PG8_BAR; PG8_MMA(1, 0, At, B0); PG8_MMA(1, 1, At, B1); PG8_BAR; PG8_SCHED;
	s_setprio 0
	s_add_i32 s52, 0, 0x18000
	s_add_i32 s51, 0, 0x1c000
	v_add_u32_e32 v10, s52, v141
	v_add_u32_e32 v11, s51, v141
	ds_read_b128 v[32:35], v10
	ds_read_b128 v[36:39], v10 offset:1024
	ds_read_b128 v[144:147], v10 offset:2048
	ds_read_b128 v[148:151], v10 offset:3072
	ds_read_b128 v[152:155], v11
	ds_read_b128 v[180:183], v11 offset:1024
	ds_read_b128 v[184:187], v11 offset:2048
	ds_read_b128 v[188:191], v11 offset:3072
	s_add_u32 s48, s14, 0x18100
	s_addc_u32 s49, s15, 0
	s_mov_b32 m0, s25
	v_lshl_add_u64 v[40:41], s[48:49], 0, v[136:137]
	ds_read_b128 v[192:195], v142 offset:32768
	ds_read_b128 v[196:199], v142 offset:33792
	ds_read_b128 v[214:217], v142 offset:34816
	ds_read_b128 v[218:221], v142 offset:35840
	ds_read_b128 v[222:225], v142 offset:36864
	ds_read_b128 v[226:229], v142 offset:37888
	ds_read_b128 v[248:251], v142 offset:38912
	ds_read_b128 v[206:209], v142 offset:39936
	global_load_lds_dwordx4 v[40:41], off
	v_lshl_add_u64 v[40:41], s[48:49], 0, v[132:133]
	s_mov_b32 m0, s26
	s_nop 0
	global_load_lds_dwordx4 v[40:41], off
	s_waitcnt vmcnt(8) lgkmcnt(0)
	s_setprio 1
	s_barrier
	v_mfma_f32_16x16x32_bf16 v[70:73], v[32:35], v[192:195], v[70:73]
	v_mfma_f32_16x16x32_bf16 v[74:77], v[144:147], v[192:195], v[74:77]
	v_mfma_f32_16x16x32_bf16 v[78:81], v[32:35], v[214:217], v[78:81]
	v_mfma_f32_16x16x32_bf16 v[82:85], v[144:147], v[214:217], v[82:85]
	v_mfma_f32_16x16x32_bf16 v[86:89], v[32:35], v[222:225], v[86:89]
	v_mfma_f32_16x16x32_bf16 v[90:93], v[144:147], v[222:225], v[90:93]
	v_mfma_f32_16x16x32_bf16 v[94:97], v[32:35], v[248:251], v[94:97]
	v_mfma_f32_16x16x32_bf16 v[98:101], v[144:147], v[248:251], v[98:101]
	v_mfma_f32_16x16x32_bf16 v[70:73], v[36:39], v[196:199], v[70:73]
	v_mfma_f32_16x16x32_bf16 v[74:77], v[148:151], v[196:199], v[74:77]
	v_mfma_f32_16x16x32_bf16 v[78:81], v[36:39], v[218:221], v[78:81]
	v_mfma_f32_16x16x32_bf16 v[82:85], v[148:151], v[218:221], v[82:85]
	v_mfma_f32_16x16x32_bf16 v[86:89], v[36:39], v[226:229], v[86:89]
	v_mfma_f32_16x16x32_bf16 v[90:93], v[148:151], v[226:229], v[90:93]
	v_mfma_f32_16x16x32_bf16 v[94:97], v[36:39], v[206:209], v[94:97]
	v_mfma_f32_16x16x32_bf16 v[98:101], v[148:151], v[206:209], v[98:101]
	v_mfma_f32_16x16x32_bf16 v[102:105], v[152:155], v[192:195], v[102:105]
	v_mfma_f32_16x16x32_bf16 v[106:109], v[184:187], v[192:195], v[106:109]
	v_mfma_f32_16x16x32_bf16 v[110:113], v[152:155], v[214:217], v[110:113]
	v_mfma_f32_16x16x32_bf16 v[40:43], v[184:187], v[214:217], v[42:45]
	v_mfma_f32_16x16x32_bf16 v[44:47], v[152:155], v[222:225], v[46:49]
	v_mfma_f32_16x16x32_bf16 v[48:51], v[184:187], v[222:225], v[50:53]
	v_mfma_f32_16x16x32_bf16 v[52:55], v[152:155], v[248:251], v[54:57]
	v_mfma_f32_16x16x32_bf16 v[56:59], v[184:187], v[248:251], v[58:61]
	v_mfma_f32_16x16x32_bf16 v[102:105], v[180:183], v[196:199], v[102:105]
	v_mfma_f32_16x16x32_bf16 v[106:109], v[188:191], v[196:199], v[106:109]
	v_mfma_f32_16x16x32_bf16 v[110:113], v[180:183], v[218:221], v[110:113]
	v_mfma_f32_16x16x32_bf16 v[40:43], v[188:191], v[218:221], v[40:43]
	v_mfma_f32_16x16x32_bf16 v[44:47], v[180:183], v[226:229], v[44:47]
	v_mfma_f32_16x16x32_bf16 v[48:51], v[188:191], v[226:229], v[48:51]
	v_mfma_f32_16x16x32_bf16 v[52:55], v[180:183], v[206:209], v[52:55]
	v_mfma_f32_16x16x32_bf16 v[56:59], v[188:191], v[206:209], v[56:59]
	s_barrier
	s_setprio 0
	s_add_i32 s52, s52, s22
	s_mov_b64 s[56:57], 0x180
	s_add_i32 s48, s52, 0x2000
	v_lshl_add_u64 v[138:139], v[0:1], 0, s[56:57]
	s_mov_b32 m0, s52
	s_add_u32 s54, s16, 0x18180
	ds_read_b128 v[60:63], v142 offset:49152
	ds_read_b128 v[192:195], v142 offset:50176
	ds_read_b128 v[196:199], v142 offset:51200
	ds_read_b128 v[206:209], v142 offset:52224
	ds_read_b128 v[214:217], v142 offset:53248
	ds_read_b128 v[218:221], v142 offset:54272
	ds_read_b128 v[222:225], v142 offset:55296
	ds_read_b128 v[226:229], v142 offset:56320
	global_load_lds_dwordx4 v[138:139], off
	v_lshl_add_u64 v[138:139], v[2:3], 0, s[56:57]
	s_mov_b32 m0, s48
	s_addc_u32 s55, s17, 0
	s_add_i32 s49, s51, s22
	global_load_lds_dwordx4 v[138:139], off
	v_lshl_add_u64 v[138:139], s[54:55], 0, v[134:135]
	s_mov_b32 m0, s49
	s_add_i32 s51, s49, 0x2000
	global_load_lds_dwordx4 v[138:139], off
	v_lshl_add_u64 v[138:139], s[54:55], 0, v[130:131]
	s_mov_b32 m0, s51
	s_nop 0
	global_load_lds_dwordx4 v[138:139], off
	v_lshl_add_u64 v[138:139], v[4:5], 0, s[56:57]
	s_mov_b32 m0, s28
	s_nop 0
	global_load_lds_dwordx4 v[138:139], off
	v_lshl_add_u64 v[138:139], v[6:7], 0, s[56:57]
	s_mov_b32 m0, s29
	s_nop 0
	global_load_lds_dwordx4 v[138:139], off
	s_waitcnt vmcnt(8) lgkmcnt(0)
	s_setprio 1
	s_barrier
; #define PG8_STAGE(bufoff, gbase, voff) do { _Pragma("unroll") for (int _i = 0; _i < 2; ++_i) \
;         __builtin_amdgcn_global_load_lds((const unsigned*)((const char*)(gbase) + (voff)[_i]), (PG8_LAS unsigned*)(lds + (bufoff) + ldsw + _i * 8192), 16, 0, 0); } while (0)
; #define PG8_LDA(dst, b, h) do { _Pragma("unroll") for (int m = 0; m < 4; ++m) _Pragma("unroll") for (int k = 0; k < 2; ++k) dst[m][k] = *(const PG8_LAS bf16x8*)(lds + PG8_SA(b, h) + aoff + m * 2048 + k * 1024); } while (0)
; #define PG8_LDB(dst, b, h) do { _Pragma("unroll") for (int n = 0; n < 2; ++n) _Pragma("unroll") for (int k = 0; k < 2; ++k) dst[n][k] = *(const PG8_LAS bf16x8*)(lds + PG8_SB(b, h) + boff + n * 2048 + k * 1024); } while (0)
; #define PG8_MMA(ai, bj, At, Bt) do { __builtin_amdgcn_s_setprio(1); _Pragma("unroll") for (int m = 0; m < 4; ++m) _Pragma("unroll") for (int n = 0; n < 2; ++n) _Pragma("unroll") for (int k = 0; k < 2; ++k) \
;         acc[ai][bj][m][n] = __builtin_amdgcn_mfma_f32_16x16x32_bf16(Bt[n][k], At[m][k], acc[ai][bj][m][n], 0, 0, 0); __builtin_amdgcn_s_setprio(0); } while (0)
; #define PG8_BAR __builtin_amdgcn_s_barrier()
; template <class Epi, class Sched, bool ALIGN_EPI = false, bool SP2 = false>
; __device__ __forceinline__ void gemm_phase(PG8_LAS unsigned char* lds, const Gemm g, const Sched& S, const Epi& E, const int tid) {
;     ...
;             PG8_LDB(B0, 0, 0); PG8_LDB(B1, 0, 1); PG8_SCHED; PG8_LDA(At, 0, 0); PG8_STAGE(PG8_SA(1, 1), a1 + hstep, voffA);
;             PG8_WAIT_V(8); PG8_WAIT_L(0); PG8_BAR; PG8_MMA(0, 0, At, B0); PG8_MMA(0, 1, At, B1); PG8_BAR; PG8_SCHED;
;             PG8_LDA(At, 0, 1); PG8_STAGE(PG8_SB(0, 0), b2, voffB); PG8_STAGE(PG8_SB(0, 1), b2 + hstep, voffB); PG8_STAGE(PG8_SA(0, 0), a2, voffA);
;             PG8_WAIT_V(8); PG8_WAIT_L(0); PG8_BAR; PG8_MMA(1, 0, At, B0); PG8_MMA(1, 1, At, B1); PG8_BAR; PG8_SCHED;
;             PG8_LDB(B0, 1, 0); PG8_LDB(B1, 1, 1); PG8_SCHED; PG8_LDA(At, 1, 0); PG8_STAGE(PG8_SA(0, 1), a2 + hstep, voffA);
;             PG8_WAIT_V(8); PG8_WAIT_L(0); PG8_BAR; PG8_MMA(0, 0, At, B0); PG8_MMA(0, 1, At, B1); PG8_BAR; PG8_SCHED;
;             PG8_LDA(At, 1, 1); PG8_STAGE(PG8_SB(1, 0), b3, voffB); PG8_STAGE(PG8_SB(1, 1), b3 + hstep, voffB); PG8_STAGE(PG8_SA(1, 0), a3, voffA);
;             PG8_WAIT_V(8); PG8_WAIT_L(0); PG8_BAR; PG8_MMA(1, 0, At, B0); PG8_MMA(1, 1, At, B1); PG8_BAR; PG8_SCHED;
	v_mfma_f32_16x16x32_bf16 v[12:15], v[32:35], v[222:225], v[12:15]
	v_mfma_f32_16x16x32_bf16 v[16:19], v[144:147], v[222:225], v[16:19]
	v_mfma_f32_16x16x32_bf16 v[156:159], v[32:35], v[60:63], v[156:159]
	v_mfma_f32_16x16x32_bf16 v[160:163], v[144:147], v[60:63], v[160:163]
	v_mfma_f32_16x16x32_bf16 v[164:167], v[32:35], v[196:199], v[164:167]
	v_mfma_f32_16x16x32_bf16 v[168:171], v[144:147], v[196:199], v[168:171]
	v_mfma_f32_16x16x32_bf16 v[172:175], v[32:35], v[214:217], v[172:175]
	v_mfma_f32_16x16x32_bf16 v[176:179], v[144:147], v[214:217], v[176:179]
	v_mfma_f32_16x16x32_bf16 v[12:15], v[36:39], v[226:229], v[12:15]
	v_mfma_f32_16x16x32_bf16 v[16:19], v[148:151], v[226:229], v[16:19]
	v_mfma_f32_16x16x32_bf16 v[156:159], v[36:39], v[192:195], v[156:159]
	v_mfma_f32_16x16x32_bf16 v[160:163], v[148:151], v[192:195], v[160:163]
	v_mfma_f32_16x16x32_bf16 v[164:167], v[36:39], v[206:209], v[164:167]
	v_mfma_f32_16x16x32_bf16 v[168:171], v[148:151], v[206:209], v[168:171]
	v_mfma_f32_16x16x32_bf16 v[172:175], v[36:39], v[218:221], v[172:175]
	v_mfma_f32_16x16x32_bf16 v[176:179], v[148:151], v[218:221], v[176:179]
	v_mfma_f32_16x16x32_bf16 v[20:23], v[152:155], v[60:63], v[20:23]
	v_mfma_f32_16x16x32_bf16 v[32:35], v[184:187], v[60:63], v[66:69]
	v_mfma_f32_16x16x32_bf16 v[36:39], v[152:155], v[196:199], v[114:117]
	v_mfma_f32_16x16x32_bf16 v[60:63], v[184:187], v[196:199], v[118:121]
	v_mfma_f32_16x16x32_bf16 v[66:69], v[152:155], v[214:217], v[122:125]
	v_mfma_f32_16x16x32_bf16 v[114:117], v[184:187], v[214:217], v[126:129]
	v_mfma_f32_16x16x32_bf16 v[24:27], v[152:155], v[222:225], v[24:27]
	v_mfma_f32_16x16x32_bf16 v[28:31], v[184:187], v[222:225], v[28:31]
	v_mfma_f32_16x16x32_bf16 v[20:23], v[180:183], v[192:195], v[20:23]
	v_mfma_f32_16x16x32_bf16 v[32:35], v[188:191], v[192:195], v[32:35]
	v_mfma_f32_16x16x32_bf16 v[36:39], v[180:183], v[206:209], v[36:39]
	v_mfma_f32_16x16x32_bf16 v[60:63], v[188:191], v[206:209], v[60:63]
	v_mfma_f32_16x16x32_bf16 v[66:69], v[180:183], v[218:221], v[66:69]
	v_mfma_f32_16x16x32_bf16 v[114:117], v[188:191], v[218:221], v[114:117]
	v_mfma_f32_16x16x32_bf16 v[24:27], v[180:183], v[226:229], v[24:27]
	v_mfma_f32_16x16x32_bf16 v[28:31], v[188:191], v[226:229], v[28:31]
	s_barrier
	s_setprio 0
	ds_read_b128 v[118:121], v8
	ds_read_b128 v[122:125], v8 offset:1024
	ds_read_b128 v[126:129], v8 offset:2048
	ds_read_b128 v[144:147], v8 offset:3072
	ds_read_b128 v[148:151], v9
	ds_read_b128 v[152:155], v9 offset:1024
	ds_read_b128 v[180:183], v9 offset:2048
	ds_read_b128 v[184:187], v9 offset:3072
	s_add_u32 s54, s14, 0x18180
	s_addc_u32 s55, s15, 0
	s_mov_b32 m0, s50
	v_lshl_add_u64 v[138:139], s[54:55], 0, v[136:137]
	ds_read_b128 v[188:191], v142
	ds_read_b128 v[192:195], v142 offset:1024
	ds_read_b128 v[196:199], v142 offset:2048
	ds_read_b128 v[206:209], v142 offset:3072
	ds_read_b128 v[214:217], v142 offset:4096
	ds_read_b128 v[218:221], v142 offset:5120
	ds_read_b128 v[222:225], v142 offset:6144
	ds_read_b128 v[226:229], v142 offset:7168
	global_load_lds_dwordx4 v[138:139], off
	v_lshl_add_u64 v[138:139], s[54:55], 0, v[132:133]
	s_mov_b32 m0, s2
	s_nop 0
	global_load_lds_dwordx4 v[138:139], off
	s_waitcnt vmcnt(8) lgkmcnt(0)
	s_setprio 1
	s_barrier
	v_mfma_f32_16x16x32_bf16 v[70:73], v[118:121], v[188:191], v[70:73]
	v_mfma_f32_16x16x32_bf16 v[74:77], v[126:129], v[188:191], v[74:77]
	v_mfma_f32_16x16x32_bf16 v[78:81], v[118:121], v[196:199], v[78:81]
	v_mfma_f32_16x16x32_bf16 v[82:85], v[126:129], v[196:199], v[82:85]
	v_mfma_f32_16x16x32_bf16 v[86:89], v[118:121], v[214:217], v[86:89]
	v_mfma_f32_16x16x32_bf16 v[90:93], v[126:129], v[214:217], v[90:93]
	v_mfma_f32_16x16x32_bf16 v[94:97], v[118:121], v[222:225], v[94:97]
	v_mfma_f32_16x16x32_bf16 v[98:101], v[126:129], v[222:225], v[98:101]
	v_mfma_f32_16x16x32_bf16 v[70:73], v[122:125], v[192:195], v[70:73]
	v_mfma_f32_16x16x32_bf16 v[74:77], v[144:147], v[192:195], v[74:77]
	v_mfma_f32_16x16x32_bf16 v[78:81], v[122:125], v[206:209], v[78:81]
	v_mfma_f32_16x16x32_bf16 v[82:85], v[144:147], v[206:209], v[82:85]
	v_mfma_f32_16x16x32_bf16 v[86:89], v[122:125], v[218:221], v[86:89]
	v_mfma_f32_16x16x32_bf16 v[90:93], v[144:147], v[218:221], v[90:93]
	v_mfma_f32_16x16x32_bf16 v[94:97], v[122:125], v[226:229], v[94:97]
	v_mfma_f32_16x16x32_bf16 v[98:101], v[144:147], v[226:229], v[98:101]
	v_mfma_f32_16x16x32_bf16 v[102:105], v[148:151], v[188:191], v[102:105]
	v_mfma_f32_16x16x32_bf16 v[106:109], v[180:183], v[188:191], v[106:109]
	v_mfma_f32_16x16x32_bf16 v[110:113], v[148:151], v[196:199], v[110:113]
	v_mfma_f32_16x16x32_bf16 v[40:43], v[180:183], v[196:199], v[40:43]
	v_mfma_f32_16x16x32_bf16 v[44:47], v[148:151], v[214:217], v[44:47]
	v_mfma_f32_16x16x32_bf16 v[48:51], v[180:183], v[214:217], v[48:51]
	v_mfma_f32_16x16x32_bf16 v[52:55], v[148:151], v[222:225], v[52:55]
	v_mfma_f32_16x16x32_bf16 v[56:59], v[180:183], v[222:225], v[56:59]
	v_mfma_f32_16x16x32_bf16 v[102:105], v[152:155], v[192:195], v[102:105]
	v_mfma_f32_16x16x32_bf16 v[106:109], v[184:187], v[192:195], v[106:109]
	v_mfma_f32_16x16x32_bf16 v[110:113], v[152:155], v[206:209], v[110:113]
	v_mfma_f32_16x16x32_bf16 v[40:43], v[184:187], v[206:209], v[40:43]
	v_mfma_f32_16x16x32_bf16 v[44:47], v[152:155], v[218:221], v[44:47]
	v_mfma_f32_16x16x32_bf16 v[48:51], v[184:187], v[218:221], v[48:51]
	v_mfma_f32_16x16x32_bf16 v[52:55], v[152:155], v[226:229], v[52:55]
	v_mfma_f32_16x16x32_bf16 v[56:59], v[184:187], v[226:229], v[56:59]
	s_barrier
; #define PG8_STAGE(bufoff, gbase, voff) do { _Pragma("unroll") for (int _i = 0; _i < 2; ++_i) \
;         __builtin_amdgcn_global_load_lds((const unsigned*)((const char*)(gbase) + (voff)[_i]), (PG8_LAS unsigned*)(lds + (bufoff) + ldsw + _i * 8192), 16, 0, 0); } while (0)
; #define PG8_LDA(dst, b, h) do { _Pragma("unroll") for (int m = 0; m < 4; ++m) _Pragma("unroll") for (int k = 0; k < 2; ++k) dst[m][k] = *(const PG8_LAS bf16x8*)(lds + PG8_SA(b, h) + aoff + m * 2048 + k * 1024); } while (0)
; #define PG8_LDB(dst, b, h) do { _Pragma("unroll") for (int n = 0; n < 2; ++n) _Pragma("unroll") for (int k = 0; k < 2; ++k) dst[n][k] = *(const PG8_LAS bf16x8*)(lds + PG8_SB(b, h) + boff + n * 2048 + k * 1024); } while (0)
; #define PG8_MMA(ai, bj, At, Bt) do { __builtin_amdgcn_s_setprio(1); _Pragma("unroll") for (int m = 0; m < 4; ++m) _Pragma("unroll") for (int n = 0; n < 2; ++n) _Pragma("unroll") for (int k = 0; k < 2; ++k) \
;         acc[ai][bj][m][n] = __builtin_amdgcn_mfma_f32_16x16x32_bf16(Bt[n][k], At[m][k], acc[ai][bj][m][n], 0, 0, 0); __builtin_amdgcn_s_setprio(0); } while (0)
; #define PG8_WAIT_V(n) asm volatile("s_waitcnt vmcnt(" #n ")" ::: "memory")
; #define PG8_WAIT_L(n) asm volatile("s_waitcnt lgkmcnt(" #n ")" ::: "memory")
; #define PG8_BAR __builtin_amdgcn_s_barrier()
; #define PG8_SCHED __builtin_amdgcn_sched_barrier(0)
; template <class Epi, class Sched, bool ALIGN_EPI = false, bool SP2 = false>
; __device__ __forceinline__ void gemm_phase(PG8_LAS unsigned char* lds, const Gemm g, const Sched& S, const Epi& E, const int tid) {
;     ...
;             PG8_LDA(At, 0, 1); PG8_STAGE(PG8_SB(0, 0), b2, voffB); PG8_STAGE(PG8_SB(0, 1), b2 + hstep, voffB); PG8_STAGE(PG8_SA(0, 0), a2, voffA);
;             PG8_WAIT_V(8); PG8_WAIT_L(0); PG8_BAR; PG8_MMA(1, 0, At, B0); PG8_MMA(1, 1, At, B1); PG8_BAR; PG8_SCHED;
;             PG8_LDB(B0, 1, 0); PG8_LDB(B1, 1, 1); PG8_SCHED; PG8_LDA(At, 1, 0); PG8_STAGE(PG8_SA(0, 1), a2 + hstep, voffA);
;             PG8_WAIT_V(8); PG8_WAIT_L(0); PG8_BAR; PG8_MMA(0, 0, At, B0); PG8_MMA(0, 1, At, B1); PG8_BAR; PG8_SCHED;
	s_setprio 0
	s_mov_b64 s[56:57], 0x200
	s_mov_b32 m0, s47
	v_lshl_add_u64 v[138:139], v[0:1], 0, s[56:57]
	s_add_u32 s54, s16, 0x18200
	ds_read_b128 v[188:191], v142 offset:16384
	ds_read_b128 v[192:195], v142 offset:17408
	ds_read_b128 v[196:199], v142 offset:18432
	ds_read_b128 v[206:209], v142 offset:19456
	ds_read_b128 v[214:217], v142 offset:20480
	ds_read_b128 v[218:221], v142 offset:21504
	ds_read_b128 v[222:225], v142 offset:22528
	ds_read_b128 v[226:229], v142 offset:23552
	global_load_lds_dwordx4 v[138:139], off
	v_lshl_add_u64 v[138:139], v[2:3], 0, s[56:57]
	s_mov_b32 m0, s3
	s_addc_u32 s55, s17, 0
	global_load_lds_dwordx4 v[138:139], off
	v_lshl_add_u64 v[138:139], s[54:55], 0, v[134:135]
	s_mov_b32 m0, s45
	s_nop 0
	global_load_lds_dwordx4 v[138:139], off
	v_lshl_add_u64 v[138:139], s[54:55], 0, v[130:131]
	s_mov_b32 m0, s46
	s_nop 0
	global_load_lds_dwordx4 v[138:139], off
	v_lshl_add_u64 v[138:139], v[4:5], 0, s[56:57]
	s_mov_b32 m0, s23
	s_nop 0
	global_load_lds_dwordx4 v[138:139], off
	v_lshl_add_u64 v[138:139], v[6:7], 0, s[56:57]
	s_mov_b32 m0, s24
	s_nop 0
	global_load_lds_dwordx4 v[138:139], off
	s_waitcnt vmcnt(8) lgkmcnt(0)
	s_setprio 1
	s_barrier
	v_mfma_f32_16x16x32_bf16 v[12:15], v[118:121], v[222:225], v[12:15]
	v_mfma_f32_16x16x32_bf16 v[16:19], v[126:129], v[222:225], v[16:19]
	v_mfma_f32_16x16x32_bf16 v[156:159], v[118:121], v[188:191], v[156:159]
	v_mfma_f32_16x16x32_bf16 v[160:163], v[126:129], v[188:191], v[160:163]
	v_mfma_f32_16x16x32_bf16 v[164:167], v[118:121], v[196:199], v[164:167]
	v_mfma_f32_16x16x32_bf16 v[168:171], v[126:129], v[196:199], v[168:171]
	v_mfma_f32_16x16x32_bf16 v[172:175], v[118:121], v[214:217], v[172:175]
	v_mfma_f32_16x16x32_bf16 v[176:179], v[126:129], v[214:217], v[176:179]
	v_mfma_f32_16x16x32_bf16 v[12:15], v[122:125], v[226:229], v[12:15]
	v_mfma_f32_16x16x32_bf16 v[16:19], v[144:147], v[226:229], v[16:19]
	v_mfma_f32_16x16x32_bf16 v[156:159], v[122:125], v[192:195], v[156:159]
	v_mfma_f32_16x16x32_bf16 v[160:163], v[144:147], v[192:195], v[160:163]
	v_mfma_f32_16x16x32_bf16 v[164:167], v[122:125], v[206:209], v[164:167]
	v_mfma_f32_16x16x32_bf16 v[168:171], v[144:147], v[206:209], v[168:171]
	v_mfma_f32_16x16x32_bf16 v[172:175], v[122:125], v[218:221], v[172:175]
	v_mfma_f32_16x16x32_bf16 v[176:179], v[144:147], v[218:221], v[176:179]
	v_mfma_f32_16x16x32_bf16 v[20:23], v[148:151], v[188:191], v[20:23]
	v_mfma_f32_16x16x32_bf16 v[32:35], v[180:183], v[188:191], v[32:35]
	v_mfma_f32_16x16x32_bf16 v[36:39], v[148:151], v[196:199], v[36:39]
	v_mfma_f32_16x16x32_bf16 v[60:63], v[180:183], v[196:199], v[60:63]
	v_mfma_f32_16x16x32_bf16 v[66:69], v[148:151], v[214:217], v[66:69]
	v_mfma_f32_16x16x32_bf16 v[114:117], v[180:183], v[214:217], v[114:117]
	v_mfma_f32_16x16x32_bf16 v[24:27], v[148:151], v[222:225], v[24:27]
	v_mfma_f32_16x16x32_bf16 v[28:31], v[180:183], v[222:225], v[28:31]
	v_mfma_f32_16x16x32_bf16 v[20:23], v[152:155], v[192:195], v[20:23]
	v_mfma_f32_16x16x32_bf16 v[32:35], v[184:187], v[192:195], v[32:35]
	v_mfma_f32_16x16x32_bf16 v[36:39], v[152:155], v[206:209], v[36:39]
	v_mfma_f32_16x16x32_bf16 v[60:63], v[184:187], v[206:209], v[60:63]
	v_mfma_f32_16x16x32_bf16 v[66:69], v[152:155], v[218:221], v[66:69]
	v_mfma_f32_16x16x32_bf16 v[114:117], v[184:187], v[218:221], v[114:117]
	v_mfma_f32_16x16x32_bf16 v[24:27], v[152:155], v[226:229], v[24:27]
	v_mfma_f32_16x16x32_bf16 v[28:31], v[184:187], v[226:229], v[28:31]
	s_barrier
	s_setprio 0
	ds_read_b128 v[118:121], v10
	ds_read_b128 v[122:125], v10 offset:1024
	ds_read_b128 v[126:129], v10 offset:2048
	ds_read_b128 v[144:147], v10 offset:3072
	ds_read_b128 v[148:151], v11
	ds_read_b128 v[152:155], v11 offset:1024
	ds_read_b128 v[180:183], v11 offset:2048
	ds_read_b128 v[184:187], v11 offset:3072
	s_add_u32 s54, s14, 0x18200
	s_addc_u32 s55, s15, 0
	s_mov_b32 m0, s25
	v_lshl_add_u64 v[138:139], s[54:55], 0, v[136:137]
	ds_read_b128 v[188:191], v142 offset:32768
	ds_read_b128 v[192:195], v142 offset:33792
	ds_read_b128 v[196:199], v142 offset:34816
	ds_read_b128 v[206:209], v142 offset:35840
	ds_read_b128 v[214:217], v142 offset:36864
	ds_read_b128 v[218:221], v142 offset:37888
	ds_read_b128 v[222:225], v142 offset:38912
	ds_read_b128 v[226:229], v142 offset:39936
	global_load_lds_dwordx4 v[138:139], off
	v_lshl_add_u64 v[138:139], s[54:55], 0, v[132:133]
	s_mov_b32 m0, s26
	s_nop 0
	global_load_lds_dwordx4 v[138:139], off
	s_waitcnt vmcnt(8) lgkmcnt(0)
	s_setprio 1
	s_barrier
	v_mfma_f32_16x16x32_bf16 v[70:73], v[118:121], v[188:191], v[70:73]
	v_mfma_f32_16x16x32_bf16 v[74:77], v[126:129], v[188:191], v[74:77]
	v_mfma_f32_16x16x32_bf16 v[78:81], v[118:121], v[196:199], v[78:81]
	v_mfma_f32_16x16x32_bf16 v[82:85], v[126:129], v[196:199], v[82:85]
	v_mfma_f32_16x16x32_bf16 v[86:89], v[118:121], v[214:217], v[86:89]
	v_mfma_f32_16x16x32_bf16 v[90:93], v[126:129], v[214:217], v[90:93]
	v_mfma_f32_16x16x32_bf16 v[94:97], v[118:121], v[222:225], v[94:97]
	v_mfma_f32_16x16x32_bf16 v[98:101], v[126:129], v[222:225], v[98:101]
	v_mfma_f32_16x16x32_bf16 v[70:73], v[122:125], v[192:195], v[70:73]
	v_mfma_f32_16x16x32_bf16 v[74:77], v[144:147], v[192:195], v[74:77]
	v_mfma_f32_16x16x32_bf16 v[78:81], v[122:125], v[206:209], v[78:81]
	v_mfma_f32_16x16x32_bf16 v[82:85], v[144:147], v[206:209], v[82:85]
	v_mfma_f32_16x16x32_bf16 v[86:89], v[122:125], v[218:221], v[86:89]
	v_mfma_f32_16x16x32_bf16 v[90:93], v[144:147], v[218:221], v[90:93]
	v_mfma_f32_16x16x32_bf16 v[94:97], v[122:125], v[226:229], v[94:97]
	v_mfma_f32_16x16x32_bf16 v[98:101], v[144:147], v[226:229], v[98:101]
	v_mfma_f32_16x16x32_bf16 v[102:105], v[148:151], v[188:191], v[102:105]
	v_mfma_f32_16x16x32_bf16 v[106:109], v[180:183], v[188:191], v[106:109]
	v_mfma_f32_16x16x32_bf16 v[110:113], v[148:151], v[196:199], v[110:113]
	v_mfma_f32_16x16x32_bf16 v[40:43], v[180:183], v[196:199], v[40:43]
	v_mfma_f32_16x16x32_bf16 v[44:47], v[148:151], v[214:217], v[44:47]
	v_mfma_f32_16x16x32_bf16 v[48:51], v[180:183], v[214:217], v[48:51]
	v_mfma_f32_16x16x32_bf16 v[52:55], v[148:151], v[222:225], v[52:55]
	v_mfma_f32_16x16x32_bf16 v[56:59], v[180:183], v[222:225], v[56:59]
	v_mfma_f32_16x16x32_bf16 v[102:105], v[152:155], v[192:195], v[102:105]
	v_mfma_f32_16x16x32_bf16 v[106:109], v[184:187], v[192:195], v[106:109]
	v_mfma_f32_16x16x32_bf16 v[110:113], v[152:155], v[206:209], v[110:113]
	v_mfma_f32_16x16x32_bf16 v[40:43], v[184:187], v[206:209], v[40:43]
	v_mfma_f32_16x16x32_bf16 v[44:47], v[152:155], v[218:221], v[44:47]
	v_mfma_f32_16x16x32_bf16 v[48:51], v[184:187], v[218:221], v[48:51]
	v_mfma_f32_16x16x32_bf16 v[52:55], v[152:155], v[226:229], v[52:55]
	v_mfma_f32_16x16x32_bf16 v[56:59], v[184:187], v[226:229], v[56:59]
	s_barrier
; #define PG8_STAGE(bufoff, gbase, voff) do { _Pragma("unroll") for (int _i = 0; _i < 2; ++_i) \
;         __builtin_amdgcn_global_load_lds((const unsigned*)((const char*)(gbase) + (voff)[_i]), (PG8_LAS unsigned*)(lds + (bufoff) + ldsw + _i * 8192), 16, 0, 0); } while (0)
; #define PG8_LDA(dst, b, h) do { _Pragma("unroll") for (int m = 0; m < 4; ++m) _Pragma("unroll") for (int k = 0; k < 2; ++k) dst[m][k] = *(const PG8_LAS bf16x8*)(lds + PG8_SA(b, h) + aoff + m * 2048 + k * 1024); } while (0)
; #define PG8_LDB(dst, b, h) do { _Pragma("unroll") for (int n = 0; n < 2; ++n) _Pragma("unroll") for (int k = 0; k < 2; ++k) dst[n][k] = *(const PG8_LAS bf16x8*)(lds + PG8_SB(b, h) + boff + n * 2048 + k * 1024); } while (0)
; #define PG8_MMA(ai, bj, At, Bt) do { __builtin_amdgcn_s_setprio(1); _Pragma("unroll") for (int m = 0; m < 4; ++m) _Pragma("unroll") for (int n = 0; n < 2; ++n) _Pragma("unroll") for (int k = 0; k < 2; ++k) \
;         acc[ai][bj][m][n] = __builtin_amdgcn_mfma_f32_16x16x32_bf16(Bt[n][k], At[m][k], acc[ai][bj][m][n], 0, 0, 0); __builtin_amdgcn_s_setprio(0); } while (0)
; #define PG8_BAR __builtin_amdgcn_s_barrier()
; template <class Epi, class Sched, bool ALIGN_EPI = false, bool SP2 = false>
; __device__ __forceinline__ void gemm_phase(PG8_LAS unsigned char* lds, const Gemm g, const Sched& S, const Epi& E, const int tid) {
;     ...
;             PG8_LDB(B0, 0, 0); PG8_LDB(B1, 0, 1); PG8_SCHED; PG8_LDA(At, 0, 0); PG8_STAGE(PG8_SA(1, 1), a1 + hstep, voffA);
;             PG8_WAIT_V(8); PG8_WAIT_L(0); PG8_BAR; PG8_MMA(0, 0, At, B0); PG8_MMA(0, 1, At, B1); PG8_BAR; PG8_SCHED;
;             PG8_LDA(At, 0, 1); PG8_STAGE(PG8_SB(0, 0), b2, voffB); PG8_STAGE(PG8_SB(0, 1), b2 + hstep, voffB); PG8_STAGE(PG8_SA(0, 0), a2, voffA);
;             PG8_WAIT_V(8); PG8_WAIT_L(0); PG8_BAR; PG8_MMA(1, 0, At, B0); PG8_MMA(1, 1, At, B1); PG8_BAR; PG8_SCHED;
;             PG8_LDB(B0, 1, 0); PG8_LDB(B1, 1, 1); PG8_SCHED; PG8_LDA(At, 1, 0); PG8_STAGE(PG8_SA(0, 1), a2 + hstep, voffA);
;             PG8_WAIT_V(8); PG8_WAIT_L(0); PG8_BAR; PG8_MMA(0, 0, At, B0); PG8_MMA(0, 1, At, B1); PG8_BAR; PG8_SCHED;
;             PG8_LDA(At, 1, 1); PG8_STAGE(PG8_SB(1, 0), b3, voffB); PG8_STAGE(PG8_SB(1, 1), b3 + hstep, voffB); PG8_STAGE(PG8_SA(1, 0), a3, voffA);
;             PG8_WAIT_V(8); PG8_WAIT_L(0); PG8_BAR; PG8_MMA(1, 0, At, B0); PG8_MMA(1, 1, At, B1); PG8_BAR; PG8_SCHED;
	s_setprio 0
	s_mov_b64 s[54:55], 0x280
	s_mov_b32 m0, s52
	v_lshl_add_u64 v[0:1], v[0:1], 0, s[54:55]
	s_add_u32 s16, s16, 0x18280
	ds_read_b128 v[188:191], v142 offset:49152
	ds_read_b128 v[192:195], v142 offset:50176
	ds_read_b128 v[196:199], v142 offset:51200
	ds_read_b128 v[206:209], v142 offset:52224
	ds_read_b128 v[214:217], v142 offset:53248
	ds_read_b128 v[218:221], v142 offset:54272
	ds_read_b128 v[222:225], v142 offset:55296
	ds_read_b128 v[226:229], v142 offset:56320
	global_load_lds_dwordx4 v[0:1], off
	v_lshl_add_u64 v[0:1], v[2:3], 0, s[54:55]
	s_mov_b32 m0, s48
	s_addc_u32 s17, s17, 0
	global_load_lds_dwordx4 v[0:1], off
	v_lshl_add_u64 v[0:1], s[16:17], 0, v[134:135]
	s_mov_b32 m0, s49
	s_nop 0
	global_load_lds_dwordx4 v[0:1], off
	v_lshl_add_u64 v[0:1], s[16:17], 0, v[130:131]
	s_mov_b32 m0, s51
	s_nop 0
	global_load_lds_dwordx4 v[0:1], off
	v_lshl_add_u64 v[0:1], v[4:5], 0, s[54:55]
	s_mov_b32 m0, s28
	s_nop 0
	global_load_lds_dwordx4 v[0:1], off
	v_lshl_add_u64 v[0:1], v[6:7], 0, s[54:55]
	s_mov_b32 m0, s29
	s_nop 0
	global_load_lds_dwordx4 v[0:1], off
	s_waitcnt vmcnt(8) lgkmcnt(0)
	s_setprio 1
	s_barrier
	v_mfma_f32_16x16x32_bf16 v[0:3], v[118:121], v[188:191], v[156:159]
	v_mfma_f32_16x16x32_bf16 v[4:7], v[126:129], v[188:191], v[160:163]
	v_mfma_f32_16x16x32_bf16 v[12:15], v[118:121], v[222:225], v[12:15]
	v_mfma_f32_16x16x32_bf16 v[16:19], v[126:129], v[222:225], v[16:19]
	v_mfma_f32_16x16x32_bf16 v[0:3], v[122:125], v[192:195], v[0:3]
	v_mfma_f32_16x16x32_bf16 v[4:7], v[144:147], v[192:195], v[4:7]
	v_mfma_f32_16x16x32_bf16 v[156:159], v[118:121], v[196:199], v[164:167]
	v_mfma_f32_16x16x32_bf16 v[160:163], v[126:129], v[196:199], v[168:171]
	v_mfma_f32_16x16x32_bf16 v[164:167], v[118:121], v[214:217], v[172:175]
	v_mfma_f32_16x16x32_bf16 v[168:171], v[126:129], v[214:217], v[176:179]
	v_mfma_f32_16x16x32_bf16 v[12:15], v[122:125], v[226:229], v[12:15]
	v_mfma_f32_16x16x32_bf16 v[16:19], v[144:147], v[226:229], v[16:19]
	v_mfma_f32_16x16x32_bf16 v[156:159], v[122:125], v[206:209], v[156:159]
	v_mfma_f32_16x16x32_bf16 v[160:163], v[144:147], v[206:209], v[160:163]
	v_mfma_f32_16x16x32_bf16 v[164:167], v[122:125], v[218:221], v[164:167]
	v_mfma_f32_16x16x32_bf16 v[168:171], v[144:147], v[218:221], v[168:171]
	v_mfma_f32_16x16x32_bf16 v[20:23], v[148:151], v[188:191], v[20:23]
	v_mfma_f32_16x16x32_bf16 v[32:35], v[180:183], v[188:191], v[32:35]
	v_mfma_f32_16x16x32_bf16 v[36:39], v[148:151], v[196:199], v[36:39]
	v_mfma_f32_16x16x32_bf16 v[60:63], v[180:183], v[196:199], v[60:63]
	v_mfma_f32_16x16x32_bf16 v[66:69], v[148:151], v[214:217], v[66:69]
	v_mfma_f32_16x16x32_bf16 v[114:117], v[180:183], v[214:217], v[114:117]
	v_mfma_f32_16x16x32_bf16 v[24:27], v[148:151], v[222:225], v[24:27]
	v_mfma_f32_16x16x32_bf16 v[28:31], v[180:183], v[222:225], v[28:31]
	v_mfma_f32_16x16x32_bf16 v[20:23], v[152:155], v[192:195], v[20:23]
	v_mfma_f32_16x16x32_bf16 v[32:35], v[184:187], v[192:195], v[32:35]
	v_mfma_f32_16x16x32_bf16 v[36:39], v[152:155], v[206:209], v[36:39]
	v_mfma_f32_16x16x32_bf16 v[60:63], v[184:187], v[206:209], v[60:63]
	v_mfma_f32_16x16x32_bf16 v[66:69], v[152:155], v[218:221], v[66:69]
	v_mfma_f32_16x16x32_bf16 v[114:117], v[184:187], v[218:221], v[114:117]
	v_mfma_f32_16x16x32_bf16 v[24:27], v[152:155], v[226:229], v[24:27]
	v_mfma_f32_16x16x32_bf16 v[28:31], v[184:187], v[226:229], v[28:31]
	s_barrier
	s_setprio 0
	ds_read_b128 v[118:121], v8
	ds_read_b128 v[122:125], v8 offset:1024
	ds_read_b128 v[126:129], v8 offset:2048
	ds_read_b128 v[144:147], v8 offset:3072
	ds_read_b128 v[148:151], v9
	ds_read_b128 v[152:155], v9 offset:1024
	ds_read_b128 v[172:175], v9 offset:2048
	ds_read_b128 v[176:179], v9 offset:3072
	s_add_u32 s14, s14, 0x18280
	s_addc_u32 s15, s15, 0
	s_mov_b32 m0, s50
	v_lshl_add_u64 v[8:9], s[14:15], 0, v[136:137]
	ds_read_b128 v[180:183], v142
	ds_read_b128 v[184:187], v142 offset:1024
	ds_read_b128 v[188:191], v142 offset:2048
	ds_read_b128 v[192:195], v142 offset:3072
	ds_read_b128 v[196:199], v142 offset:4096
	ds_read_b128 v[206:209], v142 offset:5120
	ds_read_b128 v[214:217], v142 offset:6144
	ds_read_b128 v[218:221], v142 offset:7168
	global_load_lds_dwordx4 v[8:9], off
	v_lshl_add_u64 v[8:9], s[14:15], 0, v[132:133]
	s_mov_b32 m0, s2
	s_nop 0
	global_load_lds_dwordx4 v[8:9], off
	s_waitcnt vmcnt(8) lgkmcnt(0)
	s_setprio 1
	s_barrier
	v_mfma_f32_16x16x32_bf16 v[94:97], v[118:121], v[214:217], v[94:97]
	v_mfma_f32_16x16x32_bf16 v[70:73], v[118:121], v[180:183], v[70:73]
	v_mfma_f32_16x16x32_bf16 v[74:77], v[126:129], v[180:183], v[74:77]
	v_mfma_f32_16x16x32_bf16 v[78:81], v[118:121], v[188:191], v[78:81]
	v_mfma_f32_16x16x32_bf16 v[82:85], v[126:129], v[188:191], v[82:85]
	v_mfma_f32_16x16x32_bf16 v[86:89], v[118:121], v[196:199], v[86:89]
	v_mfma_f32_16x16x32_bf16 v[90:93], v[126:129], v[196:199], v[90:93]
	v_mfma_f32_16x16x32_bf16 v[222:225], v[122:125], v[218:221], v[94:97]
	v_mfma_f32_16x16x32_bf16 v[94:97], v[126:129], v[214:217], v[98:101]
	v_mfma_f32_16x16x32_bf16 v[70:73], v[122:125], v[184:187], v[70:73]
	v_mfma_f32_16x16x32_bf16 v[74:77], v[144:147], v[184:187], v[74:77]
	v_mfma_f32_16x16x32_bf16 v[78:81], v[122:125], v[192:195], v[78:81]
	v_mfma_f32_16x16x32_bf16 v[82:85], v[144:147], v[192:195], v[82:85]
	v_mfma_f32_16x16x32_bf16 v[86:89], v[122:125], v[206:209], v[86:89]
	v_mfma_f32_16x16x32_bf16 v[90:93], v[144:147], v[206:209], v[90:93]
	v_mfma_f32_16x16x32_bf16 v[98:101], v[144:147], v[218:221], v[94:97]
	v_mfma_f32_16x16x32_bf16 v[94:97], v[148:151], v[180:183], v[102:105]
	v_mfma_f32_16x16x32_bf16 v[102:105], v[152:155], v[184:187], v[94:97]
	v_mfma_f32_16x16x32_bf16 v[94:97], v[172:175], v[180:183], v[106:109]
	v_mfma_f32_16x16x32_bf16 v[40:43], v[172:175], v[188:191], v[40:43]
	v_mfma_f32_16x16x32_bf16 v[44:47], v[148:151], v[196:199], v[44:47]
	v_mfma_f32_16x16x32_bf16 v[48:51], v[172:175], v[196:199], v[48:51]
	v_mfma_f32_16x16x32_bf16 v[52:55], v[148:151], v[214:217], v[52:55]
	v_mfma_f32_16x16x32_bf16 v[56:59], v[172:175], v[214:217], v[56:59]
	v_mfma_f32_16x16x32_bf16 v[180:183], v[176:179], v[184:187], v[94:97]
	v_mfma_f32_16x16x32_bf16 v[94:97], v[148:151], v[188:191], v[110:113]
	v_mfma_f32_16x16x32_bf16 v[40:43], v[176:179], v[192:195], v[40:43]
	v_mfma_f32_16x16x32_bf16 v[44:47], v[152:155], v[206:209], v[44:47]
	v_mfma_f32_16x16x32_bf16 v[48:51], v[176:179], v[206:209], v[48:51]
	v_mfma_f32_16x16x32_bf16 v[52:55], v[152:155], v[218:221], v[52:55]
	v_mfma_f32_16x16x32_bf16 v[56:59], v[176:179], v[218:221], v[56:59]
	v_mfma_f32_16x16x32_bf16 v[184:187], v[152:155], v[192:195], v[94:97]
	s_barrier
; #define PG8_STAGE(bufoff, gbase, voff) do { _Pragma("unroll") for (int _i = 0; _i < 2; ++_i) \
;         __builtin_amdgcn_global_load_lds((const unsigned*)((const char*)(gbase) + (voff)[_i]), (PG8_LAS unsigned*)(lds + (bufoff) + ldsw + _i * 8192), 16, 0, 0); } while (0)
; #define PG8_LDA(dst, b, h) do { _Pragma("unroll") for (int m = 0; m < 4; ++m) _Pragma("unroll") for (int k = 0; k < 2; ++k) dst[m][k] = *(const PG8_LAS bf16x8*)(lds + PG8_SA(b, h) + aoff + m * 2048 + k * 1024); } while (0)
; #define PG8_LDB(dst, b, h) do { _Pragma("unroll") for (int n = 0; n < 2; ++n) _Pragma("unroll") for (int k = 0; k < 2; ++k) dst[n][k] = *(const PG8_LAS bf16x8*)(lds + PG8_SB(b, h) + boff + n * 2048 + k * 1024); } while (0)
; #define PG8_MMA(ai, bj, At, Bt) do { __builtin_amdgcn_s_setprio(1); _Pragma("unroll") for (int m = 0; m < 4; ++m) _Pragma("unroll") for (int n = 0; n < 2; ++n) _Pragma("unroll") for (int k = 0; k < 2; ++k) \
;         acc[ai][bj][m][n] = __builtin_amdgcn_mfma_f32_16x16x32_bf16(Bt[n][k], At[m][k], acc[ai][bj][m][n], 0, 0, 0); __builtin_amdgcn_s_setprio(0); } while (0)
; template <class Epi, class Sched, bool ALIGN_EPI = false, bool SP2 = false>
; __device__ __forceinline__ void gemm_phase(PG8_LAS unsigned char* lds, const Gemm g, const Sched& S, const Epi& E, const int tid) {
;     ...
;             const char* a2 = last ? nA : cA + (size_t)(t + 2) * kstep; const char* b2 = last ? nB : cB + (size_t)(t + 2) * kstep;
;             const char* a3 = a2 + kstep; const char* b3 = b2 + kstep;
;             if (last && has_next) S.a_ready(nxt);
;             if constexpr (SP2) {
;             PG8_LDB(B0, 0, 0); PG8_LDB(B1, 0, 1); PG8_SCHED; PG8_LDA(At, 0, 0); PG8_STAGE(PG8_SA(1, 1), a1 + hstep, voffA);
;             PG8_WAIT_V(8); PG8_WAIT_L(0); PG8_BAR; PG8_MMA(0, 0, At, B0); PG8_MMA(0, 1, At, B1); PG8_BAR; PG8_SCHED;
;             PG8_LDA(At, 0, 1); PG8_STAGE(PG8_SB(0, 0), b2, voffB); PG8_STAGE(PG8_SB(0, 1), b2 + hstep, voffB); PG8_STAGE(PG8_SA(0, 0), a2, voffA);
;             PG8_WAIT_V(8); PG8_WAIT_L(0); PG8_BAR; PG8_MMA(1, 0, At, B0); PG8_MMA(1, 1, At, B1); PG8_BAR; PG8_SCHED;
;             PG8_LDB(B0, 1, 0); PG8_LDB(B1, 1, 1); PG8_SCHED; PG8_LDA(At, 1, 0); PG8_STAGE(PG8_SA(0, 1), a2 + hstep, voffA);
;             PG8_WAIT_V(8); PG8_WAIT_L(0); PG8_BAR; PG8_MMA(0, 0, At, B0); PG8_MMA(0, 1, At, B1); PG8_BAR; PG8_SCHED;
	s_setprio 0
	s_mov_b32 m0, s47
	v_lshl_add_u64 v[138:139], s[12:13], 0, v[134:135]
	s_add_u32 s2, s12, 0x18000
	ds_read_b128 v[94:97], v142 offset:16384
	ds_read_b128 v[106:109], v142 offset:17408
	ds_read_b128 v[110:113], v142 offset:18432
	ds_read_b128 v[188:191], v142 offset:19456
	ds_read_b128 v[192:195], v142 offset:20480
	ds_read_b128 v[196:199], v142 offset:21504
	ds_read_b128 v[206:209], v142 offset:22528
	ds_read_b128 v[214:217], v142 offset:23552
	global_load_lds_dwordx4 v[138:139], off
	v_lshl_add_u64 v[252:253], s[12:13], 0, v[130:131]
	s_mov_b32 m0, s3
	s_addc_u32 s3, s13, 0
	global_load_lds_dwordx4 v[252:253], off
	v_lshl_add_u64 v[8:9], s[2:3], 0, v[134:135]
	s_mov_b32 m0, s45
	v_lshl_add_u64 v[246:247], s[10:11], 0, v[136:137]
	global_load_lds_dwordx4 v[8:9], off
	v_lshl_add_u64 v[8:9], s[2:3], 0, v[130:131]
	s_mov_b32 m0, s46
	v_lshl_add_u64 v[210:211], s[10:11], 0, v[132:133]
	global_load_lds_dwordx4 v[8:9], off
	s_mov_b32 m0, s23
	s_nop 0
	global_load_lds_dwordx4 v[246:247], off
	s_mov_b32 m0, s24
	s_nop 0
	global_load_lds_dwordx4 v[210:211], off
	s_waitcnt vmcnt(8) lgkmcnt(0)
	s_setprio 1
	s_barrier
	v_mfma_f32_16x16x32_bf16 v[0:3], v[118:121], v[94:97], v[0:3]
	v_mfma_f32_16x16x32_bf16 v[4:7], v[126:129], v[94:97], v[4:7]
	v_mfma_f32_16x16x32_bf16 v[12:15], v[118:121], v[206:209], v[12:15]
	v_mfma_f32_16x16x32_bf16 v[16:19], v[126:129], v[206:209], v[16:19]
	v_mfma_f32_16x16x32_bf16 v[0:3], v[122:125], v[106:109], v[0:3]
	v_mfma_f32_16x16x32_bf16 v[4:7], v[144:147], v[106:109], v[4:7]
	v_mfma_f32_16x16x32_bf16 v[156:159], v[118:121], v[110:113], v[156:159]
	v_mfma_f32_16x16x32_bf16 v[160:163], v[126:129], v[110:113], v[160:163]
	v_mfma_f32_16x16x32_bf16 v[164:167], v[118:121], v[192:195], v[164:167]
	v_mfma_f32_16x16x32_bf16 v[168:171], v[126:129], v[192:195], v[168:171]
	v_mfma_f32_16x16x32_bf16 v[12:15], v[122:125], v[214:217], v[12:15]
	v_mfma_f32_16x16x32_bf16 v[16:19], v[144:147], v[214:217], v[16:19]
	v_mfma_f32_16x16x32_bf16 v[156:159], v[122:125], v[188:191], v[156:159]
	v_mfma_f32_16x16x32_bf16 v[160:163], v[144:147], v[188:191], v[160:163]
	v_mfma_f32_16x16x32_bf16 v[164:167], v[122:125], v[196:199], v[164:167]
	v_mfma_f32_16x16x32_bf16 v[168:171], v[144:147], v[196:199], v[168:171]
	v_mfma_f32_16x16x32_bf16 v[60:63], v[172:175], v[110:113], v[60:63]
	v_mfma_f32_16x16x32_bf16 v[20:23], v[148:151], v[94:97], v[20:23]
	v_mfma_f32_16x16x32_bf16 v[32:35], v[172:175], v[94:97], v[32:35]
	v_mfma_f32_16x16x32_bf16 v[36:39], v[148:151], v[110:113], v[36:39]
	v_mfma_f32_16x16x32_bf16 v[144:147], v[176:179], v[188:191], v[60:63]
	v_mfma_f32_16x16x32_bf16 v[60:63], v[148:151], v[192:195], v[66:69]
	v_mfma_f32_16x16x32_bf16 v[24:27], v[148:151], v[206:209], v[24:27]
	v_mfma_f32_16x16x32_bf16 v[20:23], v[152:155], v[106:109], v[20:23]
	v_mfma_f32_16x16x32_bf16 v[32:35], v[176:179], v[106:109], v[32:35]
	v_mfma_f32_16x16x32_bf16 v[36:39], v[152:155], v[188:191], v[36:39]
	v_mfma_f32_16x16x32_bf16 v[188:191], v[152:155], v[196:199], v[60:63]
	v_mfma_f32_16x16x32_bf16 v[60:63], v[172:175], v[192:195], v[114:117]
	v_mfma_f32_16x16x32_bf16 v[148:151], v[152:155], v[214:217], v[24:27]
	v_mfma_f32_16x16x32_bf16 v[24:27], v[172:175], v[206:209], v[28:31]
	v_mfma_f32_16x16x32_bf16 v[192:195], v[176:179], v[196:199], v[60:63]
	v_mfma_f32_16x16x32_bf16 v[152:155], v[176:179], v[214:217], v[24:27]
	s_barrier
	s_setprio 0
	ds_read_b128 v[172:175], v10
	ds_read_b128 v[176:179], v10 offset:1024
	ds_read_b128 v[196:199], v10 offset:2048
	ds_read_b128 v[206:209], v10 offset:3072
	ds_read_b128 v[214:217], v11
	ds_read_b128 v[218:221], v11 offset:1024
	ds_read_b128 v[226:229], v11 offset:2048
	ds_read_b128 v[248:251], v11 offset:3072
	s_add_u32 s2, s10, 0x18000
	s_addc_u32 s3, s11, 0
	s_mov_b32 m0, s25
	v_lshl_add_u64 v[94:95], s[2:3], 0, v[136:137]
	ds_read_b128 v[8:11], v142 offset:32768
	ds_read_b128 v[24:27], v142 offset:33792
	ds_read_b128 v[28:31], v142 offset:34816
	ds_read_b128 v[60:63], v142 offset:35840
	ds_read_b128 v[66:69], v142 offset:36864
	ds_read_b128 v[234:237], v142 offset:37888
	ds_read_b128 v[238:241], v142 offset:38912
	ds_read_b128 v[230:233], v142 offset:39936
	global_load_lds_dwordx4 v[94:95], off
	v_lshl_add_u64 v[94:95], s[2:3], 0, v[132:133]
	s_mov_b32 m0, s26
	s_nop 0
	global_load_lds_dwordx4 v[94:95], off
	s_waitcnt vmcnt(8) lgkmcnt(0)
	s_setprio 1
	s_barrier
; #define PG8_STAGE(bufoff, gbase, voff) do { _Pragma("unroll") for (int _i = 0; _i < 2; ++_i) \
;         __builtin_amdgcn_global_load_lds((const unsigned*)((const char*)(gbase) + (voff)[_i]), (PG8_LAS unsigned*)(lds + (bufoff) + ldsw + _i * 8192), 16, 0, 0); } while (0)
; #define PG8_LDA(dst, b, h) do { _Pragma("unroll") for (int m = 0; m < 4; ++m) _Pragma("unroll") for (int k = 0; k < 2; ++k) dst[m][k] = *(const PG8_LAS bf16x8*)(lds + PG8_SA(b, h) + aoff + m * 2048 + k * 1024); } while (0)
; #define PG8_MMA(ai, bj, At, Bt) do { __builtin_amdgcn_s_setprio(1); _Pragma("unroll") for (int m = 0; m < 4; ++m) _Pragma("unroll") for (int n = 0; n < 2; ++n) _Pragma("unroll") for (int k = 0; k < 2; ++k) \
;         acc[ai][bj][m][n] = __builtin_amdgcn_mfma_f32_16x16x32_bf16(Bt[n][k], At[m][k], acc[ai][bj][m][n], 0, 0, 0); __builtin_amdgcn_s_setprio(0); } while (0)
; #define PG8_WAIT_V(n) asm volatile("s_waitcnt vmcnt(" #n ")" ::: "memory")
; #define PG8_WAIT_L(n) asm volatile("s_waitcnt lgkmcnt(" #n ")" ::: "memory")
; #define PG8_BAR __builtin_amdgcn_s_barrier()
; #define PG8_SCHED __builtin_amdgcn_sched_barrier(0)
; template <class Epi, class Sched, bool ALIGN_EPI = false, bool SP2 = false>
; __device__ __forceinline__ void gemm_phase(PG8_LAS unsigned char* lds, const Gemm g, const Sched& S, const Epi& E, const int tid) {
;     ...
;             PG8_WAIT_V(8); PG8_WAIT_L(0); PG8_BAR; PG8_MMA(0, 0, At, B0); PG8_MMA(0, 1, At, B1); PG8_BAR; PG8_SCHED;
;             PG8_LDA(At, 1, 1); PG8_STAGE(PG8_SB(1, 0), b3, voffB); PG8_STAGE(PG8_SB(1, 1), b3 + hstep, voffB); PG8_STAGE(PG8_SA(1, 0), a3, voffA);
;             PG8_WAIT_V(8); PG8_WAIT_L(0); PG8_BAR; PG8_MMA(1, 0, At, B0); PG8_MMA(1, 1, At, B1); PG8_BAR; PG8_SCHED;
;     ...
;         if constexpr (ALIGN_EPI) { if (wr == 0) PG8_BAR; }
	v_mfma_f32_16x16x32_bf16 v[70:73], v[172:175], v[8:11], v[70:73]
	v_mfma_f32_16x16x32_bf16 v[126:129], v[176:179], v[24:27], v[70:73]
	v_mfma_f32_16x16x32_bf16 v[70:73], v[196:199], v[8:11], v[74:77]
	v_mfma_f32_16x16x32_bf16 v[122:125], v[206:209], v[24:27], v[70:73]
	v_mfma_f32_16x16x32_bf16 v[70:73], v[172:175], v[28:31], v[78:81]
	v_mfma_f32_16x16x32_bf16 v[110:113], v[176:179], v[60:63], v[70:73]
	v_mfma_f32_16x16x32_bf16 v[70:73], v[196:199], v[28:31], v[82:85]
	v_mfma_f32_16x16x32_bf16 v[106:109], v[206:209], v[60:63], v[70:73]
	v_mfma_f32_16x16x32_bf16 v[70:73], v[172:175], v[66:69], v[86:89]
	v_mfma_f32_16x16x32_bf16 v[94:97], v[176:179], v[234:237], v[70:73]
	v_mfma_f32_16x16x32_bf16 v[70:73], v[196:199], v[66:69], v[90:93]
	v_mfma_f32_16x16x32_bf16 v[90:93], v[206:209], v[234:237], v[70:73]
	v_mfma_f32_16x16x32_bf16 v[70:73], v[172:175], v[238:241], v[222:225]
	v_mfma_f32_16x16x32_bf16 v[78:81], v[176:179], v[230:233], v[70:73]
	v_mfma_f32_16x16x32_bf16 v[70:73], v[196:199], v[238:241], v[98:101]
	v_mfma_f32_16x16x32_bf16 v[74:77], v[206:209], v[230:233], v[70:73]
	v_mfma_f32_16x16x32_bf16 v[70:73], v[214:217], v[8:11], v[102:105]
	v_mfma_f32_16x16x32_bf16 v[8:11], v[226:229], v[8:11], v[180:183]
	v_mfma_f32_16x16x32_bf16 v[118:121], v[248:251], v[24:27], v[8:11]
	v_mfma_f32_16x16x32_bf16 v[8:11], v[214:217], v[28:31], v[184:187]
	v_mfma_f32_16x16x32_bf16 v[98:101], v[218:221], v[60:63], v[8:11]
	v_mfma_f32_16x16x32_bf16 v[8:11], v[226:229], v[28:31], v[40:43]
	v_mfma_f32_16x16x32_bf16 v[102:105], v[248:251], v[60:63], v[8:11]
	v_mfma_f32_16x16x32_bf16 v[8:11], v[214:217], v[66:69], v[44:47]
	v_mfma_f32_16x16x32_bf16 v[82:85], v[218:221], v[234:237], v[8:11]
	v_mfma_f32_16x16x32_bf16 v[8:11], v[226:229], v[66:69], v[48:51]
	v_mfma_f32_16x16x32_bf16 v[86:89], v[248:251], v[234:237], v[8:11]
	v_mfma_f32_16x16x32_bf16 v[8:11], v[214:217], v[238:241], v[52:55]
	v_mfma_f32_16x16x32_bf16 v[66:69], v[218:221], v[230:233], v[8:11]
	v_mfma_f32_16x16x32_bf16 v[8:11], v[226:229], v[238:241], v[56:59]
	v_mfma_f32_16x16x32_bf16 v[114:117], v[218:221], v[24:27], v[70:73]
	v_mfma_f32_16x16x32_bf16 v[70:73], v[248:251], v[230:233], v[8:11]
	s_barrier
	s_setprio 0
	s_mov_b32 m0, s52
	s_nop 2
	v_lshl_add_u64 v[8:9], v[138:139], 0, s[94:95]
	s_add_u32 s2, s12, 0x18080
	ds_read_b128 v[52:55], v142 offset:49152
	ds_read_b128 v[180:183], v142 offset:50176
	ds_read_b128 v[184:187], v142 offset:51200
	ds_read_b128 v[222:225], v142 offset:52224
	ds_read_b128 v[230:233], v142 offset:53248
	ds_read_b128 v[234:237], v142 offset:54272
	ds_read_b128 v[238:241], v142 offset:55296
	ds_read_b128 v[200:203], v142 offset:56320
	global_load_lds_dwordx4 v[8:9], off
	v_lshl_add_u64 v[8:9], v[252:253], 0, s[94:95]
	s_mov_b32 m0, s48
	s_addc_u32 s3, s13, 0
	global_load_lds_dwordx4 v[8:9], off
	v_lshl_add_u64 v[8:9], s[2:3], 0, v[134:135]
	s_mov_b32 m0, s49
	s_nop 0
	global_load_lds_dwordx4 v[8:9], off
	v_lshl_add_u64 v[8:9], s[2:3], 0, v[130:131]
	s_mov_b32 m0, s51
	s_nop 0
	global_load_lds_dwordx4 v[8:9], off
	v_lshl_add_u64 v[8:9], v[246:247], 0, s[94:95]
	s_mov_b32 m0, s28
	s_nop 0
	global_load_lds_dwordx4 v[8:9], off
	v_lshl_add_u64 v[8:9], v[210:211], 0, s[94:95]
	s_mov_b32 m0, s29
	s_nop 0
	global_load_lds_dwordx4 v[8:9], off
	s_waitcnt vmcnt(8) lgkmcnt(0)
	s_setprio 1
	s_barrier
	v_mfma_f32_16x16x32_bf16 v[0:3], v[172:175], v[52:55], v[0:3]
	v_mfma_f32_16x16x32_bf16 v[60:63], v[176:179], v[180:183], v[0:3]
	v_mfma_f32_16x16x32_bf16 v[0:3], v[196:199], v[52:55], v[4:7]
	v_mfma_f32_16x16x32_bf16 v[56:59], v[206:209], v[180:183], v[0:3]
	v_mfma_f32_16x16x32_bf16 v[0:3], v[172:175], v[184:187], v[156:159]
	v_mfma_f32_16x16x32_bf16 v[44:47], v[176:179], v[222:225], v[0:3]
	v_mfma_f32_16x16x32_bf16 v[0:3], v[196:199], v[184:187], v[160:163]
	v_mfma_f32_16x16x32_bf16 v[40:43], v[206:209], v[222:225], v[0:3]
	v_mfma_f32_16x16x32_bf16 v[0:3], v[172:175], v[230:233], v[164:167]
	v_mfma_f32_16x16x32_bf16 v[28:31], v[176:179], v[234:237], v[0:3]
	v_mfma_f32_16x16x32_bf16 v[0:3], v[196:199], v[230:233], v[168:171]
	v_mfma_f32_16x16x32_bf16 v[24:27], v[206:209], v[234:237], v[0:3]
	v_mfma_f32_16x16x32_bf16 v[0:3], v[172:175], v[238:241], v[12:15]
	v_mfma_f32_16x16x32_bf16 v[8:11], v[176:179], v[200:203], v[0:3]
	v_mfma_f32_16x16x32_bf16 v[0:3], v[196:199], v[238:241], v[16:19]
	v_mfma_f32_16x16x32_bf16 v[12:15], v[206:209], v[200:203], v[0:3]
	v_mfma_f32_16x16x32_bf16 v[0:3], v[214:217], v[52:55], v[20:23]
	v_mfma_f32_16x16x32_bf16 v[48:51], v[218:221], v[180:183], v[0:3]
	v_mfma_f32_16x16x32_bf16 v[0:3], v[226:229], v[52:55], v[32:35]
	v_mfma_f32_16x16x32_bf16 v[52:55], v[248:251], v[180:183], v[0:3]
	v_mfma_f32_16x16x32_bf16 v[0:3], v[214:217], v[184:187], v[36:39]
	v_mfma_f32_16x16x32_bf16 v[32:35], v[218:221], v[222:225], v[0:3]
	v_mfma_f32_16x16x32_bf16 v[0:3], v[226:229], v[184:187], v[144:147]
	v_mfma_f32_16x16x32_bf16 v[36:39], v[248:251], v[222:225], v[0:3]
	v_mfma_f32_16x16x32_bf16 v[0:3], v[214:217], v[230:233], v[188:191]
	v_mfma_f32_16x16x32_bf16 v[16:19], v[218:221], v[234:237], v[0:3]
	v_mfma_f32_16x16x32_bf16 v[0:3], v[226:229], v[230:233], v[192:195]
	v_mfma_f32_16x16x32_bf16 v[20:23], v[248:251], v[234:237], v[0:3]
	v_mfma_f32_16x16x32_bf16 v[0:3], v[214:217], v[238:241], v[148:151]
	v_mfma_f32_16x16x32_bf16 v[4:7], v[226:229], v[238:241], v[152:155]
	v_mfma_f32_16x16x32_bf16 v[0:3], v[218:221], v[200:203], v[0:3]
	v_mfma_f32_16x16x32_bf16 v[4:7], v[248:251], v[200:203], v[4:7]
	s_barrier
	s_setprio 0
	s_andn2_b64 vcc, exec, s[8:9]
	s_cbranch_vccnz .LBB0_350
	s_barrier

; #define PG8_STAGE(bufoff, gbase, voff) do { _Pragma("unroll") for (int _i = 0; _i < 2; ++_i) \
;         __builtin_amdgcn_global_load_lds((const unsigned*)((const char*)(gbase) + (voff)[_i]), (PG8_LAS unsigned*)(lds + (bufoff) + ldsw + _i * 8192), 16, 0, 0); } while (0)
; #define PG8_LDA(dst, b, h) do { _Pragma("unroll") for (int m = 0; m < 4; ++m) _Pragma("unroll") for (int k = 0; k < 2; ++k) dst[m][k] = *(const PG8_LAS bf16x8*)(lds + PG8_SA(b, h) + aoff + m * 2048 + k * 1024); } while (0)
; #define PG8_LDB(dst, b, h) do { _Pragma("unroll") for (int n = 0; n < 2; ++n) _Pragma("unroll") for (int k = 0; k < 2; ++k) dst[n][k] = *(const PG8_LAS bf16x8*)(lds + PG8_SB(b, h) + boff + n * 2048 + k * 1024); } while (0)
; #define PG8_MMA(ai, bj, At, Bt) do { __builtin_amdgcn_s_setprio(1); _Pragma("unroll") for (int m = 0; m < 4; ++m) _Pragma("unroll") for (int n = 0; n < 2; ++n) _Pragma("unroll") for (int k = 0; k < 2; ++k) \
;         acc[ai][bj][m][n] = __builtin_amdgcn_mfma_f32_16x16x32_bf16(Bt[n][k], At[m][k], acc[ai][bj][m][n], 0, 0, 0); __builtin_amdgcn_s_setprio(0); } while (0)
; #define PG8_WAIT_V(n) asm volatile("s_waitcnt vmcnt(" #n ")" ::: "memory")
; #define PG8_WAIT_L(n) asm volatile("s_waitcnt lgkmcnt(" #n ")" ::: "memory")
; template <class Epi, class Sched, bool ALIGN_EPI = false, bool SP2 = false>
; __device__ __forceinline__ void gemm_phase(PG8_LAS unsigned char* lds, const Gemm g, const Sched& S, const Epi& E, const int tid) {
;     ...
;             const bool last = (t == nt - 2);
;             const char* a1 = cA + (size_t)(t + 1) * kstep;
;             const char* a2 = last ? nA : cA + (size_t)(t + 2) * kstep; const char* b2 = last ? nB : cB + (size_t)(t + 2) * kstep;
;             const char* a3 = a2 + kstep; const char* b3 = b2 + kstep;
;             if (last && has_next) S.a_ready(nxt);
;             if constexpr (SP2) {
;             PG8_LDB(B0, 0, 0); PG8_LDB(B1, 0, 1); PG8_SCHED; PG8_LDA(At, 0, 0); PG8_STAGE(PG8_SA(1, 1), a1 + hstep, voffA);
;             PG8_WAIT_V(8); PG8_WAIT_L(0); PG8_BAR; PG8_MMA(0, 0, At, B0); PG8_MMA(0, 1, At, B1); PG8_BAR; PG8_SCHED;
;             PG8_LDA(At, 0, 1); PG8_STAGE(PG8_SB(0, 0), b2, voffB); PG8_STAGE(PG8_SB(0, 1), b2 + hstep, voffB); PG8_STAGE(PG8_SA(0, 0), a2, voffA);
;             PG8_WAIT_V(8); PG8_WAIT_L(0); PG8_BAR; PG8_MMA(1, 0, At, B0); PG8_MMA(1, 1, At, B1); PG8_BAR; PG8_SCHED;
.LBB0_511:
	s_add_u32 s6, s24, s4
	s_addc_u32 s7, s25, s5
	s_add_u32 s6, s6, 0x2c00100
	s_addc_u32 s7, s7, 0
	s_add_u32 s27, s22, s4
	s_addc_u32 s28, s23, s5
	s_add_i32 s29, 0, 0x10000
	s_cmpk_eq_i32 s4, 0x700
	s_cselect_b32 s9, s3, s7
	s_cselect_b32 s8, s2, s6
	v_add_u32_e32 v149, s29, v142
	s_cselect_b32 s7, s1, s28
	s_cselect_b32 s6, s0, s27
	s_add_i32 s27, 0, 0x14000
	ds_read_b128 v[144:147], v149
	ds_read_b128 v[150:153], v149 offset:1024
	ds_read_b128 v[154:157], v149 offset:2048
	ds_read_b128 v[158:161], v149 offset:3072
	v_add_u32_e32 v149, s27, v142
	ds_read_b128 v[162:165], v149
	ds_read_b128 v[166:169], v149 offset:1024
	ds_read_b128 v[170:173], v149 offset:2048
	ds_read_b128 v[174:177], v149 offset:3072
	v_lshl_add_u64 v[202:203], v[138:139], 0, s[4:5]
	s_add_i32 m0, s13, 0xc000
	ds_read_b128 v[178:181], v143
	ds_read_b128 v[182:185], v143 offset:1024
	ds_read_b128 v[186:189], v143 offset:2048
	ds_read_b128 v[190:193], v143 offset:3072
	ds_read_b128 v[194:197], v143 offset:4096
	ds_read_b128 v[198:201], v143 offset:5120
	ds_read_b128 v[214:217], v143 offset:6144
	ds_read_b128 v[218:221], v143 offset:7168
	global_load_lds_dwordx4 v[202:203], off
	v_lshl_add_u64 v[202:203], v[136:137], 0, s[4:5]
	s_add_i32 m0, s13, 0xe000
	s_nop 0
	global_load_lds_dwordx4 v[202:203], off
	s_waitcnt vmcnt(8) lgkmcnt(0)
	s_setprio 1
	s_barrier
	v_mfma_f32_16x16x32_bf16 v[126:129], v[144:147], v[178:181], v[126:129]
	v_mfma_f32_16x16x32_bf16 v[122:125], v[154:157], v[178:181], v[122:125]
	v_mfma_f32_16x16x32_bf16 v[118:121], v[144:147], v[186:189], v[118:121]
	v_mfma_f32_16x16x32_bf16 v[114:117], v[154:157], v[186:189], v[114:117]
	v_mfma_f32_16x16x32_bf16 v[110:113], v[144:147], v[194:197], v[110:113]
	v_mfma_f32_16x16x32_bf16 v[106:109], v[154:157], v[194:197], v[106:109]
	v_mfma_f32_16x16x32_bf16 v[102:105], v[144:147], v[214:217], v[102:105]
	v_mfma_f32_16x16x32_bf16 v[98:101], v[154:157], v[214:217], v[98:101]
	v_mfma_f32_16x16x32_bf16 v[126:129], v[150:153], v[182:185], v[126:129]
	v_mfma_f32_16x16x32_bf16 v[122:125], v[158:161], v[182:185], v[122:125]
	v_mfma_f32_16x16x32_bf16 v[118:121], v[150:153], v[190:193], v[118:121]
	v_mfma_f32_16x16x32_bf16 v[114:117], v[158:161], v[190:193], v[114:117]
	v_mfma_f32_16x16x32_bf16 v[110:113], v[150:153], v[198:201], v[110:113]
	v_mfma_f32_16x16x32_bf16 v[106:109], v[158:161], v[198:201], v[106:109]
	v_mfma_f32_16x16x32_bf16 v[102:105], v[150:153], v[218:221], v[102:105]
	v_mfma_f32_16x16x32_bf16 v[98:101], v[158:161], v[218:221], v[98:101]
	v_mfma_f32_16x16x32_bf16 v[60:63], v[162:165], v[178:181], v[60:63]
	v_mfma_f32_16x16x32_bf16 v[56:59], v[170:173], v[178:181], v[56:59]
	v_mfma_f32_16x16x32_bf16 v[52:55], v[162:165], v[186:189], v[52:55]
	v_mfma_f32_16x16x32_bf16 v[48:51], v[170:173], v[186:189], v[48:51]
	v_mfma_f32_16x16x32_bf16 v[44:47], v[162:165], v[194:197], v[44:47]
	v_mfma_f32_16x16x32_bf16 v[40:43], v[170:173], v[194:197], v[40:43]
	v_mfma_f32_16x16x32_bf16 v[36:39], v[162:165], v[214:217], v[36:39]
	v_mfma_f32_16x16x32_bf16 v[32:35], v[170:173], v[214:217], v[32:35]
	v_mfma_f32_16x16x32_bf16 v[60:63], v[166:169], v[182:185], v[60:63]
	v_mfma_f32_16x16x32_bf16 v[56:59], v[174:177], v[182:185], v[56:59]
	v_mfma_f32_16x16x32_bf16 v[52:55], v[166:169], v[190:193], v[52:55]
	v_mfma_f32_16x16x32_bf16 v[48:51], v[174:177], v[190:193], v[48:51]
	v_mfma_f32_16x16x32_bf16 v[44:47], v[166:169], v[198:201], v[44:47]
	v_mfma_f32_16x16x32_bf16 v[40:43], v[174:177], v[198:201], v[40:43]
	v_mfma_f32_16x16x32_bf16 v[36:39], v[166:169], v[218:221], v[36:39]
	v_mfma_f32_16x16x32_bf16 v[32:35], v[174:177], v[218:221], v[32:35]
	s_barrier
	s_setprio 0
	s_add_i32 s28, s29, s12
	v_lshl_add_u64 v[202:203], s[6:7], 0, v[64:65]
	s_mov_b32 m0, s28
	ds_read_b128 v[178:181], v143 offset:16384
	ds_read_b128 v[182:185], v143 offset:17408
	ds_read_b128 v[186:189], v143 offset:18432
	ds_read_b128 v[190:193], v143 offset:19456
	ds_read_b128 v[194:197], v143 offset:20480
	ds_read_b128 v[198:201], v143 offset:21504
	ds_read_b128 v[214:217], v143 offset:22528
	ds_read_b128 v[218:221], v143 offset:23552
	global_load_lds_dwordx4 v[202:203], off
	s_add_i32 m0, s28, 0x2000
	s_add_u32 s28, s6, 0x40000
	v_lshl_add_u64 v[206:207], s[6:7], 0, v[134:135]
	s_addc_u32 s29, s7, 0
	s_add_i32 s27, s27, s12
	global_load_lds_dwordx4 v[206:207], off
	v_lshl_add_u64 v[208:209], s[28:29], 0, v[64:65]
	s_mov_b32 m0, s27
	v_lshl_add_u64 v[222:223], s[8:9], 0, v[132:133]
	global_load_lds_dwordx4 v[208:209], off
	v_lshl_add_u64 v[208:209], s[28:29], 0, v[134:135]
	s_add_i32 m0, s27, 0x2000
	s_nop 0
	global_load_lds_dwordx4 v[208:209], off
	v_lshl_add_u64 v[208:209], s[8:9], 0, v[130:131]
	s_mov_b32 m0, s13
	s_nop 0
	global_load_lds_dwordx4 v[208:209], off
	s_mov_b32 m0, s16
	s_nop 0
	global_load_lds_dwordx4 v[222:223], off
	s_waitcnt vmcnt(8) lgkmcnt(0)
	s_setprio 1
	s_barrier
; #define PG8_STAGE(bufoff, gbase, voff) do { _Pragma("unroll") for (int _i = 0; _i < 2; ++_i) \
;         __builtin_amdgcn_global_load_lds((const unsigned*)((const char*)(gbase) + (voff)[_i]), (PG8_LAS unsigned*)(lds + (bufoff) + ldsw + _i * 8192), 16, 0, 0); } while (0)
; #define PG8_LDA(dst, b, h) do { _Pragma("unroll") for (int m = 0; m < 4; ++m) _Pragma("unroll") for (int k = 0; k < 2; ++k) dst[m][k] = *(const PG8_LAS bf16x8*)(lds + PG8_SA(b, h) + aoff + m * 2048 + k * 1024); } while (0)
; #define PG8_LDB(dst, b, h) do { _Pragma("unroll") for (int n = 0; n < 2; ++n) _Pragma("unroll") for (int k = 0; k < 2; ++k) dst[n][k] = *(const PG8_LAS bf16x8*)(lds + PG8_SB(b, h) + boff + n * 2048 + k * 1024); } while (0)
; #define PG8_MMA(ai, bj, At, Bt) do { __builtin_amdgcn_s_setprio(1); _Pragma("unroll") for (int m = 0; m < 4; ++m) _Pragma("unroll") for (int n = 0; n < 2; ++n) _Pragma("unroll") for (int k = 0; k < 2; ++k) \
;         acc[ai][bj][m][n] = __builtin_amdgcn_mfma_f32_16x16x32_bf16(Bt[n][k], At[m][k], acc[ai][bj][m][n], 0, 0, 0); __builtin_amdgcn_s_setprio(0); } while (0)
; #define PG8_WAIT_V(n) asm volatile("s_waitcnt vmcnt(" #n ")" ::: "memory")
; #define PG8_WAIT_L(n) asm volatile("s_waitcnt lgkmcnt(" #n ")" ::: "memory")
; #define PG8_BAR __builtin_amdgcn_s_barrier()
; #define PG8_SCHED __builtin_amdgcn_sched_barrier(0)
; template <class Epi, class Sched, bool ALIGN_EPI = false, bool SP2 = false>
; __device__ __forceinline__ void gemm_phase(PG8_LAS unsigned char* lds, const Gemm g, const Sched& S, const Epi& E, const int tid) {
;     ...
;             PG8_WAIT_V(8); PG8_WAIT_L(0); PG8_BAR; PG8_MMA(1, 0, At, B0); PG8_MMA(1, 1, At, B1); PG8_BAR; PG8_SCHED;
;             PG8_LDB(B0, 1, 0); PG8_LDB(B1, 1, 1); PG8_SCHED; PG8_LDA(At, 1, 0); PG8_STAGE(PG8_SA(0, 1), a2 + hstep, voffA);
;             PG8_WAIT_V(8); PG8_WAIT_L(0); PG8_BAR; PG8_MMA(0, 0, At, B0); PG8_MMA(0, 1, At, B1); PG8_BAR; PG8_SCHED;
	v_mfma_f32_16x16x32_bf16 v[94:97], v[144:147], v[178:181], v[94:97]
	v_mfma_f32_16x16x32_bf16 v[90:93], v[154:157], v[178:181], v[90:93]
	v_mfma_f32_16x16x32_bf16 v[86:89], v[144:147], v[186:189], v[86:89]
	v_mfma_f32_16x16x32_bf16 v[82:85], v[154:157], v[186:189], v[82:85]
	v_mfma_f32_16x16x32_bf16 v[78:81], v[144:147], v[194:197], v[78:81]
	v_mfma_f32_16x16x32_bf16 v[74:77], v[154:157], v[194:197], v[74:77]
	v_mfma_f32_16x16x32_bf16 v[70:73], v[144:147], v[214:217], v[70:73]
	v_mfma_f32_16x16x32_bf16 v[66:69], v[154:157], v[214:217], v[66:69]
	v_mfma_f32_16x16x32_bf16 v[94:97], v[150:153], v[182:185], v[94:97]
	v_mfma_f32_16x16x32_bf16 v[90:93], v[158:161], v[182:185], v[90:93]
	v_mfma_f32_16x16x32_bf16 v[86:89], v[150:153], v[190:193], v[86:89]
	v_mfma_f32_16x16x32_bf16 v[82:85], v[158:161], v[190:193], v[82:85]
	v_mfma_f32_16x16x32_bf16 v[78:81], v[150:153], v[198:201], v[78:81]
	v_mfma_f32_16x16x32_bf16 v[74:77], v[158:161], v[198:201], v[74:77]
	v_mfma_f32_16x16x32_bf16 v[70:73], v[150:153], v[218:221], v[70:73]
	v_mfma_f32_16x16x32_bf16 v[66:69], v[158:161], v[218:221], v[66:69]
	v_mfma_f32_16x16x32_bf16 v[28:31], v[162:165], v[178:181], v[28:31]
	v_mfma_f32_16x16x32_bf16 v[24:27], v[170:173], v[178:181], v[24:27]
	v_mfma_f32_16x16x32_bf16 v[20:23], v[162:165], v[186:189], v[20:23]
	v_mfma_f32_16x16x32_bf16 v[16:19], v[170:173], v[186:189], v[16:19]
	v_mfma_f32_16x16x32_bf16 v[12:15], v[162:165], v[194:197], v[12:15]
	v_mfma_f32_16x16x32_bf16 v[8:11], v[170:173], v[194:197], v[8:11]
	v_mfma_f32_16x16x32_bf16 v[4:7], v[162:165], v[214:217], v[4:7]
	v_mfma_f32_16x16x32_bf16 v[0:3], v[170:173], v[214:217], v[0:3]
	v_mfma_f32_16x16x32_bf16 v[28:31], v[166:169], v[182:185], v[28:31]
	v_mfma_f32_16x16x32_bf16 v[24:27], v[174:177], v[182:185], v[24:27]
	v_mfma_f32_16x16x32_bf16 v[20:23], v[166:169], v[190:193], v[20:23]
	v_mfma_f32_16x16x32_bf16 v[16:19], v[174:177], v[190:193], v[16:19]
	v_mfma_f32_16x16x32_bf16 v[12:15], v[166:169], v[198:201], v[12:15]
	v_mfma_f32_16x16x32_bf16 v[8:11], v[174:177], v[198:201], v[8:11]
	v_mfma_f32_16x16x32_bf16 v[4:7], v[166:169], v[218:221], v[4:7]
	v_mfma_f32_16x16x32_bf16 v[0:3], v[174:177], v[218:221], v[0:3]
	s_barrier
	s_setprio 0
	s_add_i32 s27, 0, 0x18000
	v_add_u32_e32 v149, s27, v142
	s_add_i32 s28, 0, 0x1c000
	ds_read_b128 v[144:147], v149
	ds_read_b128 v[150:153], v149 offset:1024
	ds_read_b128 v[154:157], v149 offset:2048
	ds_read_b128 v[158:161], v149 offset:3072
	v_add_u32_e32 v149, s28, v142
	ds_read_b128 v[162:165], v149
	ds_read_b128 v[166:169], v149 offset:1024
	ds_read_b128 v[170:173], v149 offset:2048
	ds_read_b128 v[174:177], v149 offset:3072
	s_add_u32 s8, s8, 0x40000
	s_addc_u32 s9, s9, 0
	s_mov_b32 m0, s17
	v_lshl_add_u64 v[224:225], s[8:9], 0, v[130:131]
	ds_read_b128 v[178:181], v143 offset:32768
	ds_read_b128 v[182:185], v143 offset:33792
	ds_read_b128 v[186:189], v143 offset:34816
	ds_read_b128 v[190:193], v143 offset:35840
	ds_read_b128 v[194:197], v143 offset:36864
	ds_read_b128 v[198:201], v143 offset:37888
	ds_read_b128 v[214:217], v143 offset:38912
	ds_read_b128 v[218:221], v143 offset:39936
	global_load_lds_dwordx4 v[224:225], off
	v_lshl_add_u64 v[224:225], s[8:9], 0, v[132:133]
	s_mov_b32 m0, s18
	s_nop 0
	global_load_lds_dwordx4 v[224:225], off
	s_waitcnt vmcnt(8) lgkmcnt(0)
	s_setprio 1
	s_barrier
	v_mfma_f32_16x16x32_bf16 v[126:129], v[144:147], v[178:181], v[126:129]
	v_mfma_f32_16x16x32_bf16 v[122:125], v[154:157], v[178:181], v[122:125]
	v_mfma_f32_16x16x32_bf16 v[118:121], v[144:147], v[186:189], v[118:121]
	v_mfma_f32_16x16x32_bf16 v[114:117], v[154:157], v[186:189], v[114:117]
	v_mfma_f32_16x16x32_bf16 v[110:113], v[144:147], v[194:197], v[110:113]
	v_mfma_f32_16x16x32_bf16 v[106:109], v[154:157], v[194:197], v[106:109]
	v_mfma_f32_16x16x32_bf16 v[102:105], v[144:147], v[214:217], v[102:105]
	v_mfma_f32_16x16x32_bf16 v[98:101], v[154:157], v[214:217], v[98:101]
	v_mfma_f32_16x16x32_bf16 v[126:129], v[150:153], v[182:185], v[126:129]
	v_mfma_f32_16x16x32_bf16 v[122:125], v[158:161], v[182:185], v[122:125]
	v_mfma_f32_16x16x32_bf16 v[118:121], v[150:153], v[190:193], v[118:121]
	v_mfma_f32_16x16x32_bf16 v[114:117], v[158:161], v[190:193], v[114:117]
	v_mfma_f32_16x16x32_bf16 v[110:113], v[150:153], v[198:201], v[110:113]
	v_mfma_f32_16x16x32_bf16 v[106:109], v[158:161], v[198:201], v[106:109]
	v_mfma_f32_16x16x32_bf16 v[102:105], v[150:153], v[218:221], v[102:105]
	v_mfma_f32_16x16x32_bf16 v[98:101], v[158:161], v[218:221], v[98:101]
	v_mfma_f32_16x16x32_bf16 v[60:63], v[162:165], v[178:181], v[60:63]
	v_mfma_f32_16x16x32_bf16 v[56:59], v[170:173], v[178:181], v[56:59]
	v_mfma_f32_16x16x32_bf16 v[52:55], v[162:165], v[186:189], v[52:55]
	v_mfma_f32_16x16x32_bf16 v[48:51], v[170:173], v[186:189], v[48:51]
	v_mfma_f32_16x16x32_bf16 v[44:47], v[162:165], v[194:197], v[44:47]
	v_mfma_f32_16x16x32_bf16 v[40:43], v[170:173], v[194:197], v[40:43]
	v_mfma_f32_16x16x32_bf16 v[36:39], v[162:165], v[214:217], v[36:39]
	v_mfma_f32_16x16x32_bf16 v[32:35], v[170:173], v[214:217], v[32:35]
	v_mfma_f32_16x16x32_bf16 v[60:63], v[166:169], v[182:185], v[60:63]
	v_mfma_f32_16x16x32_bf16 v[56:59], v[174:177], v[182:185], v[56:59]
	v_mfma_f32_16x16x32_bf16 v[52:55], v[166:169], v[190:193], v[52:55]
	v_mfma_f32_16x16x32_bf16 v[48:51], v[174:177], v[190:193], v[48:51]
	v_mfma_f32_16x16x32_bf16 v[44:47], v[166:169], v[198:201], v[44:47]
	v_mfma_f32_16x16x32_bf16 v[40:43], v[174:177], v[198:201], v[40:43]
	v_mfma_f32_16x16x32_bf16 v[36:39], v[166:169], v[218:221], v[36:39]
	v_mfma_f32_16x16x32_bf16 v[32:35], v[174:177], v[218:221], v[32:35]
	s_barrier
; #define PG8_STAGE(bufoff, gbase, voff) do { _Pragma("unroll") for (int _i = 0; _i < 2; ++_i) \
;         __builtin_amdgcn_global_load_lds((const unsigned*)((const char*)(gbase) + (voff)[_i]), (PG8_LAS unsigned*)(lds + (bufoff) + ldsw + _i * 8192), 16, 0, 0); } while (0)
; #define PG8_LDA(dst, b, h) do { _Pragma("unroll") for (int m = 0; m < 4; ++m) _Pragma("unroll") for (int k = 0; k < 2; ++k) dst[m][k] = *(const PG8_LAS bf16x8*)(lds + PG8_SA(b, h) + aoff + m * 2048 + k * 1024); } while (0)
; #define PG8_MMA(ai, bj, At, Bt) do { __builtin_amdgcn_s_setprio(1); _Pragma("unroll") for (int m = 0; m < 4; ++m) _Pragma("unroll") for (int n = 0; n < 2; ++n) _Pragma("unroll") for (int k = 0; k < 2; ++k) \
;         acc[ai][bj][m][n] = __builtin_amdgcn_mfma_f32_16x16x32_bf16(Bt[n][k], At[m][k], acc[ai][bj][m][n], 0, 0, 0); __builtin_amdgcn_s_setprio(0); } while (0)
; #define PG8_WAIT_V(n) asm volatile("s_waitcnt vmcnt(" #n ")" ::: "memory")
; template <class Epi, class Sched, bool ALIGN_EPI = false, bool SP2 = false>
; __device__ __forceinline__ void gemm_phase(PG8_LAS unsigned char* lds, const Gemm g, const Sched& S, const Epi& E, const int tid) {
;     ...
;             PG8_LDA(At, 1, 1); PG8_STAGE(PG8_SB(1, 0), b3, voffB); PG8_STAGE(PG8_SB(1, 1), b3 + hstep, voffB); PG8_STAGE(PG8_SA(1, 0), a3, voffA);
;             PG8_WAIT_V(8); PG8_WAIT_L(0); PG8_BAR; PG8_MMA(1, 0, At, B0); PG8_MMA(1, 1, At, B1); PG8_BAR; PG8_SCHED;
;     __device__ __forceinline__ void operator()(const f32x4 (&acc)[2][2][4][2], const Unit& u, int wr, int wc, int fr, int fq) const {
;     ...
;                 const int gcol = col - LDQ;
;                 const f32x4 b0 = *(const f32x4*)(bgate + gcol), b1 = *(const f32x4*)(bgate + gcol + 4);
; #pragma unroll
;                 for (int ai = 0; ai < 2; ++ai)
; #pragma unroll
;                     for (int m = 0; m < 4; ++m) {
;                         const int row = row0 + ai * 128 + m * 16;
;                         const f32x4 v0 = acc[ai][bj][m][0] + b0, v1 = acc[ai][bj][m][1] + b1;
;                         u32x4 w; w.x = pk2(sigmoidf_(v0[0]), sigmoidf_(v0[1])); w.y = pk2(sigmoidf_(v0[2]), sigmoidf_(v0[3]));
;                         w.z = pk2(sigmoidf_(v1[0]), sigmoidf_(v1[1])); w.w = pk2(sigmoidf_(v1[2]), sigmoidf_(v1[3]));
;                         __builtin_nontemporal_store(w, (u32x4*)(gates + (unsigned)(row * NG + gcol)));
;                     }
	s_setprio 0
	s_add_i32 s8, s27, s12
	v_lshl_add_u64 v[202:203], v[202:203], 0, s[94:95]
	s_mov_b32 m0, s8
	ds_read_b128 v[178:181], v143 offset:49152
	ds_read_b128 v[182:185], v143 offset:50176
	ds_read_b128 v[186:189], v143 offset:51200
	ds_read_b128 v[190:193], v143 offset:52224
	ds_read_b128 v[194:197], v143 offset:53248
	ds_read_b128 v[198:201], v143 offset:54272
	ds_read_b128 v[214:217], v143 offset:55296
	ds_read_b128 v[218:221], v143 offset:56320
	global_load_lds_dwordx4 v[202:203], off
	s_add_i32 m0, s8, 0x2000
	s_add_u32 s6, s6, 0x40080
	v_lshl_add_u64 v[202:203], v[206:207], 0, s[94:95]
	s_addc_u32 s7, s7, 0
	s_add_i32 s8, s28, s12
	global_load_lds_dwordx4 v[202:203], off
	v_lshl_add_u64 v[202:203], s[6:7], 0, v[64:65]
	s_mov_b32 m0, s8
	s_nop 0
	global_load_lds_dwordx4 v[202:203], off
	v_lshl_add_u64 v[202:203], s[6:7], 0, v[134:135]
	s_add_i32 m0, s8, 0x2000
	s_nop 0
	global_load_lds_dwordx4 v[202:203], off
	v_lshl_add_u64 v[202:203], v[208:209], 0, s[94:95]
	s_mov_b32 m0, s20
	s_nop 0
	global_load_lds_dwordx4 v[202:203], off
	v_lshl_add_u64 v[202:203], v[222:223], 0, s[94:95]
	s_mov_b32 m0, s21
	s_nop 0
	global_load_lds_dwordx4 v[202:203], off
	s_waitcnt vmcnt(8) lgkmcnt(0)
	s_setprio 1
	s_barrier
	v_mfma_f32_16x16x32_bf16 v[94:97], v[144:147], v[178:181], v[94:97]
	v_mfma_f32_16x16x32_bf16 v[90:93], v[154:157], v[178:181], v[90:93]
	v_mfma_f32_16x16x32_bf16 v[86:89], v[144:147], v[186:189], v[86:89]
	v_mfma_f32_16x16x32_bf16 v[82:85], v[154:157], v[186:189], v[82:85]
	v_mfma_f32_16x16x32_bf16 v[78:81], v[144:147], v[194:197], v[78:81]
	v_mfma_f32_16x16x32_bf16 v[74:77], v[154:157], v[194:197], v[74:77]
	v_mfma_f32_16x16x32_bf16 v[70:73], v[144:147], v[214:217], v[70:73]
	v_mfma_f32_16x16x32_bf16 v[66:69], v[154:157], v[214:217], v[66:69]
	v_mfma_f32_16x16x32_bf16 v[94:97], v[150:153], v[182:185], v[94:97]
	v_mfma_f32_16x16x32_bf16 v[90:93], v[158:161], v[182:185], v[90:93]
	v_mfma_f32_16x16x32_bf16 v[86:89], v[150:153], v[190:193], v[86:89]
	v_mfma_f32_16x16x32_bf16 v[82:85], v[158:161], v[190:193], v[82:85]
	v_mfma_f32_16x16x32_bf16 v[78:81], v[150:153], v[198:201], v[78:81]
	v_mfma_f32_16x16x32_bf16 v[74:77], v[158:161], v[198:201], v[74:77]
	v_mfma_f32_16x16x32_bf16 v[70:73], v[150:153], v[218:221], v[70:73]
	v_mfma_f32_16x16x32_bf16 v[66:69], v[158:161], v[218:221], v[66:69]
	v_mfma_f32_16x16x32_bf16 v[28:31], v[162:165], v[178:181], v[28:31]
	v_mfma_f32_16x16x32_bf16 v[24:27], v[170:173], v[178:181], v[24:27]
	v_mfma_f32_16x16x32_bf16 v[20:23], v[162:165], v[186:189], v[20:23]
	v_mfma_f32_16x16x32_bf16 v[16:19], v[170:173], v[186:189], v[16:19]
	v_mfma_f32_16x16x32_bf16 v[12:15], v[162:165], v[194:197], v[12:15]
	v_mfma_f32_16x16x32_bf16 v[8:11], v[170:173], v[194:197], v[8:11]
	v_mfma_f32_16x16x32_bf16 v[4:7], v[162:165], v[214:217], v[4:7]
	v_mfma_f32_16x16x32_bf16 v[0:3], v[170:173], v[214:217], v[0:3]
	v_mfma_f32_16x16x32_bf16 v[28:31], v[166:169], v[182:185], v[28:31]
	v_mfma_f32_16x16x32_bf16 v[24:27], v[174:177], v[182:185], v[24:27]
	v_mfma_f32_16x16x32_bf16 v[20:23], v[166:169], v[190:193], v[20:23]
	v_mfma_f32_16x16x32_bf16 v[16:19], v[174:177], v[190:193], v[16:19]
	v_mfma_f32_16x16x32_bf16 v[12:15], v[166:169], v[198:201], v[12:15]
	v_mfma_f32_16x16x32_bf16 v[8:11], v[174:177], v[198:201], v[8:11]
	v_mfma_f32_16x16x32_bf16 v[4:7], v[166:169], v[218:221], v[4:7]
	v_mfma_f32_16x16x32_bf16 v[0:3], v[174:177], v[218:221], v[0:3]
	s_barrier
	s_setprio 0
	s_add_i32 s26, s26, 2
	s_add_u32 s4, s4, 0x100
	s_addc_u32 s5, s5, 0
	s_cmp_gt_u32 s26, 13
	s_cbranch_scc0 .LBB0_511
	s_and_b32 s12, 0xffff, s11
	s_lshl_b32 s13, s19, 8
	s_lshl_b32 s11, s12, 8
	s_and_b32 s2, s13, 0xff00
	s_and_b32 s14, 0xffff, s14
	v_or_b32_e32 v64, s15, v148
	s_cmpk_gt_u32 s14, 0x8f
	v_or_b32_e32 v186, s2, v64
	s_cselect_b64 s[2:3], -1, 0
	v_cmp_eq_u32_e64 s[0:1], 0, v141
	v_add_u32_e32 v187, s11, v140
	s_mov_b64 s[4:5], -1
	s_and_b64 vcc, exec, s[2:3]
	s_cbranch_vccz .LBB0_514
	v_add_u32_e32 v138, 0xffffee00, v186
	v_ashrrev_i32_e32 v139, 31, v138
	v_lshl_add_u64 v[134:135], v[138:139], 2, s[52:53]
	global_load_dwordx4 v[130:133], v[134:135], off offset:16
	s_nop 0
	global_load_dwordx4 v[134:137], v[134:135], off
	s_waitcnt vmcnt(0)
	v_pk_add_f32 v[146:147], v[122:123], v[130:131]
	v_pk_add_f32 v[140:141], v[126:127], v[134:135]
	v_pk_add_f32 v[142:143], v[128:129], v[136:137]
	v_mul_f32_e32 v64, 0xbfb8aa3b, v140
	v_mul_f32_e32 v139, 0xbfb8aa3b, v141
	v_exp_f32_e32 v64, v64
	v_exp_f32_e32 v139, v139
	v_pk_add_f32 v[144:145], v[124:125], v[132:133]
	v_add_f32_e32 v64, 1.0, v64
	v_add_f32_e32 v139, 1.0, v139
	v_rcp_f32_e32 v64, v64
	v_rcp_f32_e32 v139, v139
	s_nop 0
	v_cvt_pk_bf16_f32 v140, v64, v139
	v_mul_f32_e32 v64, 0xbfb8aa3b, v142
	v_mul_f32_e32 v139, 0xbfb8aa3b, v143
	v_exp_f32_e32 v64, v64
	v_exp_f32_e32 v139, v139
	v_add_f32_e32 v64, 1.0, v64
	v_add_f32_e32 v139, 1.0, v139
	v_rcp_f32_e32 v64, v64
	v_rcp_f32_e32 v139, v139
	s_nop 0
	v_cvt_pk_bf16_f32 v141, v64, v139
	v_mul_f32_e32 v64, 0xbfb8aa3b, v146
	v_mul_f32_e32 v139, 0xbfb8aa3b, v147
	v_exp_f32_e32 v64, v64
	v_exp_f32_e32 v139, v139
	v_pk_add_f32 v[146:147], v[114:115], v[130:131]
	v_add_f32_e32 v64, 1.0, v64
	v_add_f32_e32 v139, 1.0, v139
	v_rcp_f32_e32 v64, v64
	v_rcp_f32_e32 v139, v139
	s_nop 0
	v_cvt_pk_bf16_f32 v142, v64, v139
	v_mul_f32_e32 v64, 0xbfb8aa3b, v144
	v_mul_f32_e32 v139, 0xbfb8aa3b, v145
	v_exp_f32_e32 v64, v64
	v_exp_f32_e32 v139, v139
	v_add_f32_e32 v64, 1.0, v64
	v_add_f32_e32 v139, 1.0, v139
	v_rcp_f32_e32 v64, v64
	v_rcp_f32_e32 v139, v139
	s_nop 0
	v_cvt_pk_bf16_f32 v143, v64, v139
	v_mad_u64_u32 v[138:139], s[4:5], v187, s76, v[138:139]
	v_mov_b32_e32 v139, v65
; __device__ __forceinline__ unsigned pk2(float lo, float hi) { f32x2_t v = {lo, hi}; bf16x2_t b = __builtin_convertvector(v, bf16x2_t); return __builtin_bit_cast(unsigned, b); }
; __device__ __forceinline__ float sigmoidf_(float x) { return __builtin_amdgcn_rcpf(1.0f + __expf(-x)); }
;     __device__ __forceinline__ void operator()(const f32x4 (&acc)[2][2][4][2], const Unit& u, int wr, int wc, int fr, int fq) const {
;     ...
;                 const int gcol = col - LDQ;
;                 const f32x4 b0 = *(const f32x4*)(bgate + gcol), b1 = *(const f32x4*)(bgate + gcol + 4);
; #pragma unroll
;                 for (int ai = 0; ai < 2; ++ai)
; #pragma unroll
;                     for (int m = 0; m < 4; ++m) {
;                         const int row = row0 + ai * 128 + m * 16;
;                         const f32x4 v0 = acc[ai][bj][m][0] + b0, v1 = acc[ai][bj][m][1] + b1;
;                         u32x4 w; w.x = pk2(sigmoidf_(v0[0]), sigmoidf_(v0[1])); w.y = pk2(sigmoidf_(v0[2]), sigmoidf_(v0[3]));
;                         w.z = pk2(sigmoidf_(v1[0]), sigmoidf_(v1[1])); w.w = pk2(sigmoidf_(v1[2]), sigmoidf_(v1[3]));
;                         __builtin_nontemporal_store(w, (u32x4*)(gates + (unsigned)(row * NG + gcol)));
;                     }
	v_lshl_add_u64 v[144:145], v[138:139], 1, s[36:37]
	flat_store_dwordx4 v[144:145], v[140:143] nt
	v_pk_add_f32 v[144:145], v[116:117], v[132:133]
	s_mov_b64 s[4:5], 0
	v_pk_add_f32 v[140:141], v[118:119], v[134:135]
	v_pk_add_f32 v[142:143], v[120:121], v[136:137]
	v_mul_f32_e32 v64, 0xbfb8aa3b, v140
	v_mul_f32_e32 v139, 0xbfb8aa3b, v141
	v_exp_f32_e32 v64, v64
	v_exp_f32_e32 v139, v139
	v_add_f32_e32 v64, 1.0, v64
	v_add_f32_e32 v139, 1.0, v139
	v_rcp_f32_e32 v64, v64
	v_rcp_f32_e32 v139, v139
	s_nop 0
	v_cvt_pk_bf16_f32 v140, v64, v139
	v_mul_f32_e32 v64, 0xbfb8aa3b, v142
	v_mul_f32_e32 v139, 0xbfb8aa3b, v143
	v_exp_f32_e32 v64, v64
	v_exp_f32_e32 v139, v139
	v_add_f32_e32 v64, 1.0, v64
	v_add_f32_e32 v139, 1.0, v139
	v_rcp_f32_e32 v64, v64
	v_rcp_f32_e32 v139, v139
	s_nop 0
	v_cvt_pk_bf16_f32 v141, v64, v139
	v_mul_f32_e32 v64, 0xbfb8aa3b, v146
	v_mul_f32_e32 v139, 0xbfb8aa3b, v147
	v_exp_f32_e32 v64, v64
	v_exp_f32_e32 v139, v139
	v_pk_add_f32 v[146:147], v[110:111], v[134:135]
	v_add_f32_e32 v64, 1.0, v64
	v_add_f32_e32 v139, 1.0, v139
	v_rcp_f32_e32 v64, v64
	v_rcp_f32_e32 v139, v139
	s_nop 0
	v_cvt_pk_bf16_f32 v142, v64, v139
	v_mul_f32_e32 v64, 0xbfb8aa3b, v144
	v_mul_f32_e32 v139, 0xbfb8aa3b, v145
	v_exp_f32_e32 v64, v64
	v_exp_f32_e32 v139, v139
	v_add_f32_e32 v64, 1.0, v64
	v_add_f32_e32 v139, 1.0, v139
	v_rcp_f32_e32 v64, v64
	v_rcp_f32_e32 v139, v139
	s_nop 0
	v_cvt_pk_bf16_f32 v143, v64, v139
	v_add_u32_e32 v64, 0xc000, v138
	v_lshl_add_u64 v[144:145], v[64:65], 1, s[36:37]
	v_mul_f32_e32 v64, 0xbfb8aa3b, v146
	v_mul_f32_e32 v139, 0xbfb8aa3b, v147
	v_exp_f32_e32 v64, v64
	v_exp_f32_e32 v139, v139
	flat_store_dwordx4 v[144:145], v[140:143] nt
	v_pk_add_f32 v[144:145], v[112:113], v[136:137]
	v_add_f32_e32 v64, 1.0, v64
	v_add_f32_e32 v139, 1.0, v139
	v_rcp_f32_e32 v64, v64
	v_rcp_f32_e32 v139, v139
	v_pk_add_f32 v[142:143], v[106:107], v[130:131]
	v_pk_add_f32 v[140:141], v[108:109], v[132:133]
	v_pk_add_f32 v[146:147], v[98:99], v[130:131]
	v_cvt_pk_bf16_f32 v150, v64, v139
	v_mul_f32_e32 v64, 0xbfb8aa3b, v144
	v_mul_f32_e32 v139, 0xbfb8aa3b, v145
	v_exp_f32_e32 v64, v64
	v_exp_f32_e32 v139, v139
	v_pk_add_f32 v[144:145], v[100:101], v[132:133]
	v_add_f32_e32 v64, 1.0, v64
	v_add_f32_e32 v139, 1.0, v139
	v_rcp_f32_e32 v64, v64
	v_rcp_f32_e32 v139, v139
	s_nop 0
	v_cvt_pk_bf16_f32 v151, v64, v139
	v_mul_f32_e32 v64, 0xbfb8aa3b, v142
	v_mul_f32_e32 v139, 0xbfb8aa3b, v143
	v_exp_f32_e32 v64, v64
	v_exp_f32_e32 v139, v139
	v_pk_add_f32 v[142:143], v[104:105], v[136:137]
	v_add_f32_e32 v64, 1.0, v64
	v_add_f32_e32 v139, 1.0, v139
	v_rcp_f32_e32 v64, v64
	v_rcp_f32_e32 v139, v139
	s_nop 0
	v_cvt_pk_bf16_f32 v152, v64, v139
	v_mul_f32_e32 v64, 0xbfb8aa3b, v140
	v_mul_f32_e32 v139, 0xbfb8aa3b, v141
	v_exp_f32_e32 v64, v64
	v_exp_f32_e32 v139, v139
	v_add_f32_e32 v64, 1.0, v64
	v_add_f32_e32 v139, 1.0, v139
	v_rcp_f32_e32 v64, v64
	v_rcp_f32_e32 v139, v139
	s_nop 0
	v_cvt_pk_bf16_f32 v153, v64, v139
	v_add_u32_e32 v64, 0x18000, v138
	v_lshl_add_u64 v[140:141], v[64:65], 1, s[36:37]
	flat_store_dwordx4 v[140:141], v[150:153] nt
	v_pk_add_f32 v[140:141], v[102:103], v[134:135]
	s_nop 0
	v_mul_f32_e32 v64, 0xbfb8aa3b, v140
	v_mul_f32_e32 v139, 0xbfb8aa3b, v141
	v_exp_f32_e32 v64, v64
	v_exp_f32_e32 v139, v139
	v_add_f32_e32 v64, 1.0, v64
	v_add_f32_e32 v139, 1.0, v139
	v_rcp_f32_e32 v64, v64
	v_rcp_f32_e32 v139, v139
	s_nop 0
	v_cvt_pk_bf16_f32 v140, v64, v139
	v_mul_f32_e32 v64, 0xbfb8aa3b, v142
	v_mul_f32_e32 v139, 0xbfb8aa3b, v143
	v_exp_f32_e32 v64, v64
	v_exp_f32_e32 v139, v139
	v_add_f32_e32 v64, 1.0, v64
	v_add_f32_e32 v139, 1.0, v139
	v_rcp_f32_e32 v64, v64
	v_rcp_f32_e32 v139, v139
	s_nop 0
	v_cvt_pk_bf16_f32 v141, v64, v139
	v_mul_f32_e32 v64, 0xbfb8aa3b, v146
	v_mul_f32_e32 v139, 0xbfb8aa3b, v147
	v_exp_f32_e32 v64, v64
	v_exp_f32_e32 v139, v139
	v_pk_add_f32 v[146:147], v[90:91], v[130:131]
	v_add_f32_e32 v64, 1.0, v64
	v_add_f32_e32 v139, 1.0, v139
	v_rcp_f32_e32 v64, v64
	v_rcp_f32_e32 v139, v139
	s_nop 0
	v_cvt_pk_bf16_f32 v142, v64, v139
	v_mul_f32_e32 v64, 0xbfb8aa3b, v144
	v_mul_f32_e32 v139, 0xbfb8aa3b, v145
	v_exp_f32_e32 v64, v64
	v_exp_f32_e32 v139, v139
	v_add_f32_e32 v64, 1.0, v64
	v_add_f32_e32 v139, 1.0, v139
	v_rcp_f32_e32 v64, v64
	v_rcp_f32_e32 v139, v139
	s_nop 0
	v_cvt_pk_bf16_f32 v143, v64, v139
	v_add_u32_e32 v64, 0x24000, v138
	v_lshl_add_u64 v[144:145], v[64:65], 1, s[36:37]
	flat_store_dwordx4 v[144:145], v[140:143] nt
	v_pk_add_f32 v[144:145], v[92:93], v[132:133]
	s_nop 0
	v_pk_add_f32 v[140:141], v[94:95], v[134:135]
	v_pk_add_f32 v[142:143], v[96:97], v[136:137]
	v_mul_f32_e32 v64, 0xbfb8aa3b, v140
	v_mul_f32_e32 v139, 0xbfb8aa3b, v141
	v_exp_f32_e32 v64, v64
	v_exp_f32_e32 v139, v139
	v_add_f32_e32 v64, 1.0, v64
	v_add_f32_e32 v139, 1.0, v139
	v_rcp_f32_e32 v64, v64
	v_rcp_f32_e32 v139, v139
	s_nop 0
	v_cvt_pk_bf16_f32 v140, v64, v139
	v_mul_f32_e32 v64, 0xbfb8aa3b, v142
	v_mul_f32_e32 v139, 0xbfb8aa3b, v143
	v_exp_f32_e32 v64, v64
	v_exp_f32_e32 v139, v139
	v_add_f32_e32 v64, 1.0, v64
	v_add_f32_e32 v139, 1.0, v139
	v_rcp_f32_e32 v64, v64
; __device__ __forceinline__ unsigned pk2(float lo, float hi) { f32x2_t v = {lo, hi}; bf16x2_t b = __builtin_convertvector(v, bf16x2_t); return __builtin_bit_cast(unsigned, b); }
; __device__ __forceinline__ float sigmoidf_(float x) { return __builtin_amdgcn_rcpf(1.0f + __expf(-x)); }
;     __device__ __forceinline__ void operator()(const f32x4 (&acc)[2][2][4][2], const Unit& u, int wr, int wc, int fr, int fq) const {
;     ...
;                 const int gcol = col - LDQ;
;                 const f32x4 b0 = *(const f32x4*)(bgate + gcol), b1 = *(const f32x4*)(bgate + gcol + 4);
; #pragma unroll
;                 for (int ai = 0; ai < 2; ++ai)
; #pragma unroll
;                     for (int m = 0; m < 4; ++m) {
;                         const int row = row0 + ai * 128 + m * 16;
;                         const f32x4 v0 = acc[ai][bj][m][0] + b0, v1 = acc[ai][bj][m][1] + b1;
;                         u32x4 w; w.x = pk2(sigmoidf_(v0[0]), sigmoidf_(v0[1])); w.y = pk2(sigmoidf_(v0[2]), sigmoidf_(v0[3]));
;                         w.z = pk2(sigmoidf_(v1[0]), sigmoidf_(v1[1])); w.w = pk2(sigmoidf_(v1[2]), sigmoidf_(v1[3]));
;                         __builtin_nontemporal_store(w, (u32x4*)(gates + (unsigned)(row * NG + gcol)));
;                     }
	v_rcp_f32_e32 v139, v139
	s_nop 0
	v_cvt_pk_bf16_f32 v141, v64, v139
	v_mul_f32_e32 v64, 0xbfb8aa3b, v146
	v_mul_f32_e32 v139, 0xbfb8aa3b, v147
	v_exp_f32_e32 v64, v64
	v_exp_f32_e32 v139, v139
	v_pk_add_f32 v[146:147], v[82:83], v[130:131]
	v_add_f32_e32 v64, 1.0, v64
	v_add_f32_e32 v139, 1.0, v139
	v_rcp_f32_e32 v64, v64
	v_rcp_f32_e32 v139, v139
	s_nop 0
	v_cvt_pk_bf16_f32 v142, v64, v139
	v_mul_f32_e32 v64, 0xbfb8aa3b, v144
	v_mul_f32_e32 v139, 0xbfb8aa3b, v145
	v_exp_f32_e32 v64, v64
	v_exp_f32_e32 v139, v139
	v_add_f32_e32 v64, 1.0, v64
	v_add_f32_e32 v139, 1.0, v139
	v_rcp_f32_e32 v64, v64
	v_rcp_f32_e32 v139, v139
	s_nop 0
	v_cvt_pk_bf16_f32 v143, v64, v139
	v_add_u32_e32 v64, 0x60000, v138
	v_lshl_add_u64 v[144:145], v[64:65], 1, s[36:37]
	flat_store_dwordx4 v[144:145], v[140:143] nt
	v_pk_add_f32 v[144:145], v[84:85], v[132:133]
	s_nop 0
	v_pk_add_f32 v[140:141], v[86:87], v[134:135]
	v_pk_add_f32 v[142:143], v[88:89], v[136:137]
	v_mul_f32_e32 v64, 0xbfb8aa3b, v140
	v_mul_f32_e32 v139, 0xbfb8aa3b, v141
	v_exp_f32_e32 v64, v64
	v_exp_f32_e32 v139, v139
	v_add_f32_e32 v64, 1.0, v64
	v_add_f32_e32 v139, 1.0, v139
	v_rcp_f32_e32 v64, v64
	v_rcp_f32_e32 v139, v139
	s_nop 0
	v_cvt_pk_bf16_f32 v140, v64, v139
	v_mul_f32_e32 v64, 0xbfb8aa3b, v142
	v_mul_f32_e32 v139, 0xbfb8aa3b, v143
	v_exp_f32_e32 v64, v64
	v_exp_f32_e32 v139, v139
	v_add_f32_e32 v64, 1.0, v64
	v_add_f32_e32 v139, 1.0, v139
	v_rcp_f32_e32 v64, v64
	v_rcp_f32_e32 v139, v139
	s_nop 0
	v_cvt_pk_bf16_f32 v141, v64, v139
	v_mul_f32_e32 v64, 0xbfb8aa3b, v146
	v_mul_f32_e32 v139, 0xbfb8aa3b, v147
	v_exp_f32_e32 v64, v64
	v_exp_f32_e32 v139, v139
	v_pk_add_f32 v[146:147], v[74:75], v[130:131]
	v_add_f32_e32 v64, 1.0, v64
	v_add_f32_e32 v139, 1.0, v139
	v_rcp_f32_e32 v64, v64
	v_rcp_f32_e32 v139, v139
	s_nop 0
	v_cvt_pk_bf16_f32 v142, v64, v139
	v_mul_f32_e32 v64, 0xbfb8aa3b, v144
	v_mul_f32_e32 v139, 0xbfb8aa3b, v145
	v_exp_f32_e32 v64, v64
	v_exp_f32_e32 v139, v139
	v_add_f32_e32 v64, 1.0, v64
	v_add_f32_e32 v139, 1.0, v139
	v_rcp_f32_e32 v64, v64
	v_rcp_f32_e32 v139, v139
	s_nop 0
	v_cvt_pk_bf16_f32 v143, v64, v139
	v_add_u32_e32 v64, 0x6c000, v138
	v_lshl_add_u64 v[144:145], v[64:65], 1, s[36:37]
	flat_store_dwordx4 v[144:145], v[140:143] nt
	v_pk_add_f32 v[144:145], v[76:77], v[132:133]
	s_nop 0
	v_pk_add_f32 v[140:141], v[78:79], v[134:135]
	v_pk_add_f32 v[142:143], v[80:81], v[136:137]
	v_mul_f32_e32 v64, 0xbfb8aa3b, v140
	v_mul_f32_e32 v139, 0xbfb8aa3b, v141
	v_exp_f32_e32 v64, v64
	v_exp_f32_e32 v139, v139
	v_pk_add_f32 v[134:135], v[70:71], v[134:135]
	v_pk_add_f32 v[136:137], v[72:73], v[136:137]
	v_add_f32_e32 v64, 1.0, v64
	v_add_f32_e32 v139, 1.0, v139
	v_rcp_f32_e32 v64, v64
	v_rcp_f32_e32 v139, v139
	s_nop 0
	v_cvt_pk_bf16_f32 v140, v64, v139
	v_mul_f32_e32 v64, 0xbfb8aa3b, v142
	v_mul_f32_e32 v139, 0xbfb8aa3b, v143
	v_exp_f32_e32 v64, v64
	v_exp_f32_e32 v139, v139
	v_add_f32_e32 v64, 1.0, v64
	v_add_f32_e32 v139, 1.0, v139
	v_rcp_f32_e32 v64, v64
	v_rcp_f32_e32 v139, v139
	s_nop 0
	v_cvt_pk_bf16_f32 v141, v64, v139
	v_mul_f32_e32 v64, 0xbfb8aa3b, v146
	v_mul_f32_e32 v139, 0xbfb8aa3b, v147
	v_exp_f32_e32 v64, v64
	v_exp_f32_e32 v139, v139
	v_add_f32_e32 v64, 1.0, v64
	v_add_f32_e32 v139, 1.0, v139
	v_rcp_f32_e32 v64, v64
	v_rcp_f32_e32 v139, v139
	s_nop 0
	v_cvt_pk_bf16_f32 v142, v64, v139
	v_mul_f32_e32 v64, 0xbfb8aa3b, v144
	v_mul_f32_e32 v139, 0xbfb8aa3b, v145
	v_exp_f32_e32 v64, v64
	v_exp_f32_e32 v139, v139
	v_add_f32_e32 v64, 1.0, v64
	v_add_f32_e32 v139, 1.0, v139
	v_rcp_f32_e32 v64, v64
	v_rcp_f32_e32 v139, v139
	s_nop 0
	v_cvt_pk_bf16_f32 v143, v64, v139
	v_add_u32_e32 v64, 0x78000, v138
	v_lshl_add_u64 v[144:145], v[64:65], 1, s[36:37]
	flat_store_dwordx4 v[144:145], v[140:143] nt
	v_mul_f32_e32 v64, 0xbfb8aa3b, v134
	v_exp_f32_e32 v64, v64
	v_pk_add_f32 v[140:141], v[68:69], v[132:133]
	v_pk_add_f32 v[132:133], v[66:67], v[130:131]
	v_mul_f32_e32 v130, 0xbfb8aa3b, v135
	v_exp_f32_e32 v130, v130
	v_add_f32_e32 v64, 1.0, v64
	v_rcp_f32_e32 v64, v64
	v_mul_f32_e32 v131, 0xbfb8aa3b, v137
	v_add_f32_e32 v130, 1.0, v130
	v_rcp_f32_e32 v130, v130
	v_exp_f32_e32 v131, v131
	v_cvt_pk_bf16_f32 v130, v64, v130
	v_mul_f32_e32 v64, 0xbfb8aa3b, v136
	v_exp_f32_e32 v64, v64
	v_add_f32_e32 v131, 1.0, v131
	v_rcp_f32_e32 v131, v131
	v_add_f32_e32 v64, 1.0, v64
	v_rcp_f32_e32 v64, v64
	s_nop 0
	v_cvt_pk_bf16_f32 v131, v64, v131
	v_mul_f32_e32 v64, 0xbfb8aa3b, v132
	v_mul_f32_e32 v132, 0xbfb8aa3b, v133
	v_exp_f32_e32 v64, v64
	v_exp_f32_e32 v132, v132
	v_mul_f32_e32 v133, 0xbfb8aa3b, v141
	v_exp_f32_e32 v133, v133
	v_add_f32_e32 v64, 1.0, v64
	v_add_f32_e32 v132, 1.0, v132
	v_rcp_f32_e32 v64, v64
	v_rcp_f32_e32 v132, v132
	v_add_f32_e32 v133, 1.0, v133
	v_rcp_f32_e32 v133, v133
	v_cvt_pk_bf16_f32 v132, v64, v132
	v_mul_f32_e32 v64, 0xbfb8aa3b, v140
	v_exp_f32_e32 v64, v64
	s_nop 0
	v_add_f32_e32 v64, 1.0, v64
	v_rcp_f32_e32 v64, v64
	s_nop 0
	v_cvt_pk_bf16_f32 v133, v64, v133
	v_add_u32_e32 v64, 0x84000, v138
	v_lshl_add_u64 v[134:135], v[64:65], 1, s[36:37]
	flat_store_dwordx4 v[134:135], v[130:133] nt

; #define PG8_STAGE(bufoff, gbase, voff) do { _Pragma("unroll") for (int _i = 0; _i < 2; ++_i) \
;         __builtin_amdgcn_global_load_lds((const unsigned*)((const char*)(gbase) + (voff)[_i]), (PG8_LAS unsigned*)(lds + (bufoff) + ldsw + _i * 8192), 16, 0, 0); } while (0)
; #define PG8_LDA(dst, b, h) do { _Pragma("unroll") for (int m = 0; m < 4; ++m) _Pragma("unroll") for (int k = 0; k < 2; ++k) dst[m][k] = *(const PG8_LAS bf16x8*)(lds + PG8_SA(b, h) + aoff + m * 2048 + k * 1024); } while (0)
; #define PG8_LDB(dst, b, h) do { _Pragma("unroll") for (int n = 0; n < 2; ++n) _Pragma("unroll") for (int k = 0; k < 2; ++k) dst[n][k] = *(const PG8_LAS bf16x8*)(lds + PG8_SB(b, h) + boff + n * 2048 + k * 1024); } while (0)
; #define PG8_MMA(ai, bj, At, Bt) do { __builtin_amdgcn_s_setprio(1); _Pragma("unroll") for (int m = 0; m < 4; ++m) _Pragma("unroll") for (int n = 0; n < 2; ++n) _Pragma("unroll") for (int k = 0; k < 2; ++k) \
;         acc[ai][bj][m][n] = __builtin_amdgcn_mfma_f32_16x16x32_bf16(Bt[n][k], At[m][k], acc[ai][bj][m][n], 0, 0, 0); __builtin_amdgcn_s_setprio(0); } while (0)
; #define PG8_WAIT_V(n) asm volatile("s_waitcnt vmcnt(" #n ")" ::: "memory")
; #define PG8_BAR __builtin_amdgcn_s_barrier()
; template <class Epi, class Sched, bool ALIGN_EPI = false, bool SP2 = false>
; __device__ __forceinline__ void gemm_phase(PG8_LAS unsigned char* lds, const Gemm g, const Sched& S, const Epi& E, const int tid) {
;     ...
;         for (int t = 0; t < nt; t += 2) {
;             const bool last = (t == nt - 2);
;             const char* a1 = cA + (size_t)(t + 1) * kstep;
;             const char* a2 = last ? nA : cA + (size_t)(t + 2) * kstep; const char* b2 = last ? nB : cB + (size_t)(t + 2) * kstep;
;             const char* a3 = a2 + kstep; const char* b3 = b2 + kstep;
;             if (last && has_next) S.a_ready(nxt);
;             if constexpr (SP2) {
;             PG8_LDB(B0, 0, 0); PG8_LDB(B1, 0, 1); PG8_SCHED; PG8_LDA(At, 0, 0); PG8_STAGE(PG8_SA(1, 1), a1 + hstep, voffA);
;             PG8_WAIT_V(8); PG8_WAIT_L(0); PG8_BAR; PG8_MMA(0, 0, At, B0); PG8_MMA(0, 1, At, B1); PG8_BAR; PG8_SCHED;
;             PG8_LDA(At, 0, 1); PG8_STAGE(PG8_SB(0, 0), b2, voffB); PG8_STAGE(PG8_SB(0, 1), b2 + hstep, voffB); PG8_STAGE(PG8_SA(0, 0), a2, voffA);
;             PG8_WAIT_V(8); PG8_WAIT_L(0); PG8_BAR; PG8_MMA(1, 0, At, B0); PG8_MMA(1, 1, At, B1); PG8_BAR; PG8_SCHED;
.LBB0_704:
	s_add_u32 s24, s2, 0xfffc0080
	s_addc_u32 s25, s3, -1
	s_add_i32 s51, 0, 0x10000
	s_cmp_eq_u32 s50, 12
	s_cselect_b32 s27, s17, s25
	s_cselect_b32 s26, s29, s24
	v_add_u32_e32 v64, s51, v213
	s_cselect_b32 s25, s15, s49
	s_cselect_b32 s24, s47, s48
	s_add_i32 s54, 0, 0x14000
	ds_read_b128 v[130:133], v64
	ds_read_b128 v[134:137], v64 offset:1024
	ds_read_b128 v[138:141], v64 offset:2048
	ds_read_b128 v[142:145], v64 offset:3072
	v_add_u32_e32 v64, s54, v213
	ds_read_b128 v[146:149], v64
	ds_read_b128 v[150:153], v64 offset:1024
	ds_read_b128 v[154:157], v64 offset:2048
	ds_read_b128 v[158:161], v64 offset:3072
	v_lshl_add_u64 v[202:203], s[2:3], 0, v[198:199]
	s_add_i32 m0, s35, 0xc000
	ds_read_b128 v[162:165], v227
	ds_read_b128 v[166:169], v227 offset:1024
	ds_read_b128 v[170:173], v227 offset:2048
	ds_read_b128 v[174:177], v227 offset:3072
	ds_read_b128 v[178:181], v227 offset:4096
	ds_read_b128 v[182:185], v227 offset:5120
	ds_read_b128 v[218:221], v227 offset:6144
	ds_read_b128 v[222:225], v227 offset:7168
	global_load_lds_dwordx4 v[202:203], off
	v_lshl_add_u64 v[202:203], s[2:3], 0, v[196:197]
	s_add_i32 m0, s35, 0xe000
	s_nop 0
	global_load_lds_dwordx4 v[202:203], off
	s_waitcnt vmcnt(8) lgkmcnt(0)
	s_setprio 1
	s_barrier
	v_mfma_f32_16x16x32_bf16 v[126:129], v[130:133], v[162:165], v[126:129]
	v_mfma_f32_16x16x32_bf16 v[122:125], v[138:141], v[162:165], v[122:125]
	v_mfma_f32_16x16x32_bf16 v[118:121], v[130:133], v[170:173], v[118:121]
	v_mfma_f32_16x16x32_bf16 v[114:117], v[138:141], v[170:173], v[114:117]
	v_mfma_f32_16x16x32_bf16 v[110:113], v[130:133], v[178:181], v[110:113]
	v_mfma_f32_16x16x32_bf16 v[106:109], v[138:141], v[178:181], v[106:109]
	v_mfma_f32_16x16x32_bf16 v[102:105], v[130:133], v[218:221], v[102:105]
	v_mfma_f32_16x16x32_bf16 v[98:101], v[138:141], v[218:221], v[98:101]
	v_mfma_f32_16x16x32_bf16 v[126:129], v[134:137], v[166:169], v[126:129]
	v_mfma_f32_16x16x32_bf16 v[122:125], v[142:145], v[166:169], v[122:125]
	v_mfma_f32_16x16x32_bf16 v[118:121], v[134:137], v[174:177], v[118:121]
	v_mfma_f32_16x16x32_bf16 v[114:117], v[142:145], v[174:177], v[114:117]
	v_mfma_f32_16x16x32_bf16 v[110:113], v[134:137], v[182:185], v[110:113]
	v_mfma_f32_16x16x32_bf16 v[106:109], v[142:145], v[182:185], v[106:109]
	v_mfma_f32_16x16x32_bf16 v[102:105], v[134:137], v[222:225], v[102:105]
	v_mfma_f32_16x16x32_bf16 v[98:101], v[142:145], v[222:225], v[98:101]
	v_mfma_f32_16x16x32_bf16 v[60:63], v[146:149], v[162:165], v[60:63]
	v_mfma_f32_16x16x32_bf16 v[56:59], v[154:157], v[162:165], v[56:59]
	v_mfma_f32_16x16x32_bf16 v[52:55], v[146:149], v[170:173], v[52:55]
	v_mfma_f32_16x16x32_bf16 v[48:51], v[154:157], v[170:173], v[48:51]
	v_mfma_f32_16x16x32_bf16 v[44:47], v[146:149], v[178:181], v[44:47]
	v_mfma_f32_16x16x32_bf16 v[40:43], v[154:157], v[178:181], v[40:43]
	v_mfma_f32_16x16x32_bf16 v[36:39], v[146:149], v[218:221], v[36:39]
	v_mfma_f32_16x16x32_bf16 v[32:35], v[154:157], v[218:221], v[32:35]
	v_mfma_f32_16x16x32_bf16 v[60:63], v[150:153], v[166:169], v[60:63]
	v_mfma_f32_16x16x32_bf16 v[56:59], v[158:161], v[166:169], v[56:59]
	v_mfma_f32_16x16x32_bf16 v[52:55], v[150:153], v[174:177], v[52:55]
	v_mfma_f32_16x16x32_bf16 v[48:51], v[158:161], v[174:177], v[48:51]
	v_mfma_f32_16x16x32_bf16 v[44:47], v[150:153], v[182:185], v[44:47]
	v_mfma_f32_16x16x32_bf16 v[40:43], v[158:161], v[182:185], v[40:43]
	v_mfma_f32_16x16x32_bf16 v[36:39], v[150:153], v[222:225], v[36:39]
	v_mfma_f32_16x16x32_bf16 v[32:35], v[158:161], v[222:225], v[32:35]
	s_barrier
	s_setprio 0
	s_add_i32 s51, s51, s34
	v_lshl_add_u64 v[202:203], s[24:25], 0, v[190:191]
	s_mov_b32 m0, s51
	ds_read_b128 v[162:165], v227 offset:16384
	ds_read_b128 v[166:169], v227 offset:17408
	ds_read_b128 v[170:173], v227 offset:18432
	ds_read_b128 v[174:177], v227 offset:19456
	ds_read_b128 v[178:181], v227 offset:20480
	ds_read_b128 v[182:185], v227 offset:21504
	ds_read_b128 v[218:221], v227 offset:22528
	ds_read_b128 v[222:225], v227 offset:23552
	global_load_lds_dwordx4 v[202:203], off
	s_add_i32 m0, s51, 0x2000
	s_add_u32 s52, s24, 0x40000
	v_lshl_add_u64 v[206:207], s[24:25], 0, v[186:187]
	s_addc_u32 s53, s25, 0
	s_add_i32 s51, s54, s34
	global_load_lds_dwordx4 v[206:207], off
	v_lshl_add_u64 v[208:209], s[52:53], 0, v[190:191]
	s_mov_b32 m0, s51
	v_lshl_add_u64 v[214:215], s[26:27], 0, v[188:189]
	global_load_lds_dwordx4 v[208:209], off
	v_lshl_add_u64 v[208:209], s[52:53], 0, v[186:187]
	s_add_i32 m0, s51, 0x2000
	s_nop 0
	global_load_lds_dwordx4 v[208:209], off
	v_lshl_add_u64 v[208:209], s[26:27], 0, v[192:193]
	s_mov_b32 m0, s35
	s_nop 0
	global_load_lds_dwordx4 v[208:209], off
	s_mov_b32 m0, s39
	s_nop 0
	global_load_lds_dwordx4 v[214:215], off
	s_waitcnt vmcnt(8) lgkmcnt(0)
	s_setprio 1
	s_barrier
; #define PG8_STAGE(bufoff, gbase, voff) do { _Pragma("unroll") for (int _i = 0; _i < 2; ++_i) \
;         __builtin_amdgcn_global_load_lds((const unsigned*)((const char*)(gbase) + (voff)[_i]), (PG8_LAS unsigned*)(lds + (bufoff) + ldsw + _i * 8192), 16, 0, 0); } while (0)
; #define PG8_LDA(dst, b, h) do { _Pragma("unroll") for (int m = 0; m < 4; ++m) _Pragma("unroll") for (int k = 0; k < 2; ++k) dst[m][k] = *(const PG8_LAS bf16x8*)(lds + PG8_SA(b, h) + aoff + m * 2048 + k * 1024); } while (0)
; #define PG8_LDB(dst, b, h) do { _Pragma("unroll") for (int n = 0; n < 2; ++n) _Pragma("unroll") for (int k = 0; k < 2; ++k) dst[n][k] = *(const PG8_LAS bf16x8*)(lds + PG8_SB(b, h) + boff + n * 2048 + k * 1024); } while (0)
; #define PG8_MMA(ai, bj, At, Bt) do { __builtin_amdgcn_s_setprio(1); _Pragma("unroll") for (int m = 0; m < 4; ++m) _Pragma("unroll") for (int n = 0; n < 2; ++n) _Pragma("unroll") for (int k = 0; k < 2; ++k) \
;         acc[ai][bj][m][n] = __builtin_amdgcn_mfma_f32_16x16x32_bf16(Bt[n][k], At[m][k], acc[ai][bj][m][n], 0, 0, 0); __builtin_amdgcn_s_setprio(0); } while (0)
; #define PG8_WAIT_V(n) asm volatile("s_waitcnt vmcnt(" #n ")" ::: "memory")
; #define PG8_WAIT_L(n) asm volatile("s_waitcnt lgkmcnt(" #n ")" ::: "memory")
; #define PG8_BAR __builtin_amdgcn_s_barrier()
; #define PG8_SCHED __builtin_amdgcn_sched_barrier(0)
; template <class Epi, class Sched, bool ALIGN_EPI = false, bool SP2 = false>
; __device__ __forceinline__ void gemm_phase(PG8_LAS unsigned char* lds, const Gemm g, const Sched& S, const Epi& E, const int tid) {
;     ...
;             PG8_WAIT_V(8); PG8_WAIT_L(0); PG8_BAR; PG8_MMA(1, 0, At, B0); PG8_MMA(1, 1, At, B1); PG8_BAR; PG8_SCHED;
;             PG8_LDB(B0, 1, 0); PG8_LDB(B1, 1, 1); PG8_SCHED; PG8_LDA(At, 1, 0); PG8_STAGE(PG8_SA(0, 1), a2 + hstep, voffA);
;             PG8_WAIT_V(8); PG8_WAIT_L(0); PG8_BAR; PG8_MMA(0, 0, At, B0); PG8_MMA(0, 1, At, B1); PG8_BAR; PG8_SCHED;
	v_mfma_f32_16x16x32_bf16 v[94:97], v[130:133], v[162:165], v[94:97]
	v_mfma_f32_16x16x32_bf16 v[90:93], v[138:141], v[162:165], v[90:93]
	v_mfma_f32_16x16x32_bf16 v[86:89], v[130:133], v[170:173], v[86:89]
	v_mfma_f32_16x16x32_bf16 v[82:85], v[138:141], v[170:173], v[82:85]
	v_mfma_f32_16x16x32_bf16 v[78:81], v[130:133], v[178:181], v[78:81]
	v_mfma_f32_16x16x32_bf16 v[74:77], v[138:141], v[178:181], v[74:77]
	v_mfma_f32_16x16x32_bf16 v[70:73], v[130:133], v[218:221], v[70:73]
	v_mfma_f32_16x16x32_bf16 v[66:69], v[138:141], v[218:221], v[66:69]
	v_mfma_f32_16x16x32_bf16 v[94:97], v[134:137], v[166:169], v[94:97]
	v_mfma_f32_16x16x32_bf16 v[90:93], v[142:145], v[166:169], v[90:93]
	v_mfma_f32_16x16x32_bf16 v[86:89], v[134:137], v[174:177], v[86:89]
	v_mfma_f32_16x16x32_bf16 v[82:85], v[142:145], v[174:177], v[82:85]
	v_mfma_f32_16x16x32_bf16 v[78:81], v[134:137], v[182:185], v[78:81]
	v_mfma_f32_16x16x32_bf16 v[74:77], v[142:145], v[182:185], v[74:77]
	v_mfma_f32_16x16x32_bf16 v[70:73], v[134:137], v[222:225], v[70:73]
	v_mfma_f32_16x16x32_bf16 v[66:69], v[142:145], v[222:225], v[66:69]
	v_mfma_f32_16x16x32_bf16 v[28:31], v[146:149], v[162:165], v[28:31]
	v_mfma_f32_16x16x32_bf16 v[24:27], v[154:157], v[162:165], v[24:27]
	v_mfma_f32_16x16x32_bf16 v[20:23], v[146:149], v[170:173], v[20:23]
	v_mfma_f32_16x16x32_bf16 v[16:19], v[154:157], v[170:173], v[16:19]
	v_mfma_f32_16x16x32_bf16 v[12:15], v[146:149], v[178:181], v[12:15]
	v_mfma_f32_16x16x32_bf16 v[8:11], v[154:157], v[178:181], v[8:11]
	v_mfma_f32_16x16x32_bf16 v[4:7], v[146:149], v[218:221], v[4:7]
	v_mfma_f32_16x16x32_bf16 v[0:3], v[154:157], v[218:221], v[0:3]
	v_mfma_f32_16x16x32_bf16 v[28:31], v[150:153], v[166:169], v[28:31]
	v_mfma_f32_16x16x32_bf16 v[24:27], v[158:161], v[166:169], v[24:27]
	v_mfma_f32_16x16x32_bf16 v[20:23], v[150:153], v[174:177], v[20:23]
	v_mfma_f32_16x16x32_bf16 v[16:19], v[158:161], v[174:177], v[16:19]
	v_mfma_f32_16x16x32_bf16 v[12:15], v[150:153], v[182:185], v[12:15]
	v_mfma_f32_16x16x32_bf16 v[8:11], v[158:161], v[182:185], v[8:11]
	v_mfma_f32_16x16x32_bf16 v[4:7], v[150:153], v[222:225], v[4:7]
	v_mfma_f32_16x16x32_bf16 v[0:3], v[158:161], v[222:225], v[0:3]
	s_barrier
	s_setprio 0
	s_add_i32 s51, 0, 0x18000
	v_add_u32_e32 v64, s51, v213
	s_add_i32 s52, 0, 0x1c000
	ds_read_b128 v[130:133], v64
	ds_read_b128 v[134:137], v64 offset:1024
	ds_read_b128 v[138:141], v64 offset:2048
	ds_read_b128 v[142:145], v64 offset:3072
	v_add_u32_e32 v64, s52, v213
	ds_read_b128 v[146:149], v64
	ds_read_b128 v[150:153], v64 offset:1024
	ds_read_b128 v[154:157], v64 offset:2048
	ds_read_b128 v[158:161], v64 offset:3072
	s_add_u32 s26, s26, 0x40000
	s_addc_u32 s27, s27, 0
	s_mov_b32 m0, s42
	v_lshl_add_u64 v[228:229], s[26:27], 0, v[192:193]
	ds_read_b128 v[162:165], v227 offset:32768
	ds_read_b128 v[166:169], v227 offset:33792
	ds_read_b128 v[170:173], v227 offset:34816
	ds_read_b128 v[174:177], v227 offset:35840
	ds_read_b128 v[178:181], v227 offset:36864
	ds_read_b128 v[182:185], v227 offset:37888
	ds_read_b128 v[218:221], v227 offset:38912
	ds_read_b128 v[222:225], v227 offset:39936
	global_load_lds_dwordx4 v[228:229], off
	v_lshl_add_u64 v[228:229], s[26:27], 0, v[188:189]
	s_mov_b32 m0, s43
	s_nop 0
	global_load_lds_dwordx4 v[228:229], off
	s_waitcnt vmcnt(8) lgkmcnt(0)
	s_setprio 1
	s_barrier
	v_mfma_f32_16x16x32_bf16 v[126:129], v[130:133], v[162:165], v[126:129]
	v_mfma_f32_16x16x32_bf16 v[122:125], v[138:141], v[162:165], v[122:125]
	v_mfma_f32_16x16x32_bf16 v[118:121], v[130:133], v[170:173], v[118:121]
	v_mfma_f32_16x16x32_bf16 v[114:117], v[138:141], v[170:173], v[114:117]
	v_mfma_f32_16x16x32_bf16 v[110:113], v[130:133], v[178:181], v[110:113]
	v_mfma_f32_16x16x32_bf16 v[106:109], v[138:141], v[178:181], v[106:109]
	v_mfma_f32_16x16x32_bf16 v[102:105], v[130:133], v[218:221], v[102:105]
	v_mfma_f32_16x16x32_bf16 v[98:101], v[138:141], v[218:221], v[98:101]
	v_mfma_f32_16x16x32_bf16 v[126:129], v[134:137], v[166:169], v[126:129]
	v_mfma_f32_16x16x32_bf16 v[122:125], v[142:145], v[166:169], v[122:125]
	v_mfma_f32_16x16x32_bf16 v[118:121], v[134:137], v[174:177], v[118:121]
	v_mfma_f32_16x16x32_bf16 v[114:117], v[142:145], v[174:177], v[114:117]
	v_mfma_f32_16x16x32_bf16 v[110:113], v[134:137], v[182:185], v[110:113]
	v_mfma_f32_16x16x32_bf16 v[106:109], v[142:145], v[182:185], v[106:109]
	v_mfma_f32_16x16x32_bf16 v[102:105], v[134:137], v[222:225], v[102:105]
	v_mfma_f32_16x16x32_bf16 v[98:101], v[142:145], v[222:225], v[98:101]
	v_mfma_f32_16x16x32_bf16 v[60:63], v[146:149], v[162:165], v[60:63]
	v_mfma_f32_16x16x32_bf16 v[56:59], v[154:157], v[162:165], v[56:59]
	v_mfma_f32_16x16x32_bf16 v[52:55], v[146:149], v[170:173], v[52:55]
	v_mfma_f32_16x16x32_bf16 v[48:51], v[154:157], v[170:173], v[48:51]
	v_mfma_f32_16x16x32_bf16 v[44:47], v[146:149], v[178:181], v[44:47]
	v_mfma_f32_16x16x32_bf16 v[40:43], v[154:157], v[178:181], v[40:43]
	v_mfma_f32_16x16x32_bf16 v[36:39], v[146:149], v[218:221], v[36:39]
	v_mfma_f32_16x16x32_bf16 v[32:35], v[154:157], v[218:221], v[32:35]
	v_mfma_f32_16x16x32_bf16 v[60:63], v[150:153], v[166:169], v[60:63]
	v_mfma_f32_16x16x32_bf16 v[56:59], v[158:161], v[166:169], v[56:59]
	v_mfma_f32_16x16x32_bf16 v[52:55], v[150:153], v[174:177], v[52:55]
	v_mfma_f32_16x16x32_bf16 v[48:51], v[158:161], v[174:177], v[48:51]
	v_mfma_f32_16x16x32_bf16 v[44:47], v[150:153], v[182:185], v[44:47]
	v_mfma_f32_16x16x32_bf16 v[40:43], v[158:161], v[182:185], v[40:43]
	v_mfma_f32_16x16x32_bf16 v[36:39], v[150:153], v[222:225], v[36:39]
	v_mfma_f32_16x16x32_bf16 v[32:35], v[158:161], v[222:225], v[32:35]
	s_barrier
; #define PG8_STAGE(bufoff, gbase, voff) do { _Pragma("unroll") for (int _i = 0; _i < 2; ++_i) \
;         __builtin_amdgcn_global_load_lds((const unsigned*)((const char*)(gbase) + (voff)[_i]), (PG8_LAS unsigned*)(lds + (bufoff) + ldsw + _i * 8192), 16, 0, 0); } while (0)
; #define PG8_LDA(dst, b, h) do { _Pragma("unroll") for (int m = 0; m < 4; ++m) _Pragma("unroll") for (int k = 0; k < 2; ++k) dst[m][k] = *(const PG8_LAS bf16x8*)(lds + PG8_SA(b, h) + aoff + m * 2048 + k * 1024); } while (0)
; #define PG8_MMA(ai, bj, At, Bt) do { __builtin_amdgcn_s_setprio(1); _Pragma("unroll") for (int m = 0; m < 4; ++m) _Pragma("unroll") for (int n = 0; n < 2; ++n) _Pragma("unroll") for (int k = 0; k < 2; ++k) \
;         acc[ai][bj][m][n] = __builtin_amdgcn_mfma_f32_16x16x32_bf16(Bt[n][k], At[m][k], acc[ai][bj][m][n], 0, 0, 0); __builtin_amdgcn_s_setprio(0); } while (0)
; #define PG8_WAIT_V(n) asm volatile("s_waitcnt vmcnt(" #n ")" ::: "memory")
; #define PG8_WAIT_L(n) asm volatile("s_waitcnt lgkmcnt(" #n ")" ::: "memory")
; #define PG8_BAR __builtin_amdgcn_s_barrier()
; #define PG8_SCHED __builtin_amdgcn_sched_barrier(0)
; template <class Epi, class Sched, bool ALIGN_EPI = false, bool SP2 = false>
; __device__ __forceinline__ void gemm_phase(PG8_LAS unsigned char* lds, const Gemm g, const Sched& S, const Epi& E, const int tid) {
;     ...
;         for (int t = 0; t < nt; t += 2) {
;     ...
;             PG8_LDA(At, 1, 1); PG8_STAGE(PG8_SB(1, 0), b3, voffB); PG8_STAGE(PG8_SB(1, 1), b3 + hstep, voffB); PG8_STAGE(PG8_SA(1, 0), a3, voffA);
;             PG8_WAIT_V(8); PG8_WAIT_L(0); PG8_BAR; PG8_MMA(1, 0, At, B0); PG8_MMA(1, 1, At, B1); PG8_BAR; PG8_SCHED;
;     ...
;         if constexpr (ALIGN_EPI) { if (wr == 0) PG8_BAR; }
	s_setprio 0
	s_add_i32 s26, s51, s34
	v_lshl_add_u64 v[202:203], v[202:203], 0, s[94:95]
	s_mov_b32 m0, s26
	ds_read_b128 v[162:165], v227 offset:49152
	ds_read_b128 v[166:169], v227 offset:50176
	ds_read_b128 v[170:173], v227 offset:51200
	ds_read_b128 v[174:177], v227 offset:52224
	ds_read_b128 v[178:181], v227 offset:53248
	ds_read_b128 v[182:185], v227 offset:54272
	ds_read_b128 v[218:221], v227 offset:55296
	ds_read_b128 v[222:225], v227 offset:56320
	global_load_lds_dwordx4 v[202:203], off
	s_add_i32 m0, s26, 0x2000
	s_add_u32 s24, s24, 0x40080
	v_lshl_add_u64 v[202:203], v[206:207], 0, s[94:95]
	s_addc_u32 s25, s25, 0
	s_add_i32 s26, s52, s34
	global_load_lds_dwordx4 v[202:203], off
	v_lshl_add_u64 v[202:203], s[24:25], 0, v[190:191]
	s_mov_b32 m0, s26
	s_nop 0
	global_load_lds_dwordx4 v[202:203], off
	v_lshl_add_u64 v[202:203], s[24:25], 0, v[186:187]
	s_add_i32 m0, s26, 0x2000
	s_nop 0
	global_load_lds_dwordx4 v[202:203], off
	v_lshl_add_u64 v[202:203], v[208:209], 0, s[94:95]
	s_mov_b32 m0, s38
	s_nop 0
	global_load_lds_dwordx4 v[202:203], off
	v_lshl_add_u64 v[202:203], v[214:215], 0, s[94:95]
	s_mov_b32 m0, s44
	s_nop 0
	global_load_lds_dwordx4 v[202:203], off
	s_waitcnt vmcnt(8) lgkmcnt(0)
	s_setprio 1
	s_barrier
	v_mfma_f32_16x16x32_bf16 v[94:97], v[130:133], v[162:165], v[94:97]
	v_mfma_f32_16x16x32_bf16 v[90:93], v[138:141], v[162:165], v[90:93]
	v_mfma_f32_16x16x32_bf16 v[86:89], v[130:133], v[170:173], v[86:89]
	v_mfma_f32_16x16x32_bf16 v[82:85], v[138:141], v[170:173], v[82:85]
	v_mfma_f32_16x16x32_bf16 v[78:81], v[130:133], v[178:181], v[78:81]
	v_mfma_f32_16x16x32_bf16 v[74:77], v[138:141], v[178:181], v[74:77]
	v_mfma_f32_16x16x32_bf16 v[70:73], v[130:133], v[218:221], v[70:73]
	v_mfma_f32_16x16x32_bf16 v[66:69], v[138:141], v[218:221], v[66:69]
	v_mfma_f32_16x16x32_bf16 v[94:97], v[134:137], v[166:169], v[94:97]
	v_mfma_f32_16x16x32_bf16 v[90:93], v[142:145], v[166:169], v[90:93]
	v_mfma_f32_16x16x32_bf16 v[86:89], v[134:137], v[174:177], v[86:89]
	v_mfma_f32_16x16x32_bf16 v[82:85], v[142:145], v[174:177], v[82:85]
	v_mfma_f32_16x16x32_bf16 v[78:81], v[134:137], v[182:185], v[78:81]
	v_mfma_f32_16x16x32_bf16 v[74:77], v[142:145], v[182:185], v[74:77]
	v_mfma_f32_16x16x32_bf16 v[70:73], v[134:137], v[222:225], v[70:73]
	v_mfma_f32_16x16x32_bf16 v[66:69], v[142:145], v[222:225], v[66:69]
	v_mfma_f32_16x16x32_bf16 v[28:31], v[146:149], v[162:165], v[28:31]
	v_mfma_f32_16x16x32_bf16 v[24:27], v[154:157], v[162:165], v[24:27]
	v_mfma_f32_16x16x32_bf16 v[20:23], v[146:149], v[170:173], v[20:23]
	v_mfma_f32_16x16x32_bf16 v[16:19], v[154:157], v[170:173], v[16:19]
	v_mfma_f32_16x16x32_bf16 v[12:15], v[146:149], v[178:181], v[12:15]
	v_mfma_f32_16x16x32_bf16 v[8:11], v[154:157], v[178:181], v[8:11]
	v_mfma_f32_16x16x32_bf16 v[4:7], v[146:149], v[218:221], v[4:7]
	v_mfma_f32_16x16x32_bf16 v[0:3], v[154:157], v[218:221], v[0:3]
	v_mfma_f32_16x16x32_bf16 v[28:31], v[150:153], v[166:169], v[28:31]
	v_mfma_f32_16x16x32_bf16 v[24:27], v[158:161], v[166:169], v[24:27]
	v_mfma_f32_16x16x32_bf16 v[20:23], v[150:153], v[174:177], v[20:23]
	v_mfma_f32_16x16x32_bf16 v[16:19], v[158:161], v[174:177], v[16:19]
	v_mfma_f32_16x16x32_bf16 v[12:15], v[150:153], v[182:185], v[12:15]
	v_mfma_f32_16x16x32_bf16 v[8:11], v[158:161], v[182:185], v[8:11]
	v_mfma_f32_16x16x32_bf16 v[4:7], v[150:153], v[222:225], v[4:7]
	v_mfma_f32_16x16x32_bf16 v[0:3], v[158:161], v[222:225], v[0:3]
	s_barrier
	s_setprio 0
	s_add_i32 s50, s50, 2
	s_add_u32 s48, s48, 0x100
	s_addc_u32 s49, s49, 0
	s_add_u32 s2, s2, 0x100
	s_addc_u32 s3, s3, 0
	s_cmp_gt_u32 s50, 13
	s_cbranch_scc0 .LBB0_704
	s_and_b64 vcc, exec, s[12:13]
	s_cbranch_vccz .LBB0_707
	s_barrier
